# loop-edge rotation: K-loop counter/address SALU and next-iteration selects hoisted above the back-edge barrier in 7 GEMM loops (on boff+ntK)
# baseline (speedup 1.0000x reference)
;     __device__ __forceinline__ bool next(int i, Unit& u) const { const int L = i * G + c; if (L >= 512) return false; u.pm = L; u.pn = L >> 4; return true; }
; #define PG8_STAGE(bufoff, gbase, voff) do { _Pragma("unroll") for (int _i = 0; _i < 2; ++_i) \
;         __builtin_amdgcn_global_load_lds((const unsigned*)((const char*)(gbase) + (voff)[_i]), (PG8_LAS unsigned*)(lds + (bufoff) + ldsw + _i * 8192), 16, 0, 0); } while (0)
; #define PG8_LDA(dst, b, h) do { _Pragma("unroll") for (int m = 0; m < 4; ++m) _Pragma("unroll") for (int k = 0; k < 2; ++k) dst[m][k] = *(const PG8_LAS bf16x8*)(lds + PG8_SA(b, h) + aoff + m * 2048 + k * 1024); } while (0)
; #define PG8_LDB(dst, b, h) do { _Pragma("unroll") for (int n = 0; n < 2; ++n) _Pragma("unroll") for (int k = 0; k < 2; ++k) dst[n][k] = *(const PG8_LAS bf16x8*)(lds + PG8_SB(b, h) + boff + n * 2048 + k * 1024); } while (0)
; #define PG8_WAIT_V(n) asm volatile("s_waitcnt vmcnt(" #n ")" ::: "memory")
; #define PG8_BAR __builtin_amdgcn_s_barrier()
; template <class Epi, class Sched, bool ALIGN_EPI = false, bool SP2 = false>
; __device__ __forceinline__ void gemm_phase(PG8_LAS unsigned char* lds, const Gemm g, const Sched& S, const Epi& E) {
;     ...
;         const bool has_next = S.next(ui + 1, nxt);
;         const char* nA = has_next ? (const char*)g.A + (size_t)nxt.pm * tstep : cA; const char* nB = has_next ? (const char*)g.Bt + (size_t)nxt.pn * tstep : cB;
;         for (int t = 0; t < nt; t += 2) {
;             const bool last = (t == nt - 2);
;             const char* a1 = cA + (size_t)(t + 1) * kstep;
;             const char* a2 = last ? nA : cA + (size_t)(t + 2) * kstep; const char* b2 = last ? nB : cB + (size_t)(t + 2) * kstep;
;             const char* a3 = a2 + kstep; const char* b3 = b2 + kstep;
;             if (last && has_next) S.a_ready(nxt);
;             if constexpr (SP2) {
;             PG8_LDB(B0, 0, 0); PG8_LDB(B1, 0, 1); PG8_SCHED; PG8_LDA(At, 0, 0); PG8_STAGE(PG8_SA(1, 1), a1 + hstep, voffA);
;             PG8_WAIT_V(8); PG8_WAIT_L(0); PG8_BAR; PG8_MMA(0, 0, At, B0); PG8_MMA(0, 1, At, B1); PG8_BAR; PG8_SCHED;
;             PG8_LDA(At, 0, 1); PG8_STAGE(PG8_SB(0, 0), b2, voffB); PG8_STAGE(PG8_SB(0, 1), b2 + hstep, voffB); PG8_STAGE(PG8_SA(0, 0), a2, voffA);
;             PG8_WAIT_V(8); PG8_WAIT_L(0); PG8_BAR; PG8_MMA(1, 0, At, B0); PG8_MMA(1, 1, At, B1); PG8_BAR; PG8_SCHED;
.Lboff_skip_B:
	s_add_u32 s16, s18, 0xfffc0080
	s_addc_u32 s17, s19, -1
	s_add_i32 s52, 0, 0x10000
	s_cmp_eq_u32 s50, 12
	s_cselect_b32 s21, s11, s17
	s_cselect_b32 s20, s46, s16
	s_cselect_b32 s17, s9, vcc_hi
	s_cselect_b32 s16, s57, vcc_lo
	s_add_i32 s63, 0, 0x14000
.LBB0_247:
	v_add_u32_e32 v0, s52, v147
	ds_read_b128 v[158:161], v0
	ds_read_b128 v[162:165], v0 offset:1024
	ds_read_b128 v[166:169], v0 offset:2048
	ds_read_b128 v[170:173], v0 offset:3072
	v_add_u32_e32 v0, s63, v147
	ds_read_b128 v[174:177], v0
	ds_read_b128 v[178:181], v0 offset:1024
	ds_read_b128 v[182:185], v0 offset:2048
	ds_read_b128 v[186:189], v0 offset:3072
	v_lshl_add_u64 v[210:211], s[18:19], 0, v[142:143]
	s_add_i32 m0, s27, 0xc000
	ds_read_b128 v[190:193], v156
	ds_read_b128 v[194:197], v156 offset:1024
	ds_read_b128 v[198:201], v156 offset:2048
	ds_read_b128 v[202:205], v156 offset:3072
	ds_read_b128 v[206:209], v156 offset:4096
	ds_read_b128 v[220:223], v156 offset:5120
	ds_read_b128 v[224:227], v156 offset:6144
	ds_read_b128 v[228:231], v156 offset:7168
	global_load_lds_dwordx4 v[210:211], off
	v_lshl_add_u64 v[210:211], s[18:19], 0, v[144:145]
	s_add_i32 m0, s27, 0xe000
	s_nop 0
	global_load_lds_dwordx4 v[210:211], off
	s_waitcnt vmcnt(8)
	s_waitcnt lgkmcnt(0)
	s_barrier
	s_setprio 1
	s_waitcnt lgkmcnt(0)
	v_mfma_f32_16x16x32_bf16 v[126:129], v[158:161], v[190:193], v[126:129]
	v_mfma_f32_16x16x32_bf16 v[122:125], v[166:169], v[190:193], v[122:125]
	v_mfma_f32_16x16x32_bf16 v[118:121], v[158:161], v[198:201], v[118:121]
	v_mfma_f32_16x16x32_bf16 v[110:113], v[166:169], v[198:201], v[110:113]
	v_mfma_f32_16x16x32_bf16 v[102:105], v[158:161], v[206:209], v[102:105]
	v_mfma_f32_16x16x32_bf16 v[94:97], v[166:169], v[206:209], v[94:97]
	v_mfma_f32_16x16x32_bf16 v[86:89], v[158:161], v[224:227], v[86:89]
	v_mfma_f32_16x16x32_bf16 v[78:81], v[166:169], v[224:227], v[78:81]
	v_mfma_f32_16x16x32_bf16 v[126:129], v[162:165], v[194:197], v[126:129]
	v_mfma_f32_16x16x32_bf16 v[122:125], v[170:173], v[194:197], v[122:125]
	v_mfma_f32_16x16x32_bf16 v[118:121], v[162:165], v[202:205], v[118:121]
	v_mfma_f32_16x16x32_bf16 v[110:113], v[170:173], v[202:205], v[110:113]
	v_mfma_f32_16x16x32_bf16 v[102:105], v[162:165], v[220:223], v[102:105]
	v_mfma_f32_16x16x32_bf16 v[94:97], v[170:173], v[220:223], v[94:97]
	v_mfma_f32_16x16x32_bf16 v[86:89], v[162:165], v[228:231], v[86:89]
	v_mfma_f32_16x16x32_bf16 v[78:81], v[170:173], v[228:231], v[78:81]
	s_setprio 0
	s_setprio 1
	v_mfma_f32_16x16x32_bf16 v[114:117], v[174:177], v[190:193], v[114:117]
	v_mfma_f32_16x16x32_bf16 v[106:109], v[182:185], v[190:193], v[106:109]
	v_mfma_f32_16x16x32_bf16 v[98:101], v[174:177], v[198:201], v[98:101]
	v_mfma_f32_16x16x32_bf16 v[90:93], v[182:185], v[198:201], v[90:93]
	v_mfma_f32_16x16x32_bf16 v[82:85], v[174:177], v[206:209], v[82:85]
	v_mfma_f32_16x16x32_bf16 v[74:77], v[182:185], v[206:209], v[74:77]
	v_mfma_f32_16x16x32_bf16 v[70:73], v[174:177], v[224:227], v[70:73]
	v_mfma_f32_16x16x32_bf16 v[66:69], v[182:185], v[224:227], v[66:69]
	v_mfma_f32_16x16x32_bf16 v[114:117], v[178:181], v[194:197], v[114:117]
	v_mfma_f32_16x16x32_bf16 v[106:109], v[186:189], v[194:197], v[106:109]
	v_mfma_f32_16x16x32_bf16 v[98:101], v[178:181], v[202:205], v[98:101]
	v_mfma_f32_16x16x32_bf16 v[90:93], v[186:189], v[202:205], v[90:93]
	v_mfma_f32_16x16x32_bf16 v[82:85], v[178:181], v[220:223], v[82:85]
	v_mfma_f32_16x16x32_bf16 v[74:77], v[186:189], v[220:223], v[74:77]
	v_mfma_f32_16x16x32_bf16 v[70:73], v[178:181], v[228:231], v[70:73]
	v_mfma_f32_16x16x32_bf16 v[66:69], v[186:189], v[228:231], v[66:69]
	s_setprio 0
	s_barrier
	s_add_i32 s52, s52, s26
	v_lshl_add_u64 v[210:211], s[16:17], 0, v[134:135]
	s_mov_b32 m0, s52
	ds_read_b128 v[190:193], v156 offset:16384
	ds_read_b128 v[194:197], v156 offset:17408
	ds_read_b128 v[198:201], v156 offset:18432
	ds_read_b128 v[202:205], v156 offset:19456
	ds_read_b128 v[206:209], v156 offset:20480
	ds_read_b128 v[220:223], v156 offset:21504
	ds_read_b128 v[224:227], v156 offset:22528
	ds_read_b128 v[228:231], v156 offset:23552
	global_load_lds_dwordx4 v[210:211], off
	s_add_i32 m0, s52, 0x2000
	s_add_u32 s52, s16, 0x40000
	v_lshl_add_u64 v[212:213], s[16:17], 0, v[130:131]
	s_addc_u32 s53, s17, 0
	s_add_i32 s63, s63, s26
	global_load_lds_dwordx4 v[212:213], off
	v_lshl_add_u64 v[214:215], s[52:53], 0, v[134:135]
	s_mov_b32 m0, s63
	v_lshl_add_u64 v[216:217], s[20:21], 0, v[132:133]
	global_load_lds_dwordx4 v[214:215], off
	v_lshl_add_u64 v[214:215], s[52:53], 0, v[130:131]
	s_add_i32 m0, s63, 0x2000
	s_nop 0
	global_load_lds_dwordx4 v[214:215], off
	v_lshl_add_u64 v[214:215], s[20:21], 0, v[136:137]
	s_mov_b32 m0, s27
	s_nop 0
	global_load_lds_dwordx4 v[214:215], off
	s_mov_b32 m0, s28
	s_nop 0
	global_load_lds_dwordx4 v[216:217], off
	s_waitcnt vmcnt(8)
	s_waitcnt lgkmcnt(0)
	s_barrier
; #define PG8_STAGE(bufoff, gbase, voff) do { _Pragma("unroll") for (int _i = 0; _i < 2; ++_i) \
;         __builtin_amdgcn_global_load_lds((const unsigned*)((const char*)(gbase) + (voff)[_i]), (PG8_LAS unsigned*)(lds + (bufoff) + ldsw + _i * 8192), 16, 0, 0); } while (0)
; #define PG8_LDA(dst, b, h) do { _Pragma("unroll") for (int m = 0; m < 4; ++m) _Pragma("unroll") for (int k = 0; k < 2; ++k) dst[m][k] = *(const PG8_LAS bf16x8*)(lds + PG8_SA(b, h) + aoff + m * 2048 + k * 1024); } while (0)
; #define PG8_LDB(dst, b, h) do { _Pragma("unroll") for (int n = 0; n < 2; ++n) _Pragma("unroll") for (int k = 0; k < 2; ++k) dst[n][k] = *(const PG8_LAS bf16x8*)(lds + PG8_SB(b, h) + boff + n * 2048 + k * 1024); } while (0)
; #define PG8_MMA(ai, bj, At, Bt) do { __builtin_amdgcn_s_setprio(1); _Pragma("unroll") for (int m = 0; m < 4; ++m) _Pragma("unroll") for (int n = 0; n < 2; ++n) _Pragma("unroll") for (int k = 0; k < 2; ++k) \
;         acc[ai][bj][m][n] = __builtin_amdgcn_mfma_f32_16x16x32_bf16(Bt[n][k], At[m][k], acc[ai][bj][m][n], 0, 0, 0); __builtin_amdgcn_s_setprio(0); } while (0)
; #define PG8_WAIT_V(n) asm volatile("s_waitcnt vmcnt(" #n ")" ::: "memory")
; #define PG8_WAIT_L(n) asm volatile("s_waitcnt lgkmcnt(" #n ")" ::: "memory")
; #define PG8_BAR __builtin_amdgcn_s_barrier()
; #define PG8_SCHED __builtin_amdgcn_sched_barrier(0)
; template <class Epi, class Sched, bool ALIGN_EPI = false, bool SP2 = false>
; __device__ __forceinline__ void gemm_phase(PG8_LAS unsigned char* lds, const Gemm g, const Sched& S, const Epi& E) {
;     ...
;             PG8_WAIT_V(8); PG8_WAIT_L(0); PG8_BAR; PG8_MMA(1, 0, At, B0); PG8_MMA(1, 1, At, B1); PG8_BAR; PG8_SCHED;
;             PG8_LDB(B0, 1, 0); PG8_LDB(B1, 1, 1); PG8_SCHED; PG8_LDA(At, 1, 0); PG8_STAGE(PG8_SA(0, 1), a2 + hstep, voffA);
;             PG8_WAIT_V(8); PG8_WAIT_L(0); PG8_BAR; PG8_MMA(0, 0, At, B0); PG8_MMA(0, 1, At, B1); PG8_BAR; PG8_SCHED;
	s_setprio 1
	s_waitcnt lgkmcnt(0)
	v_mfma_f32_16x16x32_bf16 v[62:65], v[158:161], v[190:193], v[62:65]
	v_mfma_f32_16x16x32_bf16 v[58:61], v[166:169], v[190:193], v[58:61]
	v_mfma_f32_16x16x32_bf16 v[54:57], v[158:161], v[198:201], v[54:57]
	v_mfma_f32_16x16x32_bf16 v[46:49], v[166:169], v[198:201], v[46:49]
	v_mfma_f32_16x16x32_bf16 v[38:41], v[158:161], v[206:209], v[38:41]
	v_mfma_f32_16x16x32_bf16 v[30:33], v[166:169], v[206:209], v[30:33]
	v_mfma_f32_16x16x32_bf16 v[22:25], v[158:161], v[224:227], v[22:25]
	v_mfma_f32_16x16x32_bf16 v[14:17], v[166:169], v[224:227], v[14:17]
	v_mfma_f32_16x16x32_bf16 v[62:65], v[162:165], v[194:197], v[62:65]
	v_mfma_f32_16x16x32_bf16 v[58:61], v[170:173], v[194:197], v[58:61]
	v_mfma_f32_16x16x32_bf16 v[54:57], v[162:165], v[202:205], v[54:57]
	v_mfma_f32_16x16x32_bf16 v[46:49], v[170:173], v[202:205], v[46:49]
	v_mfma_f32_16x16x32_bf16 v[38:41], v[162:165], v[220:223], v[38:41]
	v_mfma_f32_16x16x32_bf16 v[30:33], v[170:173], v[220:223], v[30:33]
	v_mfma_f32_16x16x32_bf16 v[22:25], v[162:165], v[228:231], v[22:25]
	v_mfma_f32_16x16x32_bf16 v[14:17], v[170:173], v[228:231], v[14:17]
	s_setprio 0
	s_setprio 1
	v_mfma_f32_16x16x32_bf16 v[50:53], v[174:177], v[190:193], v[50:53]
	v_mfma_f32_16x16x32_bf16 v[42:45], v[182:185], v[190:193], v[42:45]
	v_mfma_f32_16x16x32_bf16 v[34:37], v[174:177], v[198:201], v[34:37]
	v_mfma_f32_16x16x32_bf16 v[26:29], v[182:185], v[198:201], v[26:29]
	v_mfma_f32_16x16x32_bf16 v[18:21], v[174:177], v[206:209], v[18:21]
	v_mfma_f32_16x16x32_bf16 v[10:13], v[182:185], v[206:209], v[10:13]
	v_mfma_f32_16x16x32_bf16 v[6:9], v[174:177], v[224:227], v[6:9]
	v_mfma_f32_16x16x32_bf16 v[2:5], v[182:185], v[224:227], v[2:5]
	v_mfma_f32_16x16x32_bf16 v[50:53], v[178:181], v[194:197], v[50:53]
	v_mfma_f32_16x16x32_bf16 v[42:45], v[186:189], v[194:197], v[42:45]
	v_mfma_f32_16x16x32_bf16 v[34:37], v[178:181], v[202:205], v[34:37]
	v_mfma_f32_16x16x32_bf16 v[26:29], v[186:189], v[202:205], v[26:29]
	v_mfma_f32_16x16x32_bf16 v[18:21], v[178:181], v[220:223], v[18:21]
	v_mfma_f32_16x16x32_bf16 v[10:13], v[186:189], v[220:223], v[10:13]
	v_mfma_f32_16x16x32_bf16 v[6:9], v[178:181], v[228:231], v[6:9]
	v_mfma_f32_16x16x32_bf16 v[2:5], v[186:189], v[228:231], v[2:5]
	s_setprio 0
	s_barrier
	s_add_i32 s52, 0, 0x18000
	v_add_u32_e32 v0, s52, v147
	s_add_i32 s53, 0, 0x1c000
	ds_read_b128 v[158:161], v0
	ds_read_b128 v[162:165], v0 offset:1024
	ds_read_b128 v[166:169], v0 offset:2048
	ds_read_b128 v[170:173], v0 offset:3072
	v_add_u32_e32 v0, s53, v147
	ds_read_b128 v[174:177], v0
	ds_read_b128 v[178:181], v0 offset:1024
	ds_read_b128 v[182:185], v0 offset:2048
	ds_read_b128 v[186:189], v0 offset:3072
	s_add_u32 s20, s20, 0x40000
	s_addc_u32 s21, s21, 0
	s_mov_b32 m0, s29
	v_lshl_add_u64 v[232:233], s[20:21], 0, v[136:137]
	ds_read_b128 v[190:193], v156 offset:32768
	ds_read_b128 v[194:197], v156 offset:33792
	ds_read_b128 v[198:201], v156 offset:34816
	ds_read_b128 v[202:205], v156 offset:35840
	ds_read_b128 v[206:209], v156 offset:36864
	ds_read_b128 v[220:223], v156 offset:37888
	ds_read_b128 v[224:227], v156 offset:38912
	ds_read_b128 v[228:231], v156 offset:39936
	global_load_lds_dwordx4 v[232:233], off
	v_lshl_add_u64 v[232:233], s[20:21], 0, v[132:133]
	s_mov_b32 m0, s30
	s_nop 0
	global_load_lds_dwordx4 v[232:233], off
	s_waitcnt vmcnt(8)
	s_waitcnt lgkmcnt(0)
	s_barrier
	s_setprio 1
	s_waitcnt lgkmcnt(0)
	v_mfma_f32_16x16x32_bf16 v[126:129], v[158:161], v[190:193], v[126:129]
	v_mfma_f32_16x16x32_bf16 v[122:125], v[166:169], v[190:193], v[122:125]
	v_mfma_f32_16x16x32_bf16 v[118:121], v[158:161], v[198:201], v[118:121]
	v_mfma_f32_16x16x32_bf16 v[110:113], v[166:169], v[198:201], v[110:113]
	v_mfma_f32_16x16x32_bf16 v[102:105], v[158:161], v[206:209], v[102:105]
	v_mfma_f32_16x16x32_bf16 v[94:97], v[166:169], v[206:209], v[94:97]
	v_mfma_f32_16x16x32_bf16 v[86:89], v[158:161], v[224:227], v[86:89]
	v_mfma_f32_16x16x32_bf16 v[78:81], v[166:169], v[224:227], v[78:81]
	v_mfma_f32_16x16x32_bf16 v[126:129], v[162:165], v[194:197], v[126:129]
	v_mfma_f32_16x16x32_bf16 v[122:125], v[170:173], v[194:197], v[122:125]
	v_mfma_f32_16x16x32_bf16 v[118:121], v[162:165], v[202:205], v[118:121]
	v_mfma_f32_16x16x32_bf16 v[110:113], v[170:173], v[202:205], v[110:113]
	v_mfma_f32_16x16x32_bf16 v[102:105], v[162:165], v[220:223], v[102:105]
	v_mfma_f32_16x16x32_bf16 v[94:97], v[170:173], v[220:223], v[94:97]
	v_mfma_f32_16x16x32_bf16 v[86:89], v[162:165], v[228:231], v[86:89]
	v_mfma_f32_16x16x32_bf16 v[78:81], v[170:173], v[228:231], v[78:81]
	s_setprio 0
	s_setprio 1
	v_mfma_f32_16x16x32_bf16 v[114:117], v[174:177], v[190:193], v[114:117]
	v_mfma_f32_16x16x32_bf16 v[106:109], v[182:185], v[190:193], v[106:109]
	v_mfma_f32_16x16x32_bf16 v[98:101], v[174:177], v[198:201], v[98:101]
	v_mfma_f32_16x16x32_bf16 v[90:93], v[182:185], v[198:201], v[90:93]
	v_mfma_f32_16x16x32_bf16 v[82:85], v[174:177], v[206:209], v[82:85]
	v_mfma_f32_16x16x32_bf16 v[74:77], v[182:185], v[206:209], v[74:77]
	v_mfma_f32_16x16x32_bf16 v[70:73], v[174:177], v[224:227], v[70:73]
	v_mfma_f32_16x16x32_bf16 v[66:69], v[182:185], v[224:227], v[66:69]
	v_mfma_f32_16x16x32_bf16 v[114:117], v[178:181], v[194:197], v[114:117]
	v_mfma_f32_16x16x32_bf16 v[106:109], v[186:189], v[194:197], v[106:109]
	v_mfma_f32_16x16x32_bf16 v[98:101], v[178:181], v[202:205], v[98:101]
	v_mfma_f32_16x16x32_bf16 v[90:93], v[186:189], v[202:205], v[90:93]
	v_mfma_f32_16x16x32_bf16 v[82:85], v[178:181], v[220:223], v[82:85]
	v_mfma_f32_16x16x32_bf16 v[74:77], v[186:189], v[220:223], v[74:77]
	v_mfma_f32_16x16x32_bf16 v[70:73], v[178:181], v[228:231], v[70:73]
	v_mfma_f32_16x16x32_bf16 v[66:69], v[186:189], v[228:231], v[66:69]
	s_setprio 0
	s_barrier
; #define PG8_STAGE(bufoff, gbase, voff) do { _Pragma("unroll") for (int _i = 0; _i < 2; ++_i) \
;         __builtin_amdgcn_global_load_lds((const unsigned*)((const char*)(gbase) + (voff)[_i]), (PG8_LAS unsigned*)(lds + (bufoff) + ldsw + _i * 8192), 16, 0, 0); } while (0)
; #define PG8_LDA(dst, b, h) do { _Pragma("unroll") for (int m = 0; m < 4; ++m) _Pragma("unroll") for (int k = 0; k < 2; ++k) dst[m][k] = *(const PG8_LAS bf16x8*)(lds + PG8_SA(b, h) + aoff + m * 2048 + k * 1024); } while (0)
; #define PG8_MMA(ai, bj, At, Bt) do { __builtin_amdgcn_s_setprio(1); _Pragma("unroll") for (int m = 0; m < 4; ++m) _Pragma("unroll") for (int n = 0; n < 2; ++n) _Pragma("unroll") for (int k = 0; k < 2; ++k) \
;         acc[ai][bj][m][n] = __builtin_amdgcn_mfma_f32_16x16x32_bf16(Bt[n][k], At[m][k], acc[ai][bj][m][n], 0, 0, 0); __builtin_amdgcn_s_setprio(0); } while (0)
; #define PG8_WAIT_V(n) asm volatile("s_waitcnt vmcnt(" #n ")" ::: "memory")
; #define PG8_WAIT_L(n) asm volatile("s_waitcnt lgkmcnt(" #n ")" ::: "memory")
; #define PG8_BAR __builtin_amdgcn_s_barrier()
; #define PG8_SCHED __builtin_amdgcn_sched_barrier(0)
; template <class Epi, class Sched, bool ALIGN_EPI = false, bool SP2 = false>
; __device__ __forceinline__ void gemm_phase(PG8_LAS unsigned char* lds, const Gemm g, const Sched& S, const Epi& E) {
;     ...
;         for (int t = 0; t < nt; t += 2) {
;             const bool last = (t == nt - 2);
;     ...
;             PG8_LDA(At, 1, 1); PG8_STAGE(PG8_SB(1, 0), b3, voffB); PG8_STAGE(PG8_SB(1, 1), b3 + hstep, voffB); PG8_STAGE(PG8_SA(1, 0), a3, voffA);
;             PG8_WAIT_V(8); PG8_WAIT_L(0); PG8_BAR; PG8_MMA(1, 0, At, B0); PG8_MMA(1, 1, At, B1); PG8_BAR; PG8_SCHED;
;     ...
;         if constexpr (ALIGN_EPI) { if (wr == 0) PG8_BAR; }
	s_add_i32 s20, s52, s26
	v_lshl_add_u64 v[210:211], v[210:211], 0, s[94:95]
	s_mov_b32 m0, s20
	ds_read_b128 v[190:193], v156 offset:49152
	ds_read_b128 v[194:197], v156 offset:50176
	ds_read_b128 v[198:201], v156 offset:51200
	ds_read_b128 v[202:205], v156 offset:52224
	ds_read_b128 v[206:209], v156 offset:53248
	ds_read_b128 v[220:223], v156 offset:54272
	ds_read_b128 v[224:227], v156 offset:55296
	ds_read_b128 v[228:231], v156 offset:56320
	global_load_lds_dwordx4 v[210:211], off
	s_add_i32 m0, s20, 0x2000
	s_add_u32 s16, s16, 0x40080
	v_lshl_add_u64 v[210:211], v[212:213], 0, s[94:95]
	s_addc_u32 s17, s17, 0
	s_add_i32 s20, s53, s26
	global_load_lds_dwordx4 v[210:211], off
	v_lshl_add_u64 v[210:211], s[16:17], 0, v[134:135]
	s_mov_b32 m0, s20
	s_nop 0
	global_load_lds_dwordx4 v[210:211], off
	v_lshl_add_u64 v[210:211], s[16:17], 0, v[130:131]
	s_add_i32 m0, s20, 0x2000
	s_nop 0
	global_load_lds_dwordx4 v[210:211], off
	v_lshl_add_u64 v[210:211], v[214:215], 0, s[94:95]
	s_mov_b32 m0, s38
	s_nop 0
	global_load_lds_dwordx4 v[210:211], off
	v_lshl_add_u64 v[210:211], v[216:217], 0, s[94:95]
	s_mov_b32 m0, s39
	s_nop 0
	global_load_lds_dwordx4 v[210:211], off
	s_waitcnt vmcnt(8)
	s_waitcnt lgkmcnt(0)
	s_barrier
	s_setprio 1
	s_waitcnt lgkmcnt(0)
	v_mfma_f32_16x16x32_bf16 v[62:65], v[158:161], v[190:193], v[62:65]
	v_mfma_f32_16x16x32_bf16 v[58:61], v[166:169], v[190:193], v[58:61]
	v_mfma_f32_16x16x32_bf16 v[54:57], v[158:161], v[198:201], v[54:57]
	v_mfma_f32_16x16x32_bf16 v[46:49], v[166:169], v[198:201], v[46:49]
	v_mfma_f32_16x16x32_bf16 v[38:41], v[158:161], v[206:209], v[38:41]
	v_mfma_f32_16x16x32_bf16 v[30:33], v[166:169], v[206:209], v[30:33]
	v_mfma_f32_16x16x32_bf16 v[22:25], v[158:161], v[224:227], v[22:25]
	v_mfma_f32_16x16x32_bf16 v[14:17], v[166:169], v[224:227], v[14:17]
	v_mfma_f32_16x16x32_bf16 v[62:65], v[162:165], v[194:197], v[62:65]
	v_mfma_f32_16x16x32_bf16 v[58:61], v[170:173], v[194:197], v[58:61]
	v_mfma_f32_16x16x32_bf16 v[54:57], v[162:165], v[202:205], v[54:57]
	v_mfma_f32_16x16x32_bf16 v[46:49], v[170:173], v[202:205], v[46:49]
	v_mfma_f32_16x16x32_bf16 v[38:41], v[162:165], v[220:223], v[38:41]
	v_mfma_f32_16x16x32_bf16 v[30:33], v[170:173], v[220:223], v[30:33]
	v_mfma_f32_16x16x32_bf16 v[22:25], v[162:165], v[228:231], v[22:25]
	v_mfma_f32_16x16x32_bf16 v[14:17], v[170:173], v[228:231], v[14:17]
	s_setprio 0
	s_setprio 1
	v_mfma_f32_16x16x32_bf16 v[50:53], v[174:177], v[190:193], v[50:53]
	v_mfma_f32_16x16x32_bf16 v[42:45], v[182:185], v[190:193], v[42:45]
	v_mfma_f32_16x16x32_bf16 v[34:37], v[174:177], v[198:201], v[34:37]
	v_mfma_f32_16x16x32_bf16 v[26:29], v[182:185], v[198:201], v[26:29]
	v_mfma_f32_16x16x32_bf16 v[18:21], v[174:177], v[206:209], v[18:21]
	v_mfma_f32_16x16x32_bf16 v[10:13], v[182:185], v[206:209], v[10:13]
	v_mfma_f32_16x16x32_bf16 v[6:9], v[174:177], v[224:227], v[6:9]
	v_mfma_f32_16x16x32_bf16 v[2:5], v[182:185], v[224:227], v[2:5]
	v_mfma_f32_16x16x32_bf16 v[50:53], v[178:181], v[194:197], v[50:53]
	v_mfma_f32_16x16x32_bf16 v[42:45], v[186:189], v[194:197], v[42:45]
	v_mfma_f32_16x16x32_bf16 v[34:37], v[178:181], v[202:205], v[34:37]
	v_mfma_f32_16x16x32_bf16 v[26:29], v[186:189], v[202:205], v[26:29]
	v_mfma_f32_16x16x32_bf16 v[18:21], v[178:181], v[220:223], v[18:21]
	v_mfma_f32_16x16x32_bf16 v[10:13], v[186:189], v[220:223], v[10:13]
	v_mfma_f32_16x16x32_bf16 v[6:9], v[178:181], v[228:231], v[6:9]
	v_mfma_f32_16x16x32_bf16 v[2:5], v[186:189], v[228:231], v[2:5]
	s_add_i32 s50, s50, 2
	s_add_u32 s18, s18, 0x100
	s_addc_u32 s19, s19, 0
	s_add_u32 vcc_lo, vcc_lo, 0x100
	s_addc_u32 vcc_hi, vcc_hi, 0
	s_add_u32 s16, s18, 0xfffc0080
	s_addc_u32 s17, s19, -1
	s_add_i32 s52, 0, 0x10000
	s_cmp_eq_u32 s50, 12
	s_cselect_b32 s21, s11, s17
	s_cselect_b32 s20, s46, s16
	s_cselect_b32 s17, s9, vcc_hi
	s_cselect_b32 s16, s57, vcc_lo
	s_add_i32 s63, 0, 0x14000
	s_cmp_gt_u32 s50, 13
	s_setprio 0
	s_barrier
	s_cbranch_scc0 .LBB0_247
	s_and_b64 vcc, exec, s[6:7]
	s_cbranch_vccz .LBB0_252
	s_barrier
	s_cmp_gt_i32 s56, 5
	s_mov_b64 s[16:17], -1
	s_cbranch_scc1 .LBB0_253

;     __device__ __forceinline__ bool next(int i, Unit& u) const { const int L = i * G + c; if (L >= 512) return false; u.pm = L; u.pn = L >> 4; return true; }
; #define PG8_STAGE(bufoff, gbase, voff) do { _Pragma("unroll") for (int _i = 0; _i < 2; ++_i) \
;         __builtin_amdgcn_global_load_lds((const unsigned*)((const char*)(gbase) + (voff)[_i]), (PG8_LAS unsigned*)(lds + (bufoff) + ldsw + _i * 8192), 16, 0, 0); } while (0)
; #define PG8_LDA(dst, b, h) do { _Pragma("unroll") for (int m = 0; m < 4; ++m) _Pragma("unroll") for (int k = 0; k < 2; ++k) dst[m][k] = *(const PG8_LAS bf16x8*)(lds + PG8_SA(b, h) + aoff + m * 2048 + k * 1024); } while (0)
; #define PG8_LDB(dst, b, h) do { _Pragma("unroll") for (int n = 0; n < 2; ++n) _Pragma("unroll") for (int k = 0; k < 2; ++k) dst[n][k] = *(const PG8_LAS bf16x8*)(lds + PG8_SB(b, h) + boff + n * 2048 + k * 1024); } while (0)
; #define PG8_WAIT_V(n) asm volatile("s_waitcnt vmcnt(" #n ")" ::: "memory")
; #define PG8_BAR __builtin_amdgcn_s_barrier()
; template <class Epi, class Sched, bool ALIGN_EPI = false, bool SP2 = false>
; __device__ __forceinline__ void gemm_phase(PG8_LAS unsigned char* lds, const Gemm g, const Sched& S, const Epi& E) {
;     ...
;         const bool has_next = S.next(ui + 1, nxt);
;         const char* nA = has_next ? (const char*)g.A + (size_t)nxt.pm * tstep : cA; const char* nB = has_next ? (const char*)g.Bt + (size_t)nxt.pn * tstep : cB;
;         for (int t = 0; t < nt; t += 2) {
;             const bool last = (t == nt - 2);
;             const char* a1 = cA + (size_t)(t + 1) * kstep;
;             const char* a2 = last ? nA : cA + (size_t)(t + 2) * kstep; const char* b2 = last ? nB : cB + (size_t)(t + 2) * kstep;
;             const char* a3 = a2 + kstep; const char* b3 = b2 + kstep;
;             if (last && has_next) S.a_ready(nxt);
;             if constexpr (SP2) {
;             PG8_LDB(B0, 0, 0); PG8_LDB(B1, 0, 1); PG8_SCHED; PG8_LDA(At, 0, 0); PG8_STAGE(PG8_SA(1, 1), a1 + hstep, voffA);
;             PG8_WAIT_V(8); PG8_WAIT_L(0); PG8_BAR; PG8_MMA(0, 0, At, B0); PG8_MMA(0, 1, At, B1); PG8_BAR; PG8_SCHED;
;             PG8_LDA(At, 0, 1); PG8_STAGE(PG8_SB(0, 0), b2, voffB); PG8_STAGE(PG8_SB(0, 1), b2 + hstep, voffB); PG8_STAGE(PG8_SA(0, 0), a2, voffA);
;             PG8_WAIT_V(8); PG8_WAIT_L(0); PG8_BAR; PG8_MMA(1, 0, At, B0); PG8_MMA(1, 1, At, B1); PG8_BAR; PG8_SCHED;
.Lboff_skip_F:
	s_add_u32 s16, s22, 0xfffe0080
	s_addc_u32 s17, s23, -1
	s_add_i32 s52, 0, 0x10000
	s_cmp_eq_u32 s50, 4
	s_cselect_b32 s25, s15, s17
	s_cselect_b32 s24, s55, s16
	s_cselect_b32 s17, s13, s60
	s_cselect_b32 s16, s56, s57
	s_add_i32 s61, 0, 0x14000
.LBB0_547:
	v_add_u32_e32 v0, s52, v244
	ds_read_b128 v[74:77], v0
	ds_read_b128 v[82:85], v0 offset:1024
	ds_read_b128 v[90:93], v0 offset:2048
	ds_read_b128 v[94:97], v0 offset:3072
	v_add_u32_e32 v0, s61, v244
	ds_read_b128 v[98:101], v0
	ds_read_b128 v[110:113], v0 offset:1024
	ds_read_b128 v[114:117], v0 offset:2048
	ds_read_b128 v[130:133], v0 offset:3072
	v_lshl_add_u64 v[194:195], s[22:23], 0, v[220:221]
	s_add_i32 m0, s31, 0xc000
	ds_read_b128 v[138:141], v245
	ds_read_b128 v[150:153], v245 offset:1024
	ds_read_b128 v[162:165], v245 offset:2048
	ds_read_b128 v[174:177], v245 offset:3072
	ds_read_b128 v[178:181], v245 offset:4096
	ds_read_b128 v[182:185], v245 offset:5120
	ds_read_b128 v[186:189], v245 offset:6144
	ds_read_b128 v[190:193], v245 offset:7168
	global_load_lds_dwordx4 v[194:195], off
	v_lshl_add_u64 v[194:195], s[22:23], 0, v[222:223]
	s_add_i32 m0, s31, 0xe000
	s_nop 0
	global_load_lds_dwordx4 v[194:195], off
	s_waitcnt vmcnt(8)
	s_waitcnt lgkmcnt(0)
	s_barrier
	s_setprio 1
	s_waitcnt lgkmcnt(0)
	v_mfma_f32_16x16x32_bf16 v[170:173], v[74:77], v[138:141], v[170:173]
	v_mfma_f32_16x16x32_bf16 v[166:169], v[90:93], v[138:141], v[166:169]
	v_mfma_f32_16x16x32_bf16 v[146:149], v[74:77], v[162:165], v[146:149]
	v_mfma_f32_16x16x32_bf16 v[142:145], v[90:93], v[162:165], v[142:145]
	v_mfma_f32_16x16x32_bf16 v[122:125], v[74:77], v[178:181], v[122:125]
	v_mfma_f32_16x16x32_bf16 v[118:121], v[90:93], v[178:181], v[118:121]
	v_mfma_f32_16x16x32_bf16 v[86:89], v[74:77], v[186:189], v[86:89]
	v_mfma_f32_16x16x32_bf16 v[78:81], v[90:93], v[186:189], v[78:81]
	v_mfma_f32_16x16x32_bf16 v[170:173], v[82:85], v[150:153], v[170:173]
	v_mfma_f32_16x16x32_bf16 v[166:169], v[94:97], v[150:153], v[166:169]
	v_mfma_f32_16x16x32_bf16 v[146:149], v[82:85], v[174:177], v[146:149]
	v_mfma_f32_16x16x32_bf16 v[142:145], v[94:97], v[174:177], v[142:145]
	v_mfma_f32_16x16x32_bf16 v[122:125], v[82:85], v[182:185], v[122:125]
	v_mfma_f32_16x16x32_bf16 v[118:121], v[94:97], v[182:185], v[118:121]
	v_mfma_f32_16x16x32_bf16 v[86:89], v[82:85], v[190:193], v[86:89]
	v_mfma_f32_16x16x32_bf16 v[78:81], v[94:97], v[190:193], v[78:81]
	s_setprio 0
	s_setprio 1
	v_mfma_f32_16x16x32_bf16 v[158:161], v[98:101], v[138:141], v[158:161]
	v_mfma_f32_16x16x32_bf16 v[134:137], v[98:101], v[162:165], v[134:137]
	v_mfma_f32_16x16x32_bf16 v[126:129], v[114:117], v[162:165], v[126:129]
	v_mfma_f32_16x16x32_bf16 v[106:109], v[98:101], v[178:181], v[106:109]
	v_mfma_f32_16x16x32_bf16 v[102:105], v[114:117], v[178:181], v[102:105]
	v_mfma_f32_16x16x32_bf16 v[70:73], v[98:101], v[186:189], v[70:73]
	v_mfma_f32_16x16x32_bf16 v[66:69], v[114:117], v[186:189], v[66:69]
	v_mfma_f32_16x16x32_bf16 v[158:161], v[110:113], v[150:153], v[158:161]
	v_mfma_f32_16x16x32_bf16 v[138:141], v[114:117], v[138:141], v[154:157]
	v_mfma_f32_16x16x32_bf16 v[134:137], v[110:113], v[174:177], v[134:137]
	v_mfma_f32_16x16x32_bf16 v[126:129], v[130:133], v[174:177], v[126:129]
	v_mfma_f32_16x16x32_bf16 v[106:109], v[110:113], v[182:185], v[106:109]
	v_mfma_f32_16x16x32_bf16 v[102:105], v[130:133], v[182:185], v[102:105]
	v_mfma_f32_16x16x32_bf16 v[70:73], v[110:113], v[190:193], v[70:73]
	v_mfma_f32_16x16x32_bf16 v[66:69], v[130:133], v[190:193], v[66:69]
	v_mfma_f32_16x16x32_bf16 v[138:141], v[130:133], v[150:153], v[138:141]
	s_setprio 0
	s_barrier
	s_add_i32 s52, s52, s30
	v_lshl_add_u64 v[194:195], s[16:17], 0, v[206:207]
	s_mov_b32 m0, s52
	ds_read_b128 v[150:153], v245 offset:16384
	ds_read_b128 v[154:157], v245 offset:17408
	ds_read_b128 v[162:165], v245 offset:18432
	ds_read_b128 v[174:177], v245 offset:19456
	ds_read_b128 v[178:181], v245 offset:20480
	ds_read_b128 v[182:185], v245 offset:21504
	ds_read_b128 v[186:189], v245 offset:22528
	ds_read_b128 v[190:193], v245 offset:23552
	global_load_lds_dwordx4 v[194:195], off
	s_add_i32 m0, s52, 0x2000
	s_add_u32 s52, s16, 0x20000
	v_lshl_add_u64 v[196:197], s[16:17], 0, v[202:203]
	s_addc_u32 s53, s17, 0
	s_add_i32 s61, s61, s30
	global_load_lds_dwordx4 v[196:197], off
	v_lshl_add_u64 v[198:199], s[52:53], 0, v[206:207]
	s_mov_b32 m0, s61
	v_lshl_add_u64 v[200:201], s[24:25], 0, v[204:205]
	global_load_lds_dwordx4 v[198:199], off
	v_lshl_add_u64 v[198:199], s[52:53], 0, v[202:203]
	s_add_i32 m0, s61, 0x2000
	s_nop 0
	global_load_lds_dwordx4 v[198:199], off
	v_lshl_add_u64 v[198:199], s[24:25], 0, v[208:209]
	s_mov_b32 m0, s31
	s_nop 0
	global_load_lds_dwordx4 v[198:199], off
	s_mov_b32 m0, s34
	s_nop 0
	global_load_lds_dwordx4 v[200:201], off
	s_waitcnt vmcnt(8)
	s_waitcnt lgkmcnt(0)
	s_barrier
; #define PG8_STAGE(bufoff, gbase, voff) do { _Pragma("unroll") for (int _i = 0; _i < 2; ++_i) \
;         __builtin_amdgcn_global_load_lds((const unsigned*)((const char*)(gbase) + (voff)[_i]), (PG8_LAS unsigned*)(lds + (bufoff) + ldsw + _i * 8192), 16, 0, 0); } while (0)
; #define PG8_LDA(dst, b, h) do { _Pragma("unroll") for (int m = 0; m < 4; ++m) _Pragma("unroll") for (int k = 0; k < 2; ++k) dst[m][k] = *(const PG8_LAS bf16x8*)(lds + PG8_SA(b, h) + aoff + m * 2048 + k * 1024); } while (0)
; #define PG8_LDB(dst, b, h) do { _Pragma("unroll") for (int n = 0; n < 2; ++n) _Pragma("unroll") for (int k = 0; k < 2; ++k) dst[n][k] = *(const PG8_LAS bf16x8*)(lds + PG8_SB(b, h) + boff + n * 2048 + k * 1024); } while (0)
; #define PG8_MMA(ai, bj, At, Bt) do { __builtin_amdgcn_s_setprio(1); _Pragma("unroll") for (int m = 0; m < 4; ++m) _Pragma("unroll") for (int n = 0; n < 2; ++n) _Pragma("unroll") for (int k = 0; k < 2; ++k) \
;         acc[ai][bj][m][n] = __builtin_amdgcn_mfma_f32_16x16x32_bf16(Bt[n][k], At[m][k], acc[ai][bj][m][n], 0, 0, 0); __builtin_amdgcn_s_setprio(0); } while (0)
; #define PG8_WAIT_V(n) asm volatile("s_waitcnt vmcnt(" #n ")" ::: "memory")
; #define PG8_WAIT_L(n) asm volatile("s_waitcnt lgkmcnt(" #n ")" ::: "memory")
; #define PG8_BAR __builtin_amdgcn_s_barrier()
; #define PG8_SCHED __builtin_amdgcn_sched_barrier(0)
; template <class Epi, class Sched, bool ALIGN_EPI = false, bool SP2 = false>
; __device__ __forceinline__ void gemm_phase(PG8_LAS unsigned char* lds, const Gemm g, const Sched& S, const Epi& E) {
;     ...
;             PG8_WAIT_V(8); PG8_WAIT_L(0); PG8_BAR; PG8_MMA(1, 0, At, B0); PG8_MMA(1, 1, At, B1); PG8_BAR; PG8_SCHED;
;             PG8_LDB(B0, 1, 0); PG8_LDB(B1, 1, 1); PG8_SCHED; PG8_LDA(At, 1, 0); PG8_STAGE(PG8_SA(0, 1), a2 + hstep, voffA);
;             PG8_WAIT_V(8); PG8_WAIT_L(0); PG8_BAR; PG8_MMA(0, 0, At, B0); PG8_MMA(0, 1, At, B1); PG8_BAR; PG8_SCHED;
	s_setprio 1
	s_waitcnt lgkmcnt(0)
	v_mfma_f32_16x16x32_bf16 v[62:65], v[74:77], v[150:153], v[62:65]
	v_mfma_f32_16x16x32_bf16 v[58:61], v[90:93], v[150:153], v[58:61]
	v_mfma_f32_16x16x32_bf16 v[46:49], v[74:77], v[162:165], v[46:49]
	v_mfma_f32_16x16x32_bf16 v[42:45], v[90:93], v[162:165], v[42:45]
	v_mfma_f32_16x16x32_bf16 v[30:33], v[74:77], v[178:181], v[30:33]
	v_mfma_f32_16x16x32_bf16 v[26:29], v[90:93], v[178:181], v[26:29]
	v_mfma_f32_16x16x32_bf16 v[14:17], v[74:77], v[186:189], v[14:17]
	v_mfma_f32_16x16x32_bf16 v[10:13], v[90:93], v[186:189], v[10:13]
	v_mfma_f32_16x16x32_bf16 v[62:65], v[82:85], v[154:157], v[62:65]
	v_mfma_f32_16x16x32_bf16 v[58:61], v[94:97], v[154:157], v[58:61]
	v_mfma_f32_16x16x32_bf16 v[46:49], v[82:85], v[174:177], v[46:49]
	v_mfma_f32_16x16x32_bf16 v[42:45], v[94:97], v[174:177], v[42:45]
	v_mfma_f32_16x16x32_bf16 v[30:33], v[82:85], v[182:185], v[30:33]
	v_mfma_f32_16x16x32_bf16 v[26:29], v[94:97], v[182:185], v[26:29]
	v_mfma_f32_16x16x32_bf16 v[14:17], v[82:85], v[190:193], v[14:17]
	v_mfma_f32_16x16x32_bf16 v[10:13], v[94:97], v[190:193], v[10:13]
	s_setprio 0
	s_setprio 1
	v_mfma_f32_16x16x32_bf16 v[54:57], v[98:101], v[150:153], v[54:57]
	v_mfma_f32_16x16x32_bf16 v[50:53], v[114:117], v[150:153], v[50:53]
	v_mfma_f32_16x16x32_bf16 v[38:41], v[98:101], v[162:165], v[38:41]
	v_mfma_f32_16x16x32_bf16 v[34:37], v[114:117], v[162:165], v[34:37]
	v_mfma_f32_16x16x32_bf16 v[22:25], v[98:101], v[178:181], v[22:25]
	v_mfma_f32_16x16x32_bf16 v[18:21], v[114:117], v[178:181], v[18:21]
	v_mfma_f32_16x16x32_bf16 v[6:9], v[98:101], v[186:189], v[6:9]
	v_mfma_f32_16x16x32_bf16 v[2:5], v[114:117], v[186:189], v[2:5]
	v_mfma_f32_16x16x32_bf16 v[54:57], v[110:113], v[154:157], v[54:57]
	v_mfma_f32_16x16x32_bf16 v[50:53], v[130:133], v[154:157], v[50:53]
	v_mfma_f32_16x16x32_bf16 v[38:41], v[110:113], v[174:177], v[38:41]
	v_mfma_f32_16x16x32_bf16 v[34:37], v[130:133], v[174:177], v[34:37]
	v_mfma_f32_16x16x32_bf16 v[22:25], v[110:113], v[182:185], v[22:25]
	v_mfma_f32_16x16x32_bf16 v[18:21], v[130:133], v[182:185], v[18:21]
	v_mfma_f32_16x16x32_bf16 v[6:9], v[110:113], v[190:193], v[6:9]
	v_mfma_f32_16x16x32_bf16 v[2:5], v[130:133], v[190:193], v[2:5]
	s_setprio 0
	s_barrier
	s_add_i32 s52, 0, 0x18000
	v_add_u32_e32 v0, s52, v244
	s_add_i32 s53, 0, 0x1c000
	ds_read_b128 v[74:77], v0
	ds_read_b128 v[82:85], v0 offset:1024
	ds_read_b128 v[90:93], v0 offset:2048
	ds_read_b128 v[94:97], v0 offset:3072
	v_add_u32_e32 v0, s53, v244
	ds_read_b128 v[98:101], v0
	ds_read_b128 v[110:113], v0 offset:1024
	ds_read_b128 v[114:117], v0 offset:2048
	ds_read_b128 v[130:133], v0 offset:3072
	s_add_u32 s24, s24, 0x20000
	s_addc_u32 s25, s25, 0
	s_mov_b32 m0, s35
	v_lshl_add_u64 v[212:213], s[24:25], 0, v[208:209]
	ds_read_b128 v[150:153], v245 offset:32768
	ds_read_b128 v[154:157], v245 offset:33792
	ds_read_b128 v[162:165], v245 offset:34816
	ds_read_b128 v[174:177], v245 offset:35840
	ds_read_b128 v[178:181], v245 offset:36864
	ds_read_b128 v[182:185], v245 offset:37888
	ds_read_b128 v[186:189], v245 offset:38912
	ds_read_b128 v[190:193], v245 offset:39936
	global_load_lds_dwordx4 v[212:213], off
	v_lshl_add_u64 v[212:213], s[24:25], 0, v[204:205]
	s_mov_b32 m0, s36
	s_nop 0
	global_load_lds_dwordx4 v[212:213], off
	s_waitcnt vmcnt(8)
	s_waitcnt lgkmcnt(0)
	s_barrier
	s_setprio 1
	s_waitcnt lgkmcnt(0)
	v_mfma_f32_16x16x32_bf16 v[170:173], v[74:77], v[150:153], v[170:173]
	v_mfma_f32_16x16x32_bf16 v[166:169], v[90:93], v[150:153], v[166:169]
	v_mfma_f32_16x16x32_bf16 v[146:149], v[74:77], v[162:165], v[146:149]
	v_mfma_f32_16x16x32_bf16 v[142:145], v[90:93], v[162:165], v[142:145]
	v_mfma_f32_16x16x32_bf16 v[122:125], v[74:77], v[178:181], v[122:125]
	v_mfma_f32_16x16x32_bf16 v[118:121], v[90:93], v[178:181], v[118:121]
	v_mfma_f32_16x16x32_bf16 v[86:89], v[74:77], v[186:189], v[86:89]
	v_mfma_f32_16x16x32_bf16 v[78:81], v[90:93], v[186:189], v[78:81]
	v_mfma_f32_16x16x32_bf16 v[170:173], v[82:85], v[154:157], v[170:173]
	v_mfma_f32_16x16x32_bf16 v[166:169], v[94:97], v[154:157], v[166:169]
	v_mfma_f32_16x16x32_bf16 v[146:149], v[82:85], v[174:177], v[146:149]
	v_mfma_f32_16x16x32_bf16 v[142:145], v[94:97], v[174:177], v[142:145]
	v_mfma_f32_16x16x32_bf16 v[122:125], v[82:85], v[182:185], v[122:125]
	v_mfma_f32_16x16x32_bf16 v[118:121], v[94:97], v[182:185], v[118:121]
	v_mfma_f32_16x16x32_bf16 v[86:89], v[82:85], v[190:193], v[86:89]
	v_mfma_f32_16x16x32_bf16 v[78:81], v[94:97], v[190:193], v[78:81]
	s_setprio 0
	s_setprio 1
	v_mfma_f32_16x16x32_bf16 v[158:161], v[98:101], v[150:153], v[158:161]
	v_mfma_f32_16x16x32_bf16 v[138:141], v[114:117], v[150:153], v[138:141]
	v_mfma_f32_16x16x32_bf16 v[134:137], v[98:101], v[162:165], v[134:137]
	v_mfma_f32_16x16x32_bf16 v[126:129], v[114:117], v[162:165], v[126:129]
	v_mfma_f32_16x16x32_bf16 v[106:109], v[98:101], v[178:181], v[106:109]
	v_mfma_f32_16x16x32_bf16 v[102:105], v[114:117], v[178:181], v[102:105]
	v_mfma_f32_16x16x32_bf16 v[70:73], v[98:101], v[186:189], v[70:73]
	v_mfma_f32_16x16x32_bf16 v[66:69], v[114:117], v[186:189], v[66:69]
	v_mfma_f32_16x16x32_bf16 v[158:161], v[110:113], v[154:157], v[158:161]
	v_mfma_f32_16x16x32_bf16 v[154:157], v[130:133], v[154:157], v[138:141]
	v_mfma_f32_16x16x32_bf16 v[134:137], v[110:113], v[174:177], v[134:137]
	v_mfma_f32_16x16x32_bf16 v[126:129], v[130:133], v[174:177], v[126:129]
	v_mfma_f32_16x16x32_bf16 v[106:109], v[110:113], v[182:185], v[106:109]
	v_mfma_f32_16x16x32_bf16 v[102:105], v[130:133], v[182:185], v[102:105]
	v_mfma_f32_16x16x32_bf16 v[70:73], v[110:113], v[190:193], v[70:73]
	v_mfma_f32_16x16x32_bf16 v[66:69], v[130:133], v[190:193], v[66:69]
	s_setprio 0
	s_barrier
; #define PG8_STAGE(bufoff, gbase, voff) do { _Pragma("unroll") for (int _i = 0; _i < 2; ++_i) \
;         __builtin_amdgcn_global_load_lds((const unsigned*)((const char*)(gbase) + (voff)[_i]), (PG8_LAS unsigned*)(lds + (bufoff) + ldsw + _i * 8192), 16, 0, 0); } while (0)
; #define PG8_LDA(dst, b, h) do { _Pragma("unroll") for (int m = 0; m < 4; ++m) _Pragma("unroll") for (int k = 0; k < 2; ++k) dst[m][k] = *(const PG8_LAS bf16x8*)(lds + PG8_SA(b, h) + aoff + m * 2048 + k * 1024); } while (0)
; #define PG8_MMA(ai, bj, At, Bt) do { __builtin_amdgcn_s_setprio(1); _Pragma("unroll") for (int m = 0; m < 4; ++m) _Pragma("unroll") for (int n = 0; n < 2; ++n) _Pragma("unroll") for (int k = 0; k < 2; ++k) \
;         acc[ai][bj][m][n] = __builtin_amdgcn_mfma_f32_16x16x32_bf16(Bt[n][k], At[m][k], acc[ai][bj][m][n], 0, 0, 0); __builtin_amdgcn_s_setprio(0); } while (0)
; #define PG8_WAIT_V(n) asm volatile("s_waitcnt vmcnt(" #n ")" ::: "memory")
; #define PG8_WAIT_L(n) asm volatile("s_waitcnt lgkmcnt(" #n ")" ::: "memory")
; #define PG8_BAR __builtin_amdgcn_s_barrier()
; #define PG8_SCHED __builtin_amdgcn_sched_barrier(0)
; template <class Epi, class Sched, bool ALIGN_EPI = false, bool SP2 = false>
; __device__ __forceinline__ void gemm_phase(PG8_LAS unsigned char* lds, const Gemm g, const Sched& S, const Epi& E) {
;     ...
;         for (int t = 0; t < nt; t += 2) {
;             const bool last = (t == nt - 2);
;     ...
;             PG8_LDA(At, 1, 1); PG8_STAGE(PG8_SB(1, 0), b3, voffB); PG8_STAGE(PG8_SB(1, 1), b3 + hstep, voffB); PG8_STAGE(PG8_SA(1, 0), a3, voffA);
;             PG8_WAIT_V(8); PG8_WAIT_L(0); PG8_BAR; PG8_MMA(1, 0, At, B0); PG8_MMA(1, 1, At, B1); PG8_BAR; PG8_SCHED;
;     ...
;         if constexpr (ALIGN_EPI) { if (wr == 0) PG8_BAR; }
	s_add_i32 s24, s52, s30
	v_lshl_add_u64 v[194:195], v[194:195], 0, s[94:95]
	s_mov_b32 m0, s24
	ds_read_b128 v[138:141], v245 offset:49152
	ds_read_b128 v[150:153], v245 offset:50176
	ds_read_b128 v[162:165], v245 offset:51200
	ds_read_b128 v[174:177], v245 offset:52224
	ds_read_b128 v[178:181], v245 offset:53248
	ds_read_b128 v[182:185], v245 offset:54272
	ds_read_b128 v[186:189], v245 offset:55296
	ds_read_b128 v[190:193], v245 offset:56320
	global_load_lds_dwordx4 v[194:195], off
	s_add_i32 m0, s24, 0x2000
	s_add_u32 s16, s16, 0x20080
	v_lshl_add_u64 v[194:195], v[196:197], 0, s[94:95]
	s_addc_u32 s17, s17, 0
	s_add_i32 s24, s53, s30
	global_load_lds_dwordx4 v[194:195], off
	v_lshl_add_u64 v[194:195], s[16:17], 0, v[206:207]
	s_mov_b32 m0, s24
	s_nop 0
	global_load_lds_dwordx4 v[194:195], off
	v_lshl_add_u64 v[194:195], s[16:17], 0, v[202:203]
	s_add_i32 m0, s24, 0x2000
	s_nop 0
	global_load_lds_dwordx4 v[194:195], off
	v_lshl_add_u64 v[194:195], v[198:199], 0, s[94:95]
	s_mov_b32 m0, s37
	s_nop 0
	global_load_lds_dwordx4 v[194:195], off
	v_lshl_add_u64 v[194:195], v[200:201], 0, s[94:95]
	s_mov_b32 m0, s38
	s_nop 0
	global_load_lds_dwordx4 v[194:195], off
	s_waitcnt vmcnt(8)
	s_waitcnt lgkmcnt(0)
	s_barrier
	s_setprio 1
	s_waitcnt lgkmcnt(0)
	v_mfma_f32_16x16x32_bf16 v[62:65], v[74:77], v[138:141], v[62:65]
	v_mfma_f32_16x16x32_bf16 v[58:61], v[90:93], v[138:141], v[58:61]
	v_mfma_f32_16x16x32_bf16 v[46:49], v[74:77], v[162:165], v[46:49]
	v_mfma_f32_16x16x32_bf16 v[42:45], v[90:93], v[162:165], v[42:45]
	v_mfma_f32_16x16x32_bf16 v[30:33], v[74:77], v[178:181], v[30:33]
	v_mfma_f32_16x16x32_bf16 v[26:29], v[90:93], v[178:181], v[26:29]
	v_mfma_f32_16x16x32_bf16 v[14:17], v[74:77], v[186:189], v[14:17]
	v_mfma_f32_16x16x32_bf16 v[10:13], v[90:93], v[186:189], v[10:13]
	v_mfma_f32_16x16x32_bf16 v[62:65], v[82:85], v[150:153], v[62:65]
	v_mfma_f32_16x16x32_bf16 v[58:61], v[94:97], v[150:153], v[58:61]
	v_mfma_f32_16x16x32_bf16 v[46:49], v[82:85], v[174:177], v[46:49]
	v_mfma_f32_16x16x32_bf16 v[42:45], v[94:97], v[174:177], v[42:45]
	v_mfma_f32_16x16x32_bf16 v[30:33], v[82:85], v[182:185], v[30:33]
	v_mfma_f32_16x16x32_bf16 v[26:29], v[94:97], v[182:185], v[26:29]
	v_mfma_f32_16x16x32_bf16 v[14:17], v[82:85], v[190:193], v[14:17]
	v_mfma_f32_16x16x32_bf16 v[10:13], v[94:97], v[190:193], v[10:13]
	s_setprio 0
	s_setprio 1
	v_mfma_f32_16x16x32_bf16 v[54:57], v[98:101], v[138:141], v[54:57]
	v_mfma_f32_16x16x32_bf16 v[50:53], v[114:117], v[138:141], v[50:53]
	v_mfma_f32_16x16x32_bf16 v[38:41], v[98:101], v[162:165], v[38:41]
	v_mfma_f32_16x16x32_bf16 v[34:37], v[114:117], v[162:165], v[34:37]
	v_mfma_f32_16x16x32_bf16 v[22:25], v[98:101], v[178:181], v[22:25]
	v_mfma_f32_16x16x32_bf16 v[18:21], v[114:117], v[178:181], v[18:21]
	v_mfma_f32_16x16x32_bf16 v[6:9], v[98:101], v[186:189], v[6:9]
	v_mfma_f32_16x16x32_bf16 v[2:5], v[114:117], v[186:189], v[2:5]
	v_mfma_f32_16x16x32_bf16 v[54:57], v[110:113], v[150:153], v[54:57]
	v_mfma_f32_16x16x32_bf16 v[50:53], v[130:133], v[150:153], v[50:53]
	v_mfma_f32_16x16x32_bf16 v[38:41], v[110:113], v[174:177], v[38:41]
	v_mfma_f32_16x16x32_bf16 v[34:37], v[130:133], v[174:177], v[34:37]
	v_mfma_f32_16x16x32_bf16 v[22:25], v[110:113], v[182:185], v[22:25]
	v_mfma_f32_16x16x32_bf16 v[18:21], v[130:133], v[182:185], v[18:21]
	v_mfma_f32_16x16x32_bf16 v[6:9], v[110:113], v[190:193], v[6:9]
	v_mfma_f32_16x16x32_bf16 v[2:5], v[130:133], v[190:193], v[2:5]
	s_add_i32 s50, s50, 2
	s_add_u32 s22, s22, 0x100
	s_addc_u32 s23, s23, 0
	s_add_u32 s57, s57, 0x100
	s_addc_u32 s60, s60, 0
	s_add_u32 s16, s22, 0xfffe0080
	s_addc_u32 s17, s23, -1
	s_add_i32 s52, 0, 0x10000
	s_cmp_eq_u32 s50, 4
	s_cselect_b32 s25, s15, s17
	s_cselect_b32 s24, s55, s16
	s_cselect_b32 s17, s13, s60
	s_cselect_b32 s16, s56, s57
	s_add_i32 s61, 0, 0x14000
	s_cmp_gt_u32 s50, 5
	s_setprio 0
	s_barrier
	s_cbranch_scc0 .LBB0_547
	s_and_b64 vcc, exec, s[10:11]
	s_cbranch_vccz .LBB0_550
	s_barrier

;     __device__ __forceinline__ bool next(int i, Unit& u) const { const int L = i * G + c; if (L >= 512) return false; u.pm = L; u.pn = L >> 4; return true; }
; #define PG8_STAGE(bufoff, gbase, voff) do { _Pragma("unroll") for (int _i = 0; _i < 2; ++_i) \
;         __builtin_amdgcn_global_load_lds((const unsigned*)((const char*)(gbase) + (voff)[_i]), (PG8_LAS unsigned*)(lds + (bufoff) + ldsw + _i * 8192), 16, 0, 0); } while (0)
; #define PG8_LDA(dst, b, h) do { _Pragma("unroll") for (int m = 0; m < 4; ++m) _Pragma("unroll") for (int k = 0; k < 2; ++k) dst[m][k] = *(const PG8_LAS bf16x8*)(lds + PG8_SA(b, h) + aoff + m * 2048 + k * 1024); } while (0)
; #define PG8_LDB(dst, b, h) do { _Pragma("unroll") for (int n = 0; n < 2; ++n) _Pragma("unroll") for (int k = 0; k < 2; ++k) dst[n][k] = *(const PG8_LAS bf16x8*)(lds + PG8_SB(b, h) + boff + n * 2048 + k * 1024); } while (0)
; template <class Epi, class Sched, bool ALIGN_EPI = false, bool SP2 = false>
; __device__ __forceinline__ void gemm_phase(PG8_LAS unsigned char* lds, const Gemm g, const Sched& S, const Epi& E) {
;     ...
;         const bool has_next = S.next(ui + 1, nxt);
;         const char* nA = has_next ? (const char*)g.A + (size_t)nxt.pm * tstep : cA; const char* nB = has_next ? (const char*)g.Bt + (size_t)nxt.pn * tstep : cB;
;         for (int t = 0; t < nt; t += 2) {
;             const bool last = (t == nt - 2);
;             const char* a1 = cA + (size_t)(t + 1) * kstep;
;             const char* a2 = last ? nA : cA + (size_t)(t + 2) * kstep; const char* b2 = last ? nB : cB + (size_t)(t + 2) * kstep;
;             const char* a3 = a2 + kstep; const char* b3 = b2 + kstep;
;             if (last && has_next) S.a_ready(nxt);
;             if constexpr (SP2) {
;             PG8_LDB(B0, 0, 0); PG8_LDB(B1, 0, 1); PG8_SCHED; PG8_LDA(At, 0, 0); PG8_STAGE(PG8_SA(1, 1), a1 + hstep, voffA);
;             PG8_WAIT_V(8); PG8_WAIT_L(0); PG8_BAR; PG8_MMA(0, 0, At, B0); PG8_MMA(0, 1, At, B1); PG8_BAR; PG8_SCHED;
;     ...
; #pragma unroll
;         for (int a = 0; a < 2; ++a)
; #pragma unroll
;             for (int b = 0; b < 2; ++b)
; #pragma unroll
;                 for (int m = 0; m < 4; ++m)
; #pragma unroll
;                     for (int n = 0; n < 2; ++n) acc[a][b][m][n] = (f32x4){0.f, 0.f, 0.f, 0.f};
;         cur = nxt; cA = nA; cB = nB; ++ui;
;         if constexpr (ALIGN_EPI) { if (wr == 1) PG8_BAR; }
.LBB0_566:
	s_ashr_i32 s13, s12, 31
	s_lshl_b64 s[14:15], s[12:13], 18
	s_add_u32 s14, s24, s14
	s_addc_u32 s15, s25, s15
	s_and_b64 s[18:19], s[4:5], exec
	s_cselect_b32 s13, s15, s21
	s_cselect_b32 s55, s14, s20
	s_ashr_i32 s11, s10, 31
	s_lshl_b64 s[18:19], s[10:11], 18
	s_add_u32 s18, s26, s18
	s_addc_u32 s19, s27, s19
	s_and_b64 s[22:23], s[4:5], exec
	s_cselect_b32 s11, s19, s17
	s_cselect_b32 s56, s18, s16
	s_add_u32 s20, s20, 0x20080
	s_addc_u32 s21, s21, 0
	s_add_u32 s57, s16, 0x100
	v_mov_b32_e32 v2, 0
	s_addc_u32 s60, s17, 0
	s_mov_b32 s50, -2
	v_mov_b32_e32 v3, v2
	v_mov_b32_e32 v4, v2
	v_mov_b32_e32 v5, v2
	v_mov_b32_e32 v6, v2
	v_mov_b32_e32 v7, v2
	v_mov_b32_e32 v8, v2
	v_mov_b32_e32 v9, v2
	v_mov_b32_e32 v14, v2
	v_mov_b32_e32 v15, v2
	v_mov_b32_e32 v16, v2
	v_mov_b32_e32 v17, v2
	v_mov_b32_e32 v22, v2
	v_mov_b32_e32 v23, v2
	v_mov_b32_e32 v24, v2
	v_mov_b32_e32 v25, v2
	v_mov_b32_e32 v30, v2
	v_mov_b32_e32 v31, v2
	v_mov_b32_e32 v32, v2
	v_mov_b32_e32 v33, v2
	v_mov_b32_e32 v38, v2
	v_mov_b32_e32 v39, v2
	v_mov_b32_e32 v40, v2
	v_mov_b32_e32 v41, v2
	v_mov_b32_e32 v46, v2
	v_mov_b32_e32 v47, v2
	v_mov_b32_e32 v48, v2
	v_mov_b32_e32 v49, v2
	v_mov_b32_e32 v54, v2
	v_mov_b32_e32 v55, v2
	v_mov_b32_e32 v56, v2
	v_mov_b32_e32 v57, v2
	v_mov_b32_e32 v10, v2
	v_mov_b32_e32 v11, v2
	v_mov_b32_e32 v12, v2
	v_mov_b32_e32 v13, v2
	v_mov_b32_e32 v18, v2
	v_mov_b32_e32 v19, v2
	v_mov_b32_e32 v20, v2
	v_mov_b32_e32 v21, v2
	v_mov_b32_e32 v26, v2
	v_mov_b32_e32 v27, v2
	v_mov_b32_e32 v28, v2
	v_mov_b32_e32 v29, v2
	v_mov_b32_e32 v34, v2
	v_mov_b32_e32 v35, v2
	v_mov_b32_e32 v36, v2
	v_mov_b32_e32 v37, v2
	v_mov_b32_e32 v42, v2
	v_mov_b32_e32 v43, v2
	v_mov_b32_e32 v44, v2
	v_mov_b32_e32 v45, v2
	v_mov_b32_e32 v50, v2
	v_mov_b32_e32 v51, v2
	v_mov_b32_e32 v52, v2
	v_mov_b32_e32 v53, v2
	v_mov_b32_e32 v58, v2
	v_mov_b32_e32 v59, v2
	v_mov_b32_e32 v60, v2
	v_mov_b32_e32 v61, v2
	v_mov_b32_e32 v62, v2
	v_mov_b32_e32 v63, v2
	v_mov_b32_e32 v64, v2
	v_mov_b32_e32 v65, v2
	v_mov_b32_e32 v66, v2
	v_mov_b32_e32 v67, v2
	v_mov_b32_e32 v68, v2
	v_mov_b32_e32 v69, v2
	v_mov_b32_e32 v70, v2
	v_mov_b32_e32 v71, v2
	v_mov_b32_e32 v72, v2
	v_mov_b32_e32 v73, v2
	v_mov_b32_e32 v78, v2
	v_mov_b32_e32 v79, v2
	v_mov_b32_e32 v80, v2
	v_mov_b32_e32 v81, v2
	v_mov_b32_e32 v86, v2
	v_mov_b32_e32 v87, v2
	v_mov_b32_e32 v88, v2
	v_mov_b32_e32 v89, v2
	v_mov_b32_e32 v94, v2
	v_mov_b32_e32 v95, v2
	v_mov_b32_e32 v96, v2
	v_mov_b32_e32 v97, v2
	v_mov_b32_e32 v102, v2
	v_mov_b32_e32 v103, v2
	v_mov_b32_e32 v104, v2
	v_mov_b32_e32 v105, v2
	v_mov_b32_e32 v106, v2
	v_mov_b32_e32 v107, v2
	v_mov_b32_e32 v108, v2
	v_mov_b32_e32 v109, v2
	v_mov_b32_e32 v114, v2
	v_mov_b32_e32 v115, v2
	v_mov_b32_e32 v116, v2
	v_mov_b32_e32 v117, v2
	v_mov_b32_e32 v74, v2
	v_mov_b32_e32 v75, v2
	v_mov_b32_e32 v76, v2
	v_mov_b32_e32 v77, v2
	v_mov_b32_e32 v82, v2
	v_mov_b32_e32 v83, v2
	v_mov_b32_e32 v84, v2
	v_mov_b32_e32 v85, v2
	v_mov_b32_e32 v90, v2
	v_mov_b32_e32 v91, v2
	v_mov_b32_e32 v92, v2
	v_mov_b32_e32 v93, v2
	v_mov_b32_e32 v98, v2
	v_mov_b32_e32 v99, v2
	v_mov_b32_e32 v100, v2
	v_mov_b32_e32 v101, v2
	v_mov_b32_e32 v110, v2
	v_mov_b32_e32 v111, v2
	v_mov_b32_e32 v112, v2
	v_mov_b32_e32 v113, v2
	v_mov_b32_e32 v118, v2
	v_mov_b32_e32 v119, v2
	v_mov_b32_e32 v120, v2
	v_mov_b32_e32 v121, v2
	v_mov_b32_e32 v122, v2
	v_mov_b32_e32 v123, v2
	v_mov_b32_e32 v124, v2
	v_mov_b32_e32 v125, v2
	v_mov_b32_e32 v126, v2
	v_mov_b32_e32 v127, v2
	v_mov_b32_e32 v128, v2
	v_mov_b32_e32 v129, v2
	s_cmp_eq_u64 s[0:1], 0
	s_cbranch_scc1 .Lboff_skip_G
	s_barrier
.Lboff_skip_G:
	s_add_u32 s16, s20, 0xfffe0080
	s_addc_u32 s17, s21, -1
	s_add_i32 s52, 0, 0x10000
	s_cmp_eq_u32 s50, 4
	s_cselect_b32 s23, s13, s17
	s_cselect_b32 s22, s55, s16
	s_cselect_b32 s17, s11, s60
	s_cselect_b32 s16, s56, s57
	s_add_i32 s61, 0, 0x14000
.LBB0_567:
	v_add_u32_e32 v142, s52, v171
	v_add_u32_e32 v173, s61, v171
	ds_read_b128 v[130:133], v142
	ds_read_b128 v[134:137], v142 offset:1024
	ds_read_b128 v[138:141], v142 offset:2048
	ds_read_b128 v[142:145], v142 offset:3072
	ds_read_b128 v[146:149], v173
	ds_read_b128 v[162:165], v173 offset:1024
	ds_read_b128 v[166:169], v173 offset:2048
	ds_read_b128 v[174:177], v173 offset:3072
	v_lshl_add_u64 v[210:211], s[20:21], 0, v[158:159]
	s_add_i32 m0, s29, 0xc000
	ds_read_b128 v[178:181], v172
	ds_read_b128 v[182:185], v172 offset:1024
	ds_read_b128 v[186:189], v172 offset:2048
	ds_read_b128 v[190:193], v172 offset:3072
	ds_read_b128 v[194:197], v172 offset:4096
	ds_read_b128 v[198:201], v172 offset:5120
	ds_read_b128 v[202:205], v172 offset:6144
	ds_read_b128 v[206:209], v172 offset:7168
	global_load_lds_dwordx4 v[210:211], off
	v_lshl_add_u64 v[210:211], s[20:21], 0, v[160:161]
	s_add_i32 m0, s29, 0xe000
	s_nop 0
	global_load_lds_dwordx4 v[210:211], off
	s_waitcnt vmcnt(8)
	s_waitcnt lgkmcnt(0)
	s_barrier
; #define PG8_STAGE(bufoff, gbase, voff) do { _Pragma("unroll") for (int _i = 0; _i < 2; ++_i) \
;         __builtin_amdgcn_global_load_lds((const unsigned*)((const char*)(gbase) + (voff)[_i]), (PG8_LAS unsigned*)(lds + (bufoff) + ldsw + _i * 8192), 16, 0, 0); } while (0)
; #define PG8_LDA(dst, b, h) do { _Pragma("unroll") for (int m = 0; m < 4; ++m) _Pragma("unroll") for (int k = 0; k < 2; ++k) dst[m][k] = *(const PG8_LAS bf16x8*)(lds + PG8_SA(b, h) + aoff + m * 2048 + k * 1024); } while (0)
; #define PG8_MMA(ai, bj, At, Bt) do { __builtin_amdgcn_s_setprio(1); _Pragma("unroll") for (int m = 0; m < 4; ++m) _Pragma("unroll") for (int n = 0; n < 2; ++n) _Pragma("unroll") for (int k = 0; k < 2; ++k) \
;         acc[ai][bj][m][n] = __builtin_amdgcn_mfma_f32_16x16x32_bf16(Bt[n][k], At[m][k], acc[ai][bj][m][n], 0, 0, 0); __builtin_amdgcn_s_setprio(0); } while (0)
; #define PG8_WAIT_V(n) asm volatile("s_waitcnt vmcnt(" #n ")" ::: "memory")
; #define PG8_WAIT_L(n) asm volatile("s_waitcnt lgkmcnt(" #n ")" ::: "memory")
; #define PG8_BAR __builtin_amdgcn_s_barrier()
; #define PG8_SCHED __builtin_amdgcn_sched_barrier(0)
; template <class Epi, class Sched, bool ALIGN_EPI = false, bool SP2 = false>
; __device__ __forceinline__ void gemm_phase(PG8_LAS unsigned char* lds, const Gemm g, const Sched& S, const Epi& E) {
;     ...
;             PG8_WAIT_V(8); PG8_WAIT_L(0); PG8_BAR; PG8_MMA(0, 0, At, B0); PG8_MMA(0, 1, At, B1); PG8_BAR; PG8_SCHED;
;             PG8_LDA(At, 0, 1); PG8_STAGE(PG8_SB(0, 0), b2, voffB); PG8_STAGE(PG8_SB(0, 1), b2 + hstep, voffB); PG8_STAGE(PG8_SA(0, 0), a2, voffA);
;             PG8_WAIT_V(8); PG8_WAIT_L(0); PG8_BAR; PG8_MMA(1, 0, At, B0); PG8_MMA(1, 1, At, B1); PG8_BAR; PG8_SCHED;
	s_setprio 1
	s_waitcnt lgkmcnt(0)
	v_mfma_f32_16x16x32_bf16 v[126:129], v[130:133], v[178:181], v[126:129]
	v_mfma_f32_16x16x32_bf16 v[122:125], v[138:141], v[178:181], v[122:125]
	v_mfma_f32_16x16x32_bf16 v[118:121], v[130:133], v[186:189], v[118:121]
	v_mfma_f32_16x16x32_bf16 v[110:113], v[138:141], v[186:189], v[110:113]
	v_mfma_f32_16x16x32_bf16 v[98:101], v[130:133], v[194:197], v[98:101]
	v_mfma_f32_16x16x32_bf16 v[90:93], v[138:141], v[194:197], v[90:93]
	v_mfma_f32_16x16x32_bf16 v[82:85], v[130:133], v[202:205], v[82:85]
	v_mfma_f32_16x16x32_bf16 v[74:77], v[138:141], v[202:205], v[74:77]
	v_mfma_f32_16x16x32_bf16 v[126:129], v[134:137], v[182:185], v[126:129]
	v_mfma_f32_16x16x32_bf16 v[122:125], v[142:145], v[182:185], v[122:125]
	v_mfma_f32_16x16x32_bf16 v[118:121], v[134:137], v[190:193], v[118:121]
	v_mfma_f32_16x16x32_bf16 v[110:113], v[142:145], v[190:193], v[110:113]
	v_mfma_f32_16x16x32_bf16 v[98:101], v[134:137], v[198:201], v[98:101]
	v_mfma_f32_16x16x32_bf16 v[90:93], v[142:145], v[198:201], v[90:93]
	v_mfma_f32_16x16x32_bf16 v[82:85], v[134:137], v[206:209], v[82:85]
	v_mfma_f32_16x16x32_bf16 v[74:77], v[142:145], v[206:209], v[74:77]
	s_setprio 0
	s_setprio 1
	v_mfma_f32_16x16x32_bf16 v[114:117], v[146:149], v[178:181], v[114:117]
	v_mfma_f32_16x16x32_bf16 v[106:109], v[166:169], v[178:181], v[106:109]
	v_mfma_f32_16x16x32_bf16 v[102:105], v[146:149], v[186:189], v[102:105]
	v_mfma_f32_16x16x32_bf16 v[94:97], v[166:169], v[186:189], v[94:97]
	v_mfma_f32_16x16x32_bf16 v[86:89], v[146:149], v[194:197], v[86:89]
	v_mfma_f32_16x16x32_bf16 v[78:81], v[166:169], v[194:197], v[78:81]
	v_mfma_f32_16x16x32_bf16 v[70:73], v[146:149], v[202:205], v[70:73]
	v_mfma_f32_16x16x32_bf16 v[66:69], v[166:169], v[202:205], v[66:69]
	v_mfma_f32_16x16x32_bf16 v[114:117], v[162:165], v[182:185], v[114:117]
	v_mfma_f32_16x16x32_bf16 v[106:109], v[174:177], v[182:185], v[106:109]
	v_mfma_f32_16x16x32_bf16 v[102:105], v[162:165], v[190:193], v[102:105]
	v_mfma_f32_16x16x32_bf16 v[94:97], v[174:177], v[190:193], v[94:97]
	v_mfma_f32_16x16x32_bf16 v[86:89], v[162:165], v[198:201], v[86:89]
	v_mfma_f32_16x16x32_bf16 v[78:81], v[174:177], v[198:201], v[78:81]
	v_mfma_f32_16x16x32_bf16 v[70:73], v[162:165], v[206:209], v[70:73]
	v_mfma_f32_16x16x32_bf16 v[66:69], v[174:177], v[206:209], v[66:69]
	s_setprio 0
	s_barrier
	s_add_i32 s52, s52, s28
	v_lshl_add_u64 v[210:211], s[16:17], 0, v[154:155]
	s_mov_b32 m0, s52
	ds_read_b128 v[178:181], v172 offset:16384
	ds_read_b128 v[182:185], v172 offset:17408
	ds_read_b128 v[186:189], v172 offset:18432
	ds_read_b128 v[190:193], v172 offset:19456
	ds_read_b128 v[194:197], v172 offset:20480
	ds_read_b128 v[198:201], v172 offset:21504
	ds_read_b128 v[202:205], v172 offset:22528
	ds_read_b128 v[206:209], v172 offset:23552
	global_load_lds_dwordx4 v[210:211], off
	s_add_i32 m0, s52, 0x2000
	s_add_u32 s52, s16, 0x20000
	v_lshl_add_u64 v[212:213], s[16:17], 0, v[150:151]
	s_addc_u32 s53, s17, 0
	s_add_i32 s61, s61, s28
	global_load_lds_dwordx4 v[212:213], off
	v_lshl_add_u64 v[214:215], s[52:53], 0, v[154:155]
	s_mov_b32 m0, s61
	v_lshl_add_u64 v[216:217], s[22:23], 0, v[152:153]
	global_load_lds_dwordx4 v[214:215], off
	v_lshl_add_u64 v[214:215], s[52:53], 0, v[150:151]
	s_add_i32 m0, s61, 0x2000
	s_nop 0
	global_load_lds_dwordx4 v[214:215], off
	v_lshl_add_u64 v[214:215], s[22:23], 0, v[156:157]
	s_mov_b32 m0, s29
	s_nop 0
	global_load_lds_dwordx4 v[214:215], off
	s_mov_b32 m0, s30
	s_nop 0
	global_load_lds_dwordx4 v[216:217], off
	s_waitcnt vmcnt(8)
	s_waitcnt lgkmcnt(0)
	s_barrier
	s_setprio 1
	s_waitcnt lgkmcnt(0)
	v_mfma_f32_16x16x32_bf16 v[62:65], v[130:133], v[178:181], v[62:65]
	v_mfma_f32_16x16x32_bf16 v[58:61], v[138:141], v[178:181], v[58:61]
	v_mfma_f32_16x16x32_bf16 v[50:53], v[130:133], v[186:189], v[50:53]
	v_mfma_f32_16x16x32_bf16 v[42:45], v[138:141], v[186:189], v[42:45]
	v_mfma_f32_16x16x32_bf16 v[34:37], v[130:133], v[194:197], v[34:37]
	v_mfma_f32_16x16x32_bf16 v[26:29], v[138:141], v[194:197], v[26:29]
	v_mfma_f32_16x16x32_bf16 v[18:21], v[130:133], v[202:205], v[18:21]
	v_mfma_f32_16x16x32_bf16 v[10:13], v[138:141], v[202:205], v[10:13]
	v_mfma_f32_16x16x32_bf16 v[62:65], v[134:137], v[182:185], v[62:65]
	v_mfma_f32_16x16x32_bf16 v[58:61], v[142:145], v[182:185], v[58:61]
	v_mfma_f32_16x16x32_bf16 v[50:53], v[134:137], v[190:193], v[50:53]
	v_mfma_f32_16x16x32_bf16 v[42:45], v[142:145], v[190:193], v[42:45]
	v_mfma_f32_16x16x32_bf16 v[34:37], v[134:137], v[198:201], v[34:37]
	v_mfma_f32_16x16x32_bf16 v[26:29], v[142:145], v[198:201], v[26:29]
	v_mfma_f32_16x16x32_bf16 v[18:21], v[134:137], v[206:209], v[18:21]
	v_mfma_f32_16x16x32_bf16 v[10:13], v[142:145], v[206:209], v[10:13]
	s_setprio 0
	s_setprio 1
	v_mfma_f32_16x16x32_bf16 v[54:57], v[146:149], v[178:181], v[54:57]
	v_mfma_f32_16x16x32_bf16 v[46:49], v[166:169], v[178:181], v[46:49]
	v_mfma_f32_16x16x32_bf16 v[38:41], v[146:149], v[186:189], v[38:41]
	v_mfma_f32_16x16x32_bf16 v[30:33], v[166:169], v[186:189], v[30:33]
	v_mfma_f32_16x16x32_bf16 v[22:25], v[146:149], v[194:197], v[22:25]
	v_mfma_f32_16x16x32_bf16 v[14:17], v[166:169], v[194:197], v[14:17]
	v_mfma_f32_16x16x32_bf16 v[6:9], v[146:149], v[202:205], v[6:9]
	v_mfma_f32_16x16x32_bf16 v[2:5], v[166:169], v[202:205], v[2:5]
	v_mfma_f32_16x16x32_bf16 v[54:57], v[162:165], v[182:185], v[54:57]
	v_mfma_f32_16x16x32_bf16 v[46:49], v[174:177], v[182:185], v[46:49]
	v_mfma_f32_16x16x32_bf16 v[38:41], v[162:165], v[190:193], v[38:41]
	v_mfma_f32_16x16x32_bf16 v[30:33], v[174:177], v[190:193], v[30:33]
	v_mfma_f32_16x16x32_bf16 v[22:25], v[162:165], v[198:201], v[22:25]
	v_mfma_f32_16x16x32_bf16 v[14:17], v[174:177], v[198:201], v[14:17]
	v_mfma_f32_16x16x32_bf16 v[6:9], v[162:165], v[206:209], v[6:9]
	v_mfma_f32_16x16x32_bf16 v[2:5], v[174:177], v[206:209], v[2:5]
	s_setprio 0
	s_barrier
; #define PG8_STAGE(bufoff, gbase, voff) do { _Pragma("unroll") for (int _i = 0; _i < 2; ++_i) \
;         __builtin_amdgcn_global_load_lds((const unsigned*)((const char*)(gbase) + (voff)[_i]), (PG8_LAS unsigned*)(lds + (bufoff) + ldsw + _i * 8192), 16, 0, 0); } while (0)
; #define PG8_LDA(dst, b, h) do { _Pragma("unroll") for (int m = 0; m < 4; ++m) _Pragma("unroll") for (int k = 0; k < 2; ++k) dst[m][k] = *(const PG8_LAS bf16x8*)(lds + PG8_SA(b, h) + aoff + m * 2048 + k * 1024); } while (0)
; #define PG8_LDB(dst, b, h) do { _Pragma("unroll") for (int n = 0; n < 2; ++n) _Pragma("unroll") for (int k = 0; k < 2; ++k) dst[n][k] = *(const PG8_LAS bf16x8*)(lds + PG8_SB(b, h) + boff + n * 2048 + k * 1024); } while (0)
; #define PG8_MMA(ai, bj, At, Bt) do { __builtin_amdgcn_s_setprio(1); _Pragma("unroll") for (int m = 0; m < 4; ++m) _Pragma("unroll") for (int n = 0; n < 2; ++n) _Pragma("unroll") for (int k = 0; k < 2; ++k) \
;         acc[ai][bj][m][n] = __builtin_amdgcn_mfma_f32_16x16x32_bf16(Bt[n][k], At[m][k], acc[ai][bj][m][n], 0, 0, 0); __builtin_amdgcn_s_setprio(0); } while (0)
; #define PG8_WAIT_V(n) asm volatile("s_waitcnt vmcnt(" #n ")" ::: "memory")
; #define PG8_WAIT_L(n) asm volatile("s_waitcnt lgkmcnt(" #n ")" ::: "memory")
; #define PG8_BAR __builtin_amdgcn_s_barrier()
; #define PG8_SCHED __builtin_amdgcn_sched_barrier(0)
; template <class Epi, class Sched, bool ALIGN_EPI = false, bool SP2 = false>
; __device__ __forceinline__ void gemm_phase(PG8_LAS unsigned char* lds, const Gemm g, const Sched& S, const Epi& E) {
;     ...
;             PG8_LDB(B0, 1, 0); PG8_LDB(B1, 1, 1); PG8_SCHED; PG8_LDA(At, 1, 0); PG8_STAGE(PG8_SA(0, 1), a2 + hstep, voffA);
;             PG8_WAIT_V(8); PG8_WAIT_L(0); PG8_BAR; PG8_MMA(0, 0, At, B0); PG8_MMA(0, 1, At, B1); PG8_BAR; PG8_SCHED;
	s_add_i32 s52, 0, 0x18000
	s_add_i32 s53, 0, 0x1c000
	v_add_u32_e32 v142, s52, v171
	v_add_u32_e32 v173, s53, v171
	ds_read_b128 v[130:133], v142
	ds_read_b128 v[134:137], v142 offset:1024
	ds_read_b128 v[138:141], v142 offset:2048
	ds_read_b128 v[142:145], v142 offset:3072
	ds_read_b128 v[146:149], v173
	ds_read_b128 v[162:165], v173 offset:1024
	ds_read_b128 v[166:169], v173 offset:2048
	ds_read_b128 v[174:177], v173 offset:3072
	s_add_u32 s22, s22, 0x20000
	s_addc_u32 s23, s23, 0
	s_mov_b32 m0, s31
	v_lshl_add_u64 v[218:219], s[22:23], 0, v[156:157]
	ds_read_b128 v[178:181], v172 offset:32768
	ds_read_b128 v[182:185], v172 offset:33792
	ds_read_b128 v[186:189], v172 offset:34816
	ds_read_b128 v[190:193], v172 offset:35840
	ds_read_b128 v[194:197], v172 offset:36864
	ds_read_b128 v[198:201], v172 offset:37888
	ds_read_b128 v[202:205], v172 offset:38912
	ds_read_b128 v[206:209], v172 offset:39936
	global_load_lds_dwordx4 v[218:219], off
	v_lshl_add_u64 v[218:219], s[22:23], 0, v[152:153]
	s_mov_b32 m0, s34
	s_nop 0
	global_load_lds_dwordx4 v[218:219], off
	s_waitcnt vmcnt(8)
	s_waitcnt lgkmcnt(0)
	s_barrier
	s_setprio 1
	s_waitcnt lgkmcnt(0)
	v_mfma_f32_16x16x32_bf16 v[126:129], v[130:133], v[178:181], v[126:129]
	v_mfma_f32_16x16x32_bf16 v[122:125], v[138:141], v[178:181], v[122:125]
	v_mfma_f32_16x16x32_bf16 v[118:121], v[130:133], v[186:189], v[118:121]
	v_mfma_f32_16x16x32_bf16 v[110:113], v[138:141], v[186:189], v[110:113]
	v_mfma_f32_16x16x32_bf16 v[98:101], v[130:133], v[194:197], v[98:101]
	v_mfma_f32_16x16x32_bf16 v[90:93], v[138:141], v[194:197], v[90:93]
	v_mfma_f32_16x16x32_bf16 v[82:85], v[130:133], v[202:205], v[82:85]
	v_mfma_f32_16x16x32_bf16 v[74:77], v[138:141], v[202:205], v[74:77]
	v_mfma_f32_16x16x32_bf16 v[126:129], v[134:137], v[182:185], v[126:129]
	v_mfma_f32_16x16x32_bf16 v[122:125], v[142:145], v[182:185], v[122:125]
	v_mfma_f32_16x16x32_bf16 v[118:121], v[134:137], v[190:193], v[118:121]
	v_mfma_f32_16x16x32_bf16 v[110:113], v[142:145], v[190:193], v[110:113]
	v_mfma_f32_16x16x32_bf16 v[98:101], v[134:137], v[198:201], v[98:101]
	v_mfma_f32_16x16x32_bf16 v[90:93], v[142:145], v[198:201], v[90:93]
	v_mfma_f32_16x16x32_bf16 v[82:85], v[134:137], v[206:209], v[82:85]
	v_mfma_f32_16x16x32_bf16 v[74:77], v[142:145], v[206:209], v[74:77]
	s_setprio 0
	s_setprio 1
	v_mfma_f32_16x16x32_bf16 v[114:117], v[146:149], v[178:181], v[114:117]
	v_mfma_f32_16x16x32_bf16 v[106:109], v[166:169], v[178:181], v[106:109]
	v_mfma_f32_16x16x32_bf16 v[102:105], v[146:149], v[186:189], v[102:105]
	v_mfma_f32_16x16x32_bf16 v[94:97], v[166:169], v[186:189], v[94:97]
	v_mfma_f32_16x16x32_bf16 v[86:89], v[146:149], v[194:197], v[86:89]
	v_mfma_f32_16x16x32_bf16 v[78:81], v[166:169], v[194:197], v[78:81]
	v_mfma_f32_16x16x32_bf16 v[70:73], v[146:149], v[202:205], v[70:73]
	v_mfma_f32_16x16x32_bf16 v[66:69], v[166:169], v[202:205], v[66:69]
	v_mfma_f32_16x16x32_bf16 v[114:117], v[162:165], v[182:185], v[114:117]
	v_mfma_f32_16x16x32_bf16 v[106:109], v[174:177], v[182:185], v[106:109]
	v_mfma_f32_16x16x32_bf16 v[102:105], v[162:165], v[190:193], v[102:105]
	v_mfma_f32_16x16x32_bf16 v[94:97], v[174:177], v[190:193], v[94:97]
	v_mfma_f32_16x16x32_bf16 v[86:89], v[162:165], v[198:201], v[86:89]
	v_mfma_f32_16x16x32_bf16 v[78:81], v[174:177], v[198:201], v[78:81]
	v_mfma_f32_16x16x32_bf16 v[70:73], v[162:165], v[206:209], v[70:73]
	v_mfma_f32_16x16x32_bf16 v[66:69], v[174:177], v[206:209], v[66:69]
	s_setprio 0
	s_barrier
; #define PG8_STAGE(bufoff, gbase, voff) do { _Pragma("unroll") for (int _i = 0; _i < 2; ++_i) \
;         __builtin_amdgcn_global_load_lds((const unsigned*)((const char*)(gbase) + (voff)[_i]), (PG8_LAS unsigned*)(lds + (bufoff) + ldsw + _i * 8192), 16, 0, 0); } while (0)
; #define PG8_LDA(dst, b, h) do { _Pragma("unroll") for (int m = 0; m < 4; ++m) _Pragma("unroll") for (int k = 0; k < 2; ++k) dst[m][k] = *(const PG8_LAS bf16x8*)(lds + PG8_SA(b, h) + aoff + m * 2048 + k * 1024); } while (0)
; #define PG8_MMA(ai, bj, At, Bt) do { __builtin_amdgcn_s_setprio(1); _Pragma("unroll") for (int m = 0; m < 4; ++m) _Pragma("unroll") for (int n = 0; n < 2; ++n) _Pragma("unroll") for (int k = 0; k < 2; ++k) \
;         acc[ai][bj][m][n] = __builtin_amdgcn_mfma_f32_16x16x32_bf16(Bt[n][k], At[m][k], acc[ai][bj][m][n], 0, 0, 0); __builtin_amdgcn_s_setprio(0); } while (0)
; #define PG8_WAIT_V(n) asm volatile("s_waitcnt vmcnt(" #n ")" ::: "memory")
; #define PG8_WAIT_L(n) asm volatile("s_waitcnt lgkmcnt(" #n ")" ::: "memory")
; #define PG8_BAR __builtin_amdgcn_s_barrier()
; #define PG8_SCHED __builtin_amdgcn_sched_barrier(0)
; template <class Epi, class Sched, bool ALIGN_EPI = false, bool SP2 = false>
; __device__ __forceinline__ void gemm_phase(PG8_LAS unsigned char* lds, const Gemm g, const Sched& S, const Epi& E) {
;     ...
;         for (int t = 0; t < nt; t += 2) {
;             const bool last = (t == nt - 2);
;     ...
;             PG8_LDA(At, 1, 1); PG8_STAGE(PG8_SB(1, 0), b3, voffB); PG8_STAGE(PG8_SB(1, 1), b3 + hstep, voffB); PG8_STAGE(PG8_SA(1, 0), a3, voffA);
;             PG8_WAIT_V(8); PG8_WAIT_L(0); PG8_BAR; PG8_MMA(1, 0, At, B0); PG8_MMA(1, 1, At, B1); PG8_BAR; PG8_SCHED;
;     ...
;         if constexpr (ALIGN_EPI) { if (wr == 0) PG8_BAR; }
	s_add_i32 s22, s52, s28
	v_lshl_add_u64 v[210:211], v[210:211], 0, s[94:95]
	s_mov_b32 m0, s22
	ds_read_b128 v[178:181], v172 offset:49152
	ds_read_b128 v[182:185], v172 offset:50176
	ds_read_b128 v[186:189], v172 offset:51200
	ds_read_b128 v[190:193], v172 offset:52224
	ds_read_b128 v[194:197], v172 offset:53248
	ds_read_b128 v[198:201], v172 offset:54272
	ds_read_b128 v[202:205], v172 offset:55296
	ds_read_b128 v[206:209], v172 offset:56320
	global_load_lds_dwordx4 v[210:211], off
	s_add_i32 m0, s22, 0x2000
	s_add_u32 s16, s16, 0x20080
	v_lshl_add_u64 v[210:211], v[212:213], 0, s[94:95]
	s_addc_u32 s17, s17, 0
	s_add_i32 s22, s53, s28
	global_load_lds_dwordx4 v[210:211], off
	v_lshl_add_u64 v[210:211], s[16:17], 0, v[154:155]
	s_mov_b32 m0, s22
	s_nop 0
	global_load_lds_dwordx4 v[210:211], off
	v_lshl_add_u64 v[210:211], s[16:17], 0, v[150:151]
	s_add_i32 m0, s22, 0x2000
	s_nop 0
	global_load_lds_dwordx4 v[210:211], off
	v_lshl_add_u64 v[210:211], v[214:215], 0, s[94:95]
	s_mov_b32 m0, s33
	s_nop 0
	global_load_lds_dwordx4 v[210:211], off
	v_lshl_add_u64 v[210:211], v[216:217], 0, s[94:95]
	s_mov_b32 m0, s37
	s_nop 0
	global_load_lds_dwordx4 v[210:211], off
	s_waitcnt vmcnt(8)
	s_waitcnt lgkmcnt(0)
	s_barrier
	s_setprio 1
	s_waitcnt lgkmcnt(0)
	v_mfma_f32_16x16x32_bf16 v[62:65], v[130:133], v[178:181], v[62:65]
	v_mfma_f32_16x16x32_bf16 v[58:61], v[138:141], v[178:181], v[58:61]
	v_mfma_f32_16x16x32_bf16 v[50:53], v[130:133], v[186:189], v[50:53]
	v_mfma_f32_16x16x32_bf16 v[42:45], v[138:141], v[186:189], v[42:45]
	v_mfma_f32_16x16x32_bf16 v[34:37], v[130:133], v[194:197], v[34:37]
	v_mfma_f32_16x16x32_bf16 v[26:29], v[138:141], v[194:197], v[26:29]
	v_mfma_f32_16x16x32_bf16 v[18:21], v[130:133], v[202:205], v[18:21]
	v_mfma_f32_16x16x32_bf16 v[10:13], v[138:141], v[202:205], v[10:13]
	v_mfma_f32_16x16x32_bf16 v[62:65], v[134:137], v[182:185], v[62:65]
	v_mfma_f32_16x16x32_bf16 v[58:61], v[142:145], v[182:185], v[58:61]
	v_mfma_f32_16x16x32_bf16 v[50:53], v[134:137], v[190:193], v[50:53]
	v_mfma_f32_16x16x32_bf16 v[42:45], v[142:145], v[190:193], v[42:45]
	v_mfma_f32_16x16x32_bf16 v[34:37], v[134:137], v[198:201], v[34:37]
	v_mfma_f32_16x16x32_bf16 v[26:29], v[142:145], v[198:201], v[26:29]
	v_mfma_f32_16x16x32_bf16 v[18:21], v[134:137], v[206:209], v[18:21]
	v_mfma_f32_16x16x32_bf16 v[10:13], v[142:145], v[206:209], v[10:13]
	s_setprio 0
	s_setprio 1
	v_mfma_f32_16x16x32_bf16 v[54:57], v[146:149], v[178:181], v[54:57]
	v_mfma_f32_16x16x32_bf16 v[46:49], v[166:169], v[178:181], v[46:49]
	v_mfma_f32_16x16x32_bf16 v[38:41], v[146:149], v[186:189], v[38:41]
	v_mfma_f32_16x16x32_bf16 v[30:33], v[166:169], v[186:189], v[30:33]
	v_mfma_f32_16x16x32_bf16 v[22:25], v[146:149], v[194:197], v[22:25]
	v_mfma_f32_16x16x32_bf16 v[14:17], v[166:169], v[194:197], v[14:17]
	v_mfma_f32_16x16x32_bf16 v[6:9], v[146:149], v[202:205], v[6:9]
	v_mfma_f32_16x16x32_bf16 v[2:5], v[166:169], v[202:205], v[2:5]
	v_mfma_f32_16x16x32_bf16 v[54:57], v[162:165], v[182:185], v[54:57]
	v_mfma_f32_16x16x32_bf16 v[46:49], v[174:177], v[182:185], v[46:49]
	v_mfma_f32_16x16x32_bf16 v[38:41], v[162:165], v[190:193], v[38:41]
	v_mfma_f32_16x16x32_bf16 v[30:33], v[174:177], v[190:193], v[30:33]
	v_mfma_f32_16x16x32_bf16 v[22:25], v[162:165], v[198:201], v[22:25]
	v_mfma_f32_16x16x32_bf16 v[14:17], v[174:177], v[198:201], v[14:17]
	v_mfma_f32_16x16x32_bf16 v[6:9], v[162:165], v[206:209], v[6:9]
	v_mfma_f32_16x16x32_bf16 v[2:5], v[174:177], v[206:209], v[2:5]
	s_add_i32 s50, s50, 2
	s_add_u32 s20, s20, 0x100
	s_addc_u32 s21, s21, 0
	s_add_u32 s57, s57, 0x100
	s_addc_u32 s60, s60, 0
	s_add_u32 s16, s20, 0xfffe0080
	s_addc_u32 s17, s21, -1
	s_add_i32 s52, 0, 0x10000
	s_cmp_eq_u32 s50, 4
	s_cselect_b32 s23, s13, s17
	s_cselect_b32 s22, s55, s16
	s_cselect_b32 s17, s11, s60
	s_cselect_b32 s16, s56, s57
	s_add_i32 s61, 0, 0x14000
	s_cmp_gt_u32 s50, 5
	s_setprio 0
	s_barrier
	s_cbranch_scc0 .LBB0_567
	s_and_b64 vcc, exec, s[8:9]
	s_cbranch_vccz .LBB0_570
	s_barrier

; #define PG8_STAGE(bufoff, gbase, voff) do { _Pragma("unroll") for (int _i = 0; _i < 2; ++_i) \
;         __builtin_amdgcn_global_load_lds((const unsigned*)((const char*)(gbase) + (voff)[_i]), (PG8_LAS unsigned*)(lds + (bufoff) + ldsw + _i * 8192), 16, 0, 0); } while (0)
; #define PG8_LDA(dst, b, h) do { _Pragma("unroll") for (int m = 0; m < 4; ++m) _Pragma("unroll") for (int k = 0; k < 2; ++k) dst[m][k] = *(const PG8_LAS bf16x8*)(lds + PG8_SA(b, h) + aoff + m * 2048 + k * 1024); } while (0)
; #define PG8_LDB(dst, b, h) do { _Pragma("unroll") for (int n = 0; n < 2; ++n) _Pragma("unroll") for (int k = 0; k < 2; ++k) dst[n][k] = *(const PG8_LAS bf16x8*)(lds + PG8_SB(b, h) + boff + n * 2048 + k * 1024); } while (0)
; #define PG8_MMA(ai, bj, At, Bt) do { __builtin_amdgcn_s_setprio(1); _Pragma("unroll") for (int m = 0; m < 4; ++m) _Pragma("unroll") for (int n = 0; n < 2; ++n) _Pragma("unroll") for (int k = 0; k < 2; ++k) \
;         acc[ai][bj][m][n] = __builtin_amdgcn_mfma_f32_16x16x32_bf16(Bt[n][k], At[m][k], acc[ai][bj][m][n], 0, 0, 0); __builtin_amdgcn_s_setprio(0); } while (0)
; #define PG8_WAIT_V(n) asm volatile("s_waitcnt vmcnt(" #n ")" ::: "memory")
; #define PG8_BAR __builtin_amdgcn_s_barrier()
; template <class Epi, class Sched, bool ALIGN_EPI = false, bool SP2 = false>
; __device__ __forceinline__ void gemm_phase(PG8_LAS unsigned char* lds, const Gemm g, const Sched& S, const Epi& E) {
;     ...
;         for (int t = 0; t < nt; t += 2) {
;             const bool last = (t == nt - 2);
;             const char* a1 = cA + (size_t)(t + 1) * kstep;
;             const char* a2 = last ? nA : cA + (size_t)(t + 2) * kstep; const char* b2 = last ? nB : cB + (size_t)(t + 2) * kstep;
;             const char* a3 = a2 + kstep; const char* b3 = b2 + kstep;
;             if (last && has_next) S.a_ready(nxt);
;             if constexpr (SP2) {
;             PG8_LDB(B0, 0, 0); PG8_LDB(B1, 0, 1); PG8_SCHED; PG8_LDA(At, 0, 0); PG8_STAGE(PG8_SA(1, 1), a1 + hstep, voffA);
;             PG8_WAIT_V(8); PG8_WAIT_L(0); PG8_BAR; PG8_MMA(0, 0, At, B0); PG8_MMA(0, 1, At, B1); PG8_BAR; PG8_SCHED;
;             PG8_LDA(At, 0, 1); PG8_STAGE(PG8_SB(0, 0), b2, voffB); PG8_STAGE(PG8_SB(0, 1), b2 + hstep, voffB); PG8_STAGE(PG8_SA(0, 0), a2, voffA);
;             PG8_WAIT_V(8); PG8_WAIT_L(0); PG8_BAR; PG8_MMA(1, 0, At, B0); PG8_MMA(1, 1, At, B1); PG8_BAR; PG8_SCHED;
.LBB0_632:
	v_add_u32_e32 v0, s52, v205
	ds_read_b128 v[130:133], v0
	ds_read_b128 v[134:137], v0 offset:1024
	ds_read_b128 v[138:141], v0 offset:2048
	ds_read_b128 v[142:145], v0 offset:3072
	v_add_u32_e32 v0, s61, v205
	ds_read_b128 v[146:149], v0
	ds_read_b128 v[150:153], v0 offset:1024
	ds_read_b128 v[154:157], v0 offset:2048
	ds_read_b128 v[158:161], v0 offset:3072
	v_lshl_add_u64 v[210:211], s[22:23], 0, v[206:207]
	s_add_i32 m0, s31, 0xc000
	ds_read_b128 v[162:165], v226
	ds_read_b128 v[166:169], v226 offset:1024
	ds_read_b128 v[170:173], v226 offset:2048
	ds_read_b128 v[174:177], v226 offset:3072
	ds_read_b128 v[178:181], v226 offset:4096
	ds_read_b128 v[182:185], v226 offset:5120
	ds_read_b128 v[186:189], v226 offset:6144
	ds_read_b128 v[190:193], v226 offset:7168
	global_load_lds_dwordx4 v[210:211], off
	v_lshl_add_u64 v[210:211], s[22:23], 0, v[208:209]
	s_add_i32 m0, s31, 0xe000
	s_nop 0
	global_load_lds_dwordx4 v[210:211], off
	s_waitcnt vmcnt(8)
	s_waitcnt lgkmcnt(0)
	s_barrier
	s_setprio 1
	s_waitcnt lgkmcnt(0)
	v_mfma_f32_16x16x32_bf16 v[126:129], v[130:133], v[162:165], v[126:129]
	v_mfma_f32_16x16x32_bf16 v[122:125], v[138:141], v[162:165], v[122:125]
	v_mfma_f32_16x16x32_bf16 v[110:113], v[130:133], v[170:173], v[110:113]
	v_mfma_f32_16x16x32_bf16 v[106:109], v[138:141], v[170:173], v[106:109]
	v_mfma_f32_16x16x32_bf16 v[94:97], v[130:133], v[178:181], v[94:97]
	v_mfma_f32_16x16x32_bf16 v[90:93], v[138:141], v[178:181], v[90:93]
	v_mfma_f32_16x16x32_bf16 v[78:81], v[130:133], v[186:189], v[78:81]
	v_mfma_f32_16x16x32_bf16 v[74:77], v[138:141], v[186:189], v[74:77]
	v_mfma_f32_16x16x32_bf16 v[126:129], v[134:137], v[166:169], v[126:129]
	v_mfma_f32_16x16x32_bf16 v[122:125], v[142:145], v[166:169], v[122:125]
	v_mfma_f32_16x16x32_bf16 v[110:113], v[134:137], v[174:177], v[110:113]
	v_mfma_f32_16x16x32_bf16 v[106:109], v[142:145], v[174:177], v[106:109]
	v_mfma_f32_16x16x32_bf16 v[94:97], v[134:137], v[182:185], v[94:97]
	v_mfma_f32_16x16x32_bf16 v[90:93], v[142:145], v[182:185], v[90:93]
	v_mfma_f32_16x16x32_bf16 v[78:81], v[134:137], v[190:193], v[78:81]
	v_mfma_f32_16x16x32_bf16 v[74:77], v[142:145], v[190:193], v[74:77]
	s_setprio 0
	s_setprio 1
	v_mfma_f32_16x16x32_bf16 v[118:121], v[146:149], v[162:165], v[118:121]
	v_mfma_f32_16x16x32_bf16 v[114:117], v[154:157], v[162:165], v[114:117]
	v_mfma_f32_16x16x32_bf16 v[102:105], v[146:149], v[170:173], v[102:105]
	v_mfma_f32_16x16x32_bf16 v[98:101], v[154:157], v[170:173], v[98:101]
	v_mfma_f32_16x16x32_bf16 v[86:89], v[146:149], v[178:181], v[86:89]
	v_mfma_f32_16x16x32_bf16 v[82:85], v[154:157], v[178:181], v[82:85]
	v_mfma_f32_16x16x32_bf16 v[70:73], v[146:149], v[186:189], v[70:73]
	v_mfma_f32_16x16x32_bf16 v[66:69], v[154:157], v[186:189], v[66:69]
	v_mfma_f32_16x16x32_bf16 v[118:121], v[150:153], v[166:169], v[118:121]
	v_mfma_f32_16x16x32_bf16 v[114:117], v[158:161], v[166:169], v[114:117]
	v_mfma_f32_16x16x32_bf16 v[102:105], v[150:153], v[174:177], v[102:105]
	v_mfma_f32_16x16x32_bf16 v[98:101], v[158:161], v[174:177], v[98:101]
	v_mfma_f32_16x16x32_bf16 v[86:89], v[150:153], v[182:185], v[86:89]
	v_mfma_f32_16x16x32_bf16 v[82:85], v[158:161], v[182:185], v[82:85]
	v_mfma_f32_16x16x32_bf16 v[70:73], v[150:153], v[190:193], v[70:73]
	v_mfma_f32_16x16x32_bf16 v[66:69], v[158:161], v[190:193], v[66:69]
	s_setprio 0
	s_barrier
	s_add_i32 s52, s52, s30
	v_lshl_add_u64 v[210:211], s[16:17], 0, v[198:199]
	s_mov_b32 m0, s52
	ds_read_b128 v[162:165], v226 offset:16384
	ds_read_b128 v[166:169], v226 offset:17408
	ds_read_b128 v[170:173], v226 offset:18432
	ds_read_b128 v[174:177], v226 offset:19456
	ds_read_b128 v[178:181], v226 offset:20480
	ds_read_b128 v[182:185], v226 offset:21504
	ds_read_b128 v[186:189], v226 offset:22528
	ds_read_b128 v[190:193], v226 offset:23552
	global_load_lds_dwordx4 v[210:211], off
	s_add_i32 m0, s52, 0x2000
	s_add_u32 s52, s16, 0x20000
	v_lshl_add_u64 v[212:213], s[16:17], 0, v[194:195]
	s_addc_u32 s53, s17, 0
	s_add_i32 s61, s61, s30
	global_load_lds_dwordx4 v[212:213], off
	v_lshl_add_u64 v[214:215], s[52:53], 0, v[198:199]
	s_mov_b32 m0, s61
	v_lshl_add_u64 v[216:217], s[24:25], 0, v[196:197]
	global_load_lds_dwordx4 v[214:215], off
	v_lshl_add_u64 v[214:215], s[52:53], 0, v[194:195]
	s_add_i32 m0, s61, 0x2000
	s_nop 0
	global_load_lds_dwordx4 v[214:215], off
	v_lshl_add_u64 v[214:215], s[24:25], 0, v[200:201]
	s_mov_b32 m0, s31
	s_nop 0
	global_load_lds_dwordx4 v[214:215], off
	s_mov_b32 m0, s34
	s_nop 0
	global_load_lds_dwordx4 v[216:217], off
	s_waitcnt vmcnt(8)
	s_waitcnt lgkmcnt(0)
	s_barrier
; #define PG8_STAGE(bufoff, gbase, voff) do { _Pragma("unroll") for (int _i = 0; _i < 2; ++_i) \
;         __builtin_amdgcn_global_load_lds((const unsigned*)((const char*)(gbase) + (voff)[_i]), (PG8_LAS unsigned*)(lds + (bufoff) + ldsw + _i * 8192), 16, 0, 0); } while (0)
; #define PG8_LDA(dst, b, h) do { _Pragma("unroll") for (int m = 0; m < 4; ++m) _Pragma("unroll") for (int k = 0; k < 2; ++k) dst[m][k] = *(const PG8_LAS bf16x8*)(lds + PG8_SA(b, h) + aoff + m * 2048 + k * 1024); } while (0)
; #define PG8_LDB(dst, b, h) do { _Pragma("unroll") for (int n = 0; n < 2; ++n) _Pragma("unroll") for (int k = 0; k < 2; ++k) dst[n][k] = *(const PG8_LAS bf16x8*)(lds + PG8_SB(b, h) + boff + n * 2048 + k * 1024); } while (0)
; #define PG8_MMA(ai, bj, At, Bt) do { __builtin_amdgcn_s_setprio(1); _Pragma("unroll") for (int m = 0; m < 4; ++m) _Pragma("unroll") for (int n = 0; n < 2; ++n) _Pragma("unroll") for (int k = 0; k < 2; ++k) \
;         acc[ai][bj][m][n] = __builtin_amdgcn_mfma_f32_16x16x32_bf16(Bt[n][k], At[m][k], acc[ai][bj][m][n], 0, 0, 0); __builtin_amdgcn_s_setprio(0); } while (0)
; #define PG8_WAIT_V(n) asm volatile("s_waitcnt vmcnt(" #n ")" ::: "memory")
; #define PG8_WAIT_L(n) asm volatile("s_waitcnt lgkmcnt(" #n ")" ::: "memory")
; #define PG8_BAR __builtin_amdgcn_s_barrier()
; #define PG8_SCHED __builtin_amdgcn_sched_barrier(0)
; template <class Epi, class Sched, bool ALIGN_EPI = false, bool SP2 = false>
; __device__ __forceinline__ void gemm_phase(PG8_LAS unsigned char* lds, const Gemm g, const Sched& S, const Epi& E) {
;     ...
;             PG8_WAIT_V(8); PG8_WAIT_L(0); PG8_BAR; PG8_MMA(1, 0, At, B0); PG8_MMA(1, 1, At, B1); PG8_BAR; PG8_SCHED;
;             PG8_LDB(B0, 1, 0); PG8_LDB(B1, 1, 1); PG8_SCHED; PG8_LDA(At, 1, 0); PG8_STAGE(PG8_SA(0, 1), a2 + hstep, voffA);
;             PG8_WAIT_V(8); PG8_WAIT_L(0); PG8_BAR; PG8_MMA(0, 0, At, B0); PG8_MMA(0, 1, At, B1); PG8_BAR; PG8_SCHED;
	s_setprio 1
	s_waitcnt lgkmcnt(0)
	v_mfma_f32_16x16x32_bf16 v[62:65], v[130:133], v[162:165], v[62:65]
	v_mfma_f32_16x16x32_bf16 v[58:61], v[138:141], v[162:165], v[58:61]
	v_mfma_f32_16x16x32_bf16 v[46:49], v[130:133], v[170:173], v[46:49]
	v_mfma_f32_16x16x32_bf16 v[42:45], v[138:141], v[170:173], v[42:45]
	v_mfma_f32_16x16x32_bf16 v[30:33], v[130:133], v[178:181], v[30:33]
	v_mfma_f32_16x16x32_bf16 v[26:29], v[138:141], v[178:181], v[26:29]
	v_mfma_f32_16x16x32_bf16 v[14:17], v[130:133], v[186:189], v[14:17]
	v_mfma_f32_16x16x32_bf16 v[10:13], v[138:141], v[186:189], v[10:13]
	v_mfma_f32_16x16x32_bf16 v[62:65], v[134:137], v[166:169], v[62:65]
	v_mfma_f32_16x16x32_bf16 v[58:61], v[142:145], v[166:169], v[58:61]
	v_mfma_f32_16x16x32_bf16 v[46:49], v[134:137], v[174:177], v[46:49]
	v_mfma_f32_16x16x32_bf16 v[42:45], v[142:145], v[174:177], v[42:45]
	v_mfma_f32_16x16x32_bf16 v[30:33], v[134:137], v[182:185], v[30:33]
	v_mfma_f32_16x16x32_bf16 v[26:29], v[142:145], v[182:185], v[26:29]
	v_mfma_f32_16x16x32_bf16 v[14:17], v[134:137], v[190:193], v[14:17]
	v_mfma_f32_16x16x32_bf16 v[10:13], v[142:145], v[190:193], v[10:13]
	s_setprio 0
	s_setprio 1
	v_mfma_f32_16x16x32_bf16 v[54:57], v[146:149], v[162:165], v[54:57]
	v_mfma_f32_16x16x32_bf16 v[50:53], v[154:157], v[162:165], v[50:53]
	v_mfma_f32_16x16x32_bf16 v[38:41], v[146:149], v[170:173], v[38:41]
	v_mfma_f32_16x16x32_bf16 v[34:37], v[154:157], v[170:173], v[34:37]
	v_mfma_f32_16x16x32_bf16 v[22:25], v[146:149], v[178:181], v[22:25]
	v_mfma_f32_16x16x32_bf16 v[18:21], v[154:157], v[178:181], v[18:21]
	v_mfma_f32_16x16x32_bf16 v[6:9], v[146:149], v[186:189], v[6:9]
	v_mfma_f32_16x16x32_bf16 v[2:5], v[154:157], v[186:189], v[2:5]
	v_mfma_f32_16x16x32_bf16 v[54:57], v[150:153], v[166:169], v[54:57]
	v_mfma_f32_16x16x32_bf16 v[50:53], v[158:161], v[166:169], v[50:53]
	v_mfma_f32_16x16x32_bf16 v[38:41], v[150:153], v[174:177], v[38:41]
	v_mfma_f32_16x16x32_bf16 v[34:37], v[158:161], v[174:177], v[34:37]
	v_mfma_f32_16x16x32_bf16 v[22:25], v[150:153], v[182:185], v[22:25]
	v_mfma_f32_16x16x32_bf16 v[18:21], v[158:161], v[182:185], v[18:21]
	v_mfma_f32_16x16x32_bf16 v[6:9], v[150:153], v[190:193], v[6:9]
	v_mfma_f32_16x16x32_bf16 v[2:5], v[158:161], v[190:193], v[2:5]
	s_setprio 0
	s_barrier
	s_add_i32 s52, 0, 0x18000
	v_add_u32_e32 v0, s52, v205
	s_add_i32 s53, 0, 0x1c000
	ds_read_b128 v[130:133], v0
	ds_read_b128 v[134:137], v0 offset:1024
	ds_read_b128 v[138:141], v0 offset:2048
	ds_read_b128 v[142:145], v0 offset:3072
	v_add_u32_e32 v0, s53, v205
	ds_read_b128 v[146:149], v0
	ds_read_b128 v[150:153], v0 offset:1024
	ds_read_b128 v[154:157], v0 offset:2048
	ds_read_b128 v[158:161], v0 offset:3072
	s_add_u32 s24, s24, 0x20000
	s_addc_u32 s25, s25, 0
	s_mov_b32 m0, s35
	v_lshl_add_u64 v[218:219], s[24:25], 0, v[200:201]
	ds_read_b128 v[162:165], v226 offset:32768
	ds_read_b128 v[166:169], v226 offset:33792
	ds_read_b128 v[170:173], v226 offset:34816
	ds_read_b128 v[174:177], v226 offset:35840
	ds_read_b128 v[178:181], v226 offset:36864
	ds_read_b128 v[182:185], v226 offset:37888
	ds_read_b128 v[186:189], v226 offset:38912
	ds_read_b128 v[190:193], v226 offset:39936
	global_load_lds_dwordx4 v[218:219], off
	v_lshl_add_u64 v[218:219], s[24:25], 0, v[196:197]
	s_mov_b32 m0, s36
	s_nop 0
	global_load_lds_dwordx4 v[218:219], off
	s_waitcnt vmcnt(8)
	s_waitcnt lgkmcnt(0)
	s_barrier
	s_setprio 1
	s_waitcnt lgkmcnt(0)
	v_mfma_f32_16x16x32_bf16 v[126:129], v[130:133], v[162:165], v[126:129]
	v_mfma_f32_16x16x32_bf16 v[122:125], v[138:141], v[162:165], v[122:125]
	v_mfma_f32_16x16x32_bf16 v[110:113], v[130:133], v[170:173], v[110:113]
	v_mfma_f32_16x16x32_bf16 v[106:109], v[138:141], v[170:173], v[106:109]
	v_mfma_f32_16x16x32_bf16 v[94:97], v[130:133], v[178:181], v[94:97]
	v_mfma_f32_16x16x32_bf16 v[90:93], v[138:141], v[178:181], v[90:93]
	v_mfma_f32_16x16x32_bf16 v[78:81], v[130:133], v[186:189], v[78:81]
	v_mfma_f32_16x16x32_bf16 v[74:77], v[138:141], v[186:189], v[74:77]
	v_mfma_f32_16x16x32_bf16 v[126:129], v[134:137], v[166:169], v[126:129]
	v_mfma_f32_16x16x32_bf16 v[122:125], v[142:145], v[166:169], v[122:125]
	v_mfma_f32_16x16x32_bf16 v[110:113], v[134:137], v[174:177], v[110:113]
	v_mfma_f32_16x16x32_bf16 v[106:109], v[142:145], v[174:177], v[106:109]
	v_mfma_f32_16x16x32_bf16 v[94:97], v[134:137], v[182:185], v[94:97]
	v_mfma_f32_16x16x32_bf16 v[90:93], v[142:145], v[182:185], v[90:93]
	v_mfma_f32_16x16x32_bf16 v[78:81], v[134:137], v[190:193], v[78:81]
	v_mfma_f32_16x16x32_bf16 v[74:77], v[142:145], v[190:193], v[74:77]
	s_setprio 0
	s_setprio 1
	v_mfma_f32_16x16x32_bf16 v[118:121], v[146:149], v[162:165], v[118:121]
	v_mfma_f32_16x16x32_bf16 v[114:117], v[154:157], v[162:165], v[114:117]
	v_mfma_f32_16x16x32_bf16 v[102:105], v[146:149], v[170:173], v[102:105]
	v_mfma_f32_16x16x32_bf16 v[98:101], v[154:157], v[170:173], v[98:101]
	v_mfma_f32_16x16x32_bf16 v[86:89], v[146:149], v[178:181], v[86:89]
	v_mfma_f32_16x16x32_bf16 v[82:85], v[154:157], v[178:181], v[82:85]
	v_mfma_f32_16x16x32_bf16 v[70:73], v[146:149], v[186:189], v[70:73]
	v_mfma_f32_16x16x32_bf16 v[66:69], v[154:157], v[186:189], v[66:69]
	v_mfma_f32_16x16x32_bf16 v[118:121], v[150:153], v[166:169], v[118:121]
	v_mfma_f32_16x16x32_bf16 v[114:117], v[158:161], v[166:169], v[114:117]
	v_mfma_f32_16x16x32_bf16 v[102:105], v[150:153], v[174:177], v[102:105]
	v_mfma_f32_16x16x32_bf16 v[98:101], v[158:161], v[174:177], v[98:101]
	v_mfma_f32_16x16x32_bf16 v[86:89], v[150:153], v[182:185], v[86:89]
	v_mfma_f32_16x16x32_bf16 v[82:85], v[158:161], v[182:185], v[82:85]
	v_mfma_f32_16x16x32_bf16 v[70:73], v[150:153], v[190:193], v[70:73]
	v_mfma_f32_16x16x32_bf16 v[66:69], v[158:161], v[190:193], v[66:69]
	s_setprio 0
	s_barrier
; #define PG8_STAGE(bufoff, gbase, voff) do { _Pragma("unroll") for (int _i = 0; _i < 2; ++_i) \
;         __builtin_amdgcn_global_load_lds((const unsigned*)((const char*)(gbase) + (voff)[_i]), (PG8_LAS unsigned*)(lds + (bufoff) + ldsw + _i * 8192), 16, 0, 0); } while (0)
; #define PG8_LDA(dst, b, h) do { _Pragma("unroll") for (int m = 0; m < 4; ++m) _Pragma("unroll") for (int k = 0; k < 2; ++k) dst[m][k] = *(const PG8_LAS bf16x8*)(lds + PG8_SA(b, h) + aoff + m * 2048 + k * 1024); } while (0)
; #define PG8_MMA(ai, bj, At, Bt) do { __builtin_amdgcn_s_setprio(1); _Pragma("unroll") for (int m = 0; m < 4; ++m) _Pragma("unroll") for (int n = 0; n < 2; ++n) _Pragma("unroll") for (int k = 0; k < 2; ++k) \
;         acc[ai][bj][m][n] = __builtin_amdgcn_mfma_f32_16x16x32_bf16(Bt[n][k], At[m][k], acc[ai][bj][m][n], 0, 0, 0); __builtin_amdgcn_s_setprio(0); } while (0)
; #define PG8_WAIT_V(n) asm volatile("s_waitcnt vmcnt(" #n ")" ::: "memory")
; #define PG8_WAIT_L(n) asm volatile("s_waitcnt lgkmcnt(" #n ")" ::: "memory")
; #define PG8_BAR __builtin_amdgcn_s_barrier()
; #define PG8_SCHED __builtin_amdgcn_sched_barrier(0)
; template <class Epi, class Sched, bool ALIGN_EPI = false, bool SP2 = false>
; __device__ __forceinline__ void gemm_phase(PG8_LAS unsigned char* lds, const Gemm g, const Sched& S, const Epi& E) {
;     ...
;         for (int t = 0; t < nt; t += 2) {
;             const bool last = (t == nt - 2);
;     ...
;             PG8_LDA(At, 1, 1); PG8_STAGE(PG8_SB(1, 0), b3, voffB); PG8_STAGE(PG8_SB(1, 1), b3 + hstep, voffB); PG8_STAGE(PG8_SA(1, 0), a3, voffA);
;             PG8_WAIT_V(8); PG8_WAIT_L(0); PG8_BAR; PG8_MMA(1, 0, At, B0); PG8_MMA(1, 1, At, B1); PG8_BAR; PG8_SCHED;
;     ...
;         if constexpr (ALIGN_EPI) { if (wr == 0) PG8_BAR; }
	s_add_i32 s24, s52, s30
	v_lshl_add_u64 v[210:211], v[210:211], 0, s[94:95]
	s_mov_b32 m0, s24
	ds_read_b128 v[162:165], v226 offset:49152
	ds_read_b128 v[166:169], v226 offset:50176
	ds_read_b128 v[170:173], v226 offset:51200
	ds_read_b128 v[174:177], v226 offset:52224
	ds_read_b128 v[178:181], v226 offset:53248
	ds_read_b128 v[182:185], v226 offset:54272
	ds_read_b128 v[186:189], v226 offset:55296
	ds_read_b128 v[190:193], v226 offset:56320
	global_load_lds_dwordx4 v[210:211], off
	s_add_i32 m0, s24, 0x2000
	s_add_u32 s16, s16, 0x20080
	v_lshl_add_u64 v[210:211], v[212:213], 0, s[94:95]
	s_addc_u32 s17, s17, 0
	s_add_i32 s24, s53, s30
	global_load_lds_dwordx4 v[210:211], off
	v_lshl_add_u64 v[210:211], s[16:17], 0, v[198:199]
	s_mov_b32 m0, s24
	s_nop 0
	global_load_lds_dwordx4 v[210:211], off
	v_lshl_add_u64 v[210:211], s[16:17], 0, v[194:195]
	s_add_i32 m0, s24, 0x2000
	s_nop 0
	global_load_lds_dwordx4 v[210:211], off
	v_lshl_add_u64 v[210:211], v[214:215], 0, s[94:95]
	s_mov_b32 m0, s37
	s_nop 0
	global_load_lds_dwordx4 v[210:211], off
	v_lshl_add_u64 v[210:211], v[216:217], 0, s[94:95]
	s_mov_b32 m0, s38
	s_nop 0
	global_load_lds_dwordx4 v[210:211], off
	s_waitcnt vmcnt(8)
	s_waitcnt lgkmcnt(0)
	s_barrier
	s_setprio 1
	s_waitcnt lgkmcnt(0)
	v_mfma_f32_16x16x32_bf16 v[62:65], v[130:133], v[162:165], v[62:65]
	v_mfma_f32_16x16x32_bf16 v[58:61], v[138:141], v[162:165], v[58:61]
	v_mfma_f32_16x16x32_bf16 v[46:49], v[130:133], v[170:173], v[46:49]
	v_mfma_f32_16x16x32_bf16 v[42:45], v[138:141], v[170:173], v[42:45]
	v_mfma_f32_16x16x32_bf16 v[30:33], v[130:133], v[178:181], v[30:33]
	v_mfma_f32_16x16x32_bf16 v[26:29], v[138:141], v[178:181], v[26:29]
	v_mfma_f32_16x16x32_bf16 v[14:17], v[130:133], v[186:189], v[14:17]
	v_mfma_f32_16x16x32_bf16 v[10:13], v[138:141], v[186:189], v[10:13]
	v_mfma_f32_16x16x32_bf16 v[62:65], v[134:137], v[166:169], v[62:65]
	v_mfma_f32_16x16x32_bf16 v[58:61], v[142:145], v[166:169], v[58:61]
	v_mfma_f32_16x16x32_bf16 v[46:49], v[134:137], v[174:177], v[46:49]
	v_mfma_f32_16x16x32_bf16 v[42:45], v[142:145], v[174:177], v[42:45]
	v_mfma_f32_16x16x32_bf16 v[30:33], v[134:137], v[182:185], v[30:33]
	v_mfma_f32_16x16x32_bf16 v[26:29], v[142:145], v[182:185], v[26:29]
	v_mfma_f32_16x16x32_bf16 v[14:17], v[134:137], v[190:193], v[14:17]
	v_mfma_f32_16x16x32_bf16 v[10:13], v[142:145], v[190:193], v[10:13]
	s_setprio 0
	s_setprio 1
	v_mfma_f32_16x16x32_bf16 v[54:57], v[146:149], v[162:165], v[54:57]
	v_mfma_f32_16x16x32_bf16 v[50:53], v[154:157], v[162:165], v[50:53]
	v_mfma_f32_16x16x32_bf16 v[38:41], v[146:149], v[170:173], v[38:41]
	v_mfma_f32_16x16x32_bf16 v[34:37], v[154:157], v[170:173], v[34:37]
	v_mfma_f32_16x16x32_bf16 v[22:25], v[146:149], v[178:181], v[22:25]
	v_mfma_f32_16x16x32_bf16 v[18:21], v[154:157], v[178:181], v[18:21]
	v_mfma_f32_16x16x32_bf16 v[6:9], v[146:149], v[186:189], v[6:9]
	v_mfma_f32_16x16x32_bf16 v[2:5], v[154:157], v[186:189], v[2:5]
	v_mfma_f32_16x16x32_bf16 v[54:57], v[150:153], v[166:169], v[54:57]
	v_mfma_f32_16x16x32_bf16 v[50:53], v[158:161], v[166:169], v[50:53]
	v_mfma_f32_16x16x32_bf16 v[38:41], v[150:153], v[174:177], v[38:41]
	v_mfma_f32_16x16x32_bf16 v[34:37], v[158:161], v[174:177], v[34:37]
	v_mfma_f32_16x16x32_bf16 v[22:25], v[150:153], v[182:185], v[22:25]
	v_mfma_f32_16x16x32_bf16 v[18:21], v[158:161], v[182:185], v[18:21]
	v_mfma_f32_16x16x32_bf16 v[6:9], v[150:153], v[190:193], v[6:9]
	v_mfma_f32_16x16x32_bf16 v[2:5], v[158:161], v[190:193], v[2:5]
	s_add_i32 s50, s50, 2
	s_add_u32 s22, s22, 0x100
	s_addc_u32 s23, s23, 0
	s_add_u32 s57, s57, 0x100
	s_addc_u32 s60, s60, 0
	s_add_u32 s16, s22, 0xfffe0080
	s_addc_u32 s17, s23, -1
	s_add_i32 s52, 0, 0x10000
	s_cmp_eq_u32 s50, 4
	s_cselect_b32 s25, s15, s17
	s_cselect_b32 s24, s55, s16
	s_cselect_b32 s17, s13, s60
	s_cselect_b32 s16, s56, s57
	s_add_i32 s61, 0, 0x14000
	s_cmp_gt_u32 s50, 5
	s_setprio 0
	s_barrier
	s_cbranch_scc0 .LBB0_632
	s_and_b64 vcc, exec, s[10:11]
	s_cbranch_vccz .LBB0_635
	s_barrier

;     __device__ __forceinline__ bool next(int i, Unit& u) const { const int L = i * G + c; if (L >= 512) return false; u.pm = L; u.pn = L >> 4; return true; }
; #define PG8_STAGE(bufoff, gbase, voff) do { _Pragma("unroll") for (int _i = 0; _i < 2; ++_i) \
;         __builtin_amdgcn_global_load_lds((const unsigned*)((const char*)(gbase) + (voff)[_i]), (PG8_LAS unsigned*)(lds + (bufoff) + ldsw + _i * 8192), 16, 0, 0); } while (0)
; #define PG8_LDA(dst, b, h) do { _Pragma("unroll") for (int m = 0; m < 4; ++m) _Pragma("unroll") for (int k = 0; k < 2; ++k) dst[m][k] = *(const PG8_LAS bf16x8*)(lds + PG8_SA(b, h) + aoff + m * 2048 + k * 1024); } while (0)
; #define PG8_LDB(dst, b, h) do { _Pragma("unroll") for (int n = 0; n < 2; ++n) _Pragma("unroll") for (int k = 0; k < 2; ++k) dst[n][k] = *(const PG8_LAS bf16x8*)(lds + PG8_SB(b, h) + boff + n * 2048 + k * 1024); } while (0)
; template <class Epi, class Sched, bool ALIGN_EPI = false, bool SP2 = false>
; __device__ __forceinline__ void gemm_phase(PG8_LAS unsigned char* lds, const Gemm g, const Sched& S, const Epi& E) {
;     ...
;         const bool has_next = S.next(ui + 1, nxt);
;         const char* nA = has_next ? (const char*)g.A + (size_t)nxt.pm * tstep : cA; const char* nB = has_next ? (const char*)g.Bt + (size_t)nxt.pn * tstep : cB;
;         for (int t = 0; t < nt; t += 2) {
;             const bool last = (t == nt - 2);
;             const char* a1 = cA + (size_t)(t + 1) * kstep;
;             const char* a2 = last ? nA : cA + (size_t)(t + 2) * kstep; const char* b2 = last ? nB : cB + (size_t)(t + 2) * kstep;
;             const char* a3 = a2 + kstep; const char* b3 = b2 + kstep;
;             if (last && has_next) S.a_ready(nxt);
;             if constexpr (SP2) {
;             PG8_LDB(B0, 0, 0); PG8_LDB(B1, 0, 1); PG8_SCHED; PG8_LDA(At, 0, 0); PG8_STAGE(PG8_SA(1, 1), a1 + hstep, voffA);
;             PG8_WAIT_V(8); PG8_WAIT_L(0); PG8_BAR; PG8_MMA(0, 0, At, B0); PG8_MMA(0, 1, At, B1); PG8_BAR; PG8_SCHED;
;     ...
; #pragma unroll
;         for (int a = 0; a < 2; ++a)
; #pragma unroll
;             for (int b = 0; b < 2; ++b)
; #pragma unroll
;                 for (int m = 0; m < 4; ++m)
; #pragma unroll
;                     for (int n = 0; n < 2; ++n) acc[a][b][m][n] = (f32x4){0.f, 0.f, 0.f, 0.f};
;         cur = nxt; cA = nA; cB = nB; ++ui;
;         if constexpr (ALIGN_EPI) { if (wr == 1) PG8_BAR; }
.LBB0_696:
	s_ashr_i32 s13, s12, 31
	s_lshl_b64 s[14:15], s[12:13], 19
	s_add_u32 s14, s24, s14
	s_addc_u32 s15, s25, s15
	s_and_b64 s[18:19], s[4:5], exec
	s_cselect_b32 s13, s15, s21
	s_cselect_b32 s39, s14, s20
	s_ashr_i32 s11, s10, 31
	s_lshl_b64 s[18:19], s[10:11], 19
	s_add_u32 s18, s26, s18
	s_addc_u32 s19, s27, s19
	s_and_b64 s[22:23], s[4:5], exec
	s_cselect_b32 s11, s19, s17
	s_cselect_b32 s46, s18, s16
	s_add_u32 s20, s20, 0x40080
	s_addc_u32 s21, s21, 0
	s_add_u32 s55, s16, 0x100
	v_mov_b32_e32 v2, 0
	s_addc_u32 s56, s17, 0
	s_mov_b32 s50, -2
	v_mov_b32_e32 v3, v2
	v_mov_b32_e32 v4, v2
	v_mov_b32_e32 v5, v2
	v_mov_b32_e32 v6, v2
	v_mov_b32_e32 v7, v2
	v_mov_b32_e32 v8, v2
	v_mov_b32_e32 v9, v2
	v_mov_b32_e32 v14, v2
	v_mov_b32_e32 v15, v2
	v_mov_b32_e32 v16, v2
	v_mov_b32_e32 v17, v2
	v_mov_b32_e32 v22, v2
	v_mov_b32_e32 v23, v2
	v_mov_b32_e32 v24, v2
	v_mov_b32_e32 v25, v2
	v_mov_b32_e32 v30, v2
	v_mov_b32_e32 v31, v2
	v_mov_b32_e32 v32, v2
	v_mov_b32_e32 v33, v2
	v_mov_b32_e32 v38, v2
	v_mov_b32_e32 v39, v2
	v_mov_b32_e32 v40, v2
	v_mov_b32_e32 v41, v2
	v_mov_b32_e32 v46, v2
	v_mov_b32_e32 v47, v2
	v_mov_b32_e32 v48, v2
	v_mov_b32_e32 v49, v2
	v_mov_b32_e32 v54, v2
	v_mov_b32_e32 v55, v2
	v_mov_b32_e32 v56, v2
	v_mov_b32_e32 v57, v2
	v_mov_b32_e32 v10, v2
	v_mov_b32_e32 v11, v2
	v_mov_b32_e32 v12, v2
	v_mov_b32_e32 v13, v2
	v_mov_b32_e32 v18, v2
	v_mov_b32_e32 v19, v2
	v_mov_b32_e32 v20, v2
	v_mov_b32_e32 v21, v2
	v_mov_b32_e32 v26, v2
	v_mov_b32_e32 v27, v2
	v_mov_b32_e32 v28, v2
	v_mov_b32_e32 v29, v2
	v_mov_b32_e32 v34, v2
	v_mov_b32_e32 v35, v2
	v_mov_b32_e32 v36, v2
	v_mov_b32_e32 v37, v2
	v_mov_b32_e32 v42, v2
	v_mov_b32_e32 v43, v2
	v_mov_b32_e32 v44, v2
	v_mov_b32_e32 v45, v2
	v_mov_b32_e32 v50, v2
	v_mov_b32_e32 v51, v2
	v_mov_b32_e32 v52, v2
	v_mov_b32_e32 v53, v2
	v_mov_b32_e32 v58, v2
	v_mov_b32_e32 v59, v2
	v_mov_b32_e32 v60, v2
	v_mov_b32_e32 v61, v2
	v_mov_b32_e32 v62, v2
	v_mov_b32_e32 v63, v2
	v_mov_b32_e32 v64, v2
	v_mov_b32_e32 v65, v2
	v_mov_b32_e32 v66, v2
	v_mov_b32_e32 v67, v2
	v_mov_b32_e32 v68, v2
	v_mov_b32_e32 v69, v2
	v_mov_b32_e32 v70, v2
	v_mov_b32_e32 v71, v2
	v_mov_b32_e32 v72, v2
	v_mov_b32_e32 v73, v2
	v_mov_b32_e32 v78, v2
	v_mov_b32_e32 v79, v2
	v_mov_b32_e32 v80, v2
	v_mov_b32_e32 v81, v2
	v_mov_b32_e32 v86, v2
	v_mov_b32_e32 v87, v2
	v_mov_b32_e32 v88, v2
	v_mov_b32_e32 v89, v2
	v_mov_b32_e32 v94, v2
	v_mov_b32_e32 v95, v2
	v_mov_b32_e32 v96, v2
	v_mov_b32_e32 v97, v2
	v_mov_b32_e32 v102, v2
	v_mov_b32_e32 v103, v2
	v_mov_b32_e32 v104, v2
	v_mov_b32_e32 v105, v2
	v_mov_b32_e32 v110, v2
	v_mov_b32_e32 v111, v2
	v_mov_b32_e32 v112, v2
	v_mov_b32_e32 v113, v2
	v_mov_b32_e32 v118, v2
	v_mov_b32_e32 v119, v2
	v_mov_b32_e32 v120, v2
	v_mov_b32_e32 v121, v2
	v_mov_b32_e32 v74, v2
	v_mov_b32_e32 v75, v2
	v_mov_b32_e32 v76, v2
	v_mov_b32_e32 v77, v2
	v_mov_b32_e32 v82, v2
	v_mov_b32_e32 v83, v2
	v_mov_b32_e32 v84, v2
	v_mov_b32_e32 v85, v2
	v_mov_b32_e32 v90, v2
	v_mov_b32_e32 v91, v2
	v_mov_b32_e32 v92, v2
	v_mov_b32_e32 v93, v2
	v_mov_b32_e32 v98, v2
	v_mov_b32_e32 v99, v2
	v_mov_b32_e32 v100, v2
	v_mov_b32_e32 v101, v2
	v_mov_b32_e32 v106, v2
	v_mov_b32_e32 v107, v2
	v_mov_b32_e32 v108, v2
	v_mov_b32_e32 v109, v2
	v_mov_b32_e32 v114, v2
	v_mov_b32_e32 v115, v2
	v_mov_b32_e32 v116, v2
	v_mov_b32_e32 v117, v2
	v_mov_b32_e32 v122, v2
	v_mov_b32_e32 v123, v2
	v_mov_b32_e32 v124, v2
	v_mov_b32_e32 v125, v2
	v_mov_b32_e32 v126, v2
	v_mov_b32_e32 v127, v2
	v_mov_b32_e32 v128, v2
	v_mov_b32_e32 v129, v2
	s_cmp_eq_u64 s[0:1], 0
	s_cbranch_scc1 .Lboff_skip_I
	s_barrier
.Lboff_skip_I:
	s_add_u32 s16, s20, 0xfffc0080
	s_addc_u32 s17, s21, -1
	s_add_i32 s52, 0, 0x10000
	s_cmp_eq_u32 s50, 12
	s_cselect_b32 s23, s13, s17
	s_cselect_b32 s22, s39, s16
	s_cselect_b32 s17, s11, s56
	s_cselect_b32 s16, s46, s55
	s_add_i32 s57, 0, 0x14000
.LBB0_697:
	v_add_u32_e32 v142, s52, v231
	v_add_u32_e32 v158, s57, v231
	ds_read_b128 v[130:133], v142
	ds_read_b128 v[134:137], v142 offset:1024
	ds_read_b128 v[138:141], v142 offset:2048
	ds_read_b128 v[142:145], v142 offset:3072
	ds_read_b128 v[146:149], v158
	ds_read_b128 v[150:153], v158 offset:1024
	ds_read_b128 v[154:157], v158 offset:2048
	ds_read_b128 v[158:161], v158 offset:3072
	v_lshl_add_u64 v[206:207], s[20:21], 0, v[202:203]
	s_add_i32 m0, s29, 0xc000
	ds_read_b128 v[162:165], v232
	ds_read_b128 v[166:169], v232 offset:1024
	ds_read_b128 v[170:173], v232 offset:2048
	ds_read_b128 v[174:177], v232 offset:3072
	ds_read_b128 v[178:181], v232 offset:4096
	ds_read_b128 v[182:185], v232 offset:5120
	ds_read_b128 v[186:189], v232 offset:6144
	ds_read_b128 v[190:193], v232 offset:7168
	global_load_lds_dwordx4 v[206:207], off
	v_lshl_add_u64 v[206:207], s[20:21], 0, v[204:205]
	s_add_i32 m0, s29, 0xe000
	s_nop 0
	global_load_lds_dwordx4 v[206:207], off
	s_waitcnt vmcnt(8)
	s_waitcnt lgkmcnt(0)
	s_barrier
; #define PG8_STAGE(bufoff, gbase, voff) do { _Pragma("unroll") for (int _i = 0; _i < 2; ++_i) \
;         __builtin_amdgcn_global_load_lds((const unsigned*)((const char*)(gbase) + (voff)[_i]), (PG8_LAS unsigned*)(lds + (bufoff) + ldsw + _i * 8192), 16, 0, 0); } while (0)
; #define PG8_LDA(dst, b, h) do { _Pragma("unroll") for (int m = 0; m < 4; ++m) _Pragma("unroll") for (int k = 0; k < 2; ++k) dst[m][k] = *(const PG8_LAS bf16x8*)(lds + PG8_SA(b, h) + aoff + m * 2048 + k * 1024); } while (0)
; #define PG8_MMA(ai, bj, At, Bt) do { __builtin_amdgcn_s_setprio(1); _Pragma("unroll") for (int m = 0; m < 4; ++m) _Pragma("unroll") for (int n = 0; n < 2; ++n) _Pragma("unroll") for (int k = 0; k < 2; ++k) \
;         acc[ai][bj][m][n] = __builtin_amdgcn_mfma_f32_16x16x32_bf16(Bt[n][k], At[m][k], acc[ai][bj][m][n], 0, 0, 0); __builtin_amdgcn_s_setprio(0); } while (0)
; #define PG8_WAIT_V(n) asm volatile("s_waitcnt vmcnt(" #n ")" ::: "memory")
; #define PG8_WAIT_L(n) asm volatile("s_waitcnt lgkmcnt(" #n ")" ::: "memory")
; #define PG8_BAR __builtin_amdgcn_s_barrier()
; #define PG8_SCHED __builtin_amdgcn_sched_barrier(0)
; template <class Epi, class Sched, bool ALIGN_EPI = false, bool SP2 = false>
; __device__ __forceinline__ void gemm_phase(PG8_LAS unsigned char* lds, const Gemm g, const Sched& S, const Epi& E) {
;     ...
;             PG8_WAIT_V(8); PG8_WAIT_L(0); PG8_BAR; PG8_MMA(0, 0, At, B0); PG8_MMA(0, 1, At, B1); PG8_BAR; PG8_SCHED;
;             PG8_LDA(At, 0, 1); PG8_STAGE(PG8_SB(0, 0), b2, voffB); PG8_STAGE(PG8_SB(0, 1), b2 + hstep, voffB); PG8_STAGE(PG8_SA(0, 0), a2, voffA);
;             PG8_WAIT_V(8); PG8_WAIT_L(0); PG8_BAR; PG8_MMA(1, 0, At, B0); PG8_MMA(1, 1, At, B1); PG8_BAR; PG8_SCHED;
	s_setprio 1
	s_waitcnt lgkmcnt(0)
	v_mfma_f32_16x16x32_bf16 v[126:129], v[130:133], v[162:165], v[126:129]
	v_mfma_f32_16x16x32_bf16 v[122:125], v[138:141], v[162:165], v[122:125]
	v_mfma_f32_16x16x32_bf16 v[114:117], v[130:133], v[170:173], v[114:117]
	v_mfma_f32_16x16x32_bf16 v[106:109], v[138:141], v[170:173], v[106:109]
	v_mfma_f32_16x16x32_bf16 v[98:101], v[130:133], v[178:181], v[98:101]
	v_mfma_f32_16x16x32_bf16 v[90:93], v[138:141], v[178:181], v[90:93]
	v_mfma_f32_16x16x32_bf16 v[82:85], v[130:133], v[186:189], v[82:85]
	v_mfma_f32_16x16x32_bf16 v[74:77], v[138:141], v[186:189], v[74:77]
	v_mfma_f32_16x16x32_bf16 v[126:129], v[134:137], v[166:169], v[126:129]
	v_mfma_f32_16x16x32_bf16 v[122:125], v[142:145], v[166:169], v[122:125]
	v_mfma_f32_16x16x32_bf16 v[114:117], v[134:137], v[174:177], v[114:117]
	v_mfma_f32_16x16x32_bf16 v[106:109], v[142:145], v[174:177], v[106:109]
	v_mfma_f32_16x16x32_bf16 v[98:101], v[134:137], v[182:185], v[98:101]
	v_mfma_f32_16x16x32_bf16 v[90:93], v[142:145], v[182:185], v[90:93]
	v_mfma_f32_16x16x32_bf16 v[82:85], v[134:137], v[190:193], v[82:85]
	v_mfma_f32_16x16x32_bf16 v[74:77], v[142:145], v[190:193], v[74:77]
	s_setprio 0
	s_setprio 1
	v_mfma_f32_16x16x32_bf16 v[118:121], v[146:149], v[162:165], v[118:121]
	v_mfma_f32_16x16x32_bf16 v[110:113], v[154:157], v[162:165], v[110:113]
	v_mfma_f32_16x16x32_bf16 v[102:105], v[146:149], v[170:173], v[102:105]
	v_mfma_f32_16x16x32_bf16 v[94:97], v[154:157], v[170:173], v[94:97]
	v_mfma_f32_16x16x32_bf16 v[86:89], v[146:149], v[178:181], v[86:89]
	v_mfma_f32_16x16x32_bf16 v[78:81], v[154:157], v[178:181], v[78:81]
	v_mfma_f32_16x16x32_bf16 v[70:73], v[146:149], v[186:189], v[70:73]
	v_mfma_f32_16x16x32_bf16 v[66:69], v[154:157], v[186:189], v[66:69]
	v_mfma_f32_16x16x32_bf16 v[118:121], v[150:153], v[166:169], v[118:121]
	v_mfma_f32_16x16x32_bf16 v[110:113], v[158:161], v[166:169], v[110:113]
	v_mfma_f32_16x16x32_bf16 v[102:105], v[150:153], v[174:177], v[102:105]
	v_mfma_f32_16x16x32_bf16 v[94:97], v[158:161], v[174:177], v[94:97]
	v_mfma_f32_16x16x32_bf16 v[86:89], v[150:153], v[182:185], v[86:89]
	v_mfma_f32_16x16x32_bf16 v[78:81], v[158:161], v[182:185], v[78:81]
	v_mfma_f32_16x16x32_bf16 v[70:73], v[150:153], v[190:193], v[70:73]
	v_mfma_f32_16x16x32_bf16 v[66:69], v[158:161], v[190:193], v[66:69]
	s_setprio 0
	s_barrier
	s_add_i32 s52, s52, s28
	v_lshl_add_u64 v[206:207], s[16:17], 0, v[198:199]
	s_mov_b32 m0, s52
	ds_read_b128 v[162:165], v232 offset:16384
	ds_read_b128 v[166:169], v232 offset:17408
	ds_read_b128 v[170:173], v232 offset:18432
	ds_read_b128 v[174:177], v232 offset:19456
	ds_read_b128 v[178:181], v232 offset:20480
	ds_read_b128 v[182:185], v232 offset:21504
	ds_read_b128 v[186:189], v232 offset:22528
	ds_read_b128 v[190:193], v232 offset:23552
	global_load_lds_dwordx4 v[206:207], off
	s_add_i32 m0, s52, 0x2000
	s_add_u32 s52, s16, 0x40000
	v_lshl_add_u64 v[208:209], s[16:17], 0, v[194:195]
	s_addc_u32 s53, s17, 0
	s_add_i32 s57, s57, s28
	global_load_lds_dwordx4 v[208:209], off
	v_lshl_add_u64 v[210:211], s[52:53], 0, v[198:199]
	s_mov_b32 m0, s57
	v_lshl_add_u64 v[212:213], s[22:23], 0, v[196:197]
	global_load_lds_dwordx4 v[210:211], off
	v_lshl_add_u64 v[210:211], s[52:53], 0, v[194:195]
	s_add_i32 m0, s57, 0x2000
	s_nop 0
	global_load_lds_dwordx4 v[210:211], off
	v_lshl_add_u64 v[210:211], s[22:23], 0, v[200:201]
	s_mov_b32 m0, s29
	s_nop 0
	global_load_lds_dwordx4 v[210:211], off
	s_mov_b32 m0, s30
	s_nop 0
	global_load_lds_dwordx4 v[212:213], off
	s_waitcnt vmcnt(8)
	s_waitcnt lgkmcnt(0)
	s_barrier
	s_setprio 1
	s_waitcnt lgkmcnt(0)
	v_mfma_f32_16x16x32_bf16 v[62:65], v[130:133], v[162:165], v[62:65]
	v_mfma_f32_16x16x32_bf16 v[58:61], v[138:141], v[162:165], v[58:61]
	v_mfma_f32_16x16x32_bf16 v[50:53], v[130:133], v[170:173], v[50:53]
	v_mfma_f32_16x16x32_bf16 v[42:45], v[138:141], v[170:173], v[42:45]
	v_mfma_f32_16x16x32_bf16 v[34:37], v[130:133], v[178:181], v[34:37]
	v_mfma_f32_16x16x32_bf16 v[26:29], v[138:141], v[178:181], v[26:29]
	v_mfma_f32_16x16x32_bf16 v[18:21], v[130:133], v[186:189], v[18:21]
	v_mfma_f32_16x16x32_bf16 v[10:13], v[138:141], v[186:189], v[10:13]
	v_mfma_f32_16x16x32_bf16 v[62:65], v[134:137], v[166:169], v[62:65]
	v_mfma_f32_16x16x32_bf16 v[58:61], v[142:145], v[166:169], v[58:61]
	v_mfma_f32_16x16x32_bf16 v[50:53], v[134:137], v[174:177], v[50:53]
	v_mfma_f32_16x16x32_bf16 v[42:45], v[142:145], v[174:177], v[42:45]
	v_mfma_f32_16x16x32_bf16 v[34:37], v[134:137], v[182:185], v[34:37]
	v_mfma_f32_16x16x32_bf16 v[26:29], v[142:145], v[182:185], v[26:29]
	v_mfma_f32_16x16x32_bf16 v[18:21], v[134:137], v[190:193], v[18:21]
	v_mfma_f32_16x16x32_bf16 v[10:13], v[142:145], v[190:193], v[10:13]
	s_setprio 0
	s_setprio 1
	v_mfma_f32_16x16x32_bf16 v[54:57], v[146:149], v[162:165], v[54:57]
	v_mfma_f32_16x16x32_bf16 v[46:49], v[154:157], v[162:165], v[46:49]
	v_mfma_f32_16x16x32_bf16 v[38:41], v[146:149], v[170:173], v[38:41]
	v_mfma_f32_16x16x32_bf16 v[30:33], v[154:157], v[170:173], v[30:33]
	v_mfma_f32_16x16x32_bf16 v[22:25], v[146:149], v[178:181], v[22:25]
	v_mfma_f32_16x16x32_bf16 v[14:17], v[154:157], v[178:181], v[14:17]
	v_mfma_f32_16x16x32_bf16 v[6:9], v[146:149], v[186:189], v[6:9]
	v_mfma_f32_16x16x32_bf16 v[2:5], v[154:157], v[186:189], v[2:5]
	v_mfma_f32_16x16x32_bf16 v[54:57], v[150:153], v[166:169], v[54:57]
	v_mfma_f32_16x16x32_bf16 v[46:49], v[158:161], v[166:169], v[46:49]
	v_mfma_f32_16x16x32_bf16 v[38:41], v[150:153], v[174:177], v[38:41]
	v_mfma_f32_16x16x32_bf16 v[30:33], v[158:161], v[174:177], v[30:33]
	v_mfma_f32_16x16x32_bf16 v[22:25], v[150:153], v[182:185], v[22:25]
	v_mfma_f32_16x16x32_bf16 v[14:17], v[158:161], v[182:185], v[14:17]
	v_mfma_f32_16x16x32_bf16 v[6:9], v[150:153], v[190:193], v[6:9]
	v_mfma_f32_16x16x32_bf16 v[2:5], v[158:161], v[190:193], v[2:5]
	s_setprio 0
	s_barrier
; #define PG8_STAGE(bufoff, gbase, voff) do { _Pragma("unroll") for (int _i = 0; _i < 2; ++_i) \
;         __builtin_amdgcn_global_load_lds((const unsigned*)((const char*)(gbase) + (voff)[_i]), (PG8_LAS unsigned*)(lds + (bufoff) + ldsw + _i * 8192), 16, 0, 0); } while (0)
; #define PG8_LDA(dst, b, h) do { _Pragma("unroll") for (int m = 0; m < 4; ++m) _Pragma("unroll") for (int k = 0; k < 2; ++k) dst[m][k] = *(const PG8_LAS bf16x8*)(lds + PG8_SA(b, h) + aoff + m * 2048 + k * 1024); } while (0)
; #define PG8_LDB(dst, b, h) do { _Pragma("unroll") for (int n = 0; n < 2; ++n) _Pragma("unroll") for (int k = 0; k < 2; ++k) dst[n][k] = *(const PG8_LAS bf16x8*)(lds + PG8_SB(b, h) + boff + n * 2048 + k * 1024); } while (0)
; #define PG8_MMA(ai, bj, At, Bt) do { __builtin_amdgcn_s_setprio(1); _Pragma("unroll") for (int m = 0; m < 4; ++m) _Pragma("unroll") for (int n = 0; n < 2; ++n) _Pragma("unroll") for (int k = 0; k < 2; ++k) \
;         acc[ai][bj][m][n] = __builtin_amdgcn_mfma_f32_16x16x32_bf16(Bt[n][k], At[m][k], acc[ai][bj][m][n], 0, 0, 0); __builtin_amdgcn_s_setprio(0); } while (0)
; #define PG8_WAIT_V(n) asm volatile("s_waitcnt vmcnt(" #n ")" ::: "memory")
; #define PG8_WAIT_L(n) asm volatile("s_waitcnt lgkmcnt(" #n ")" ::: "memory")
; #define PG8_BAR __builtin_amdgcn_s_barrier()
; #define PG8_SCHED __builtin_amdgcn_sched_barrier(0)
; template <class Epi, class Sched, bool ALIGN_EPI = false, bool SP2 = false>
; __device__ __forceinline__ void gemm_phase(PG8_LAS unsigned char* lds, const Gemm g, const Sched& S, const Epi& E) {
;     ...
;             PG8_LDB(B0, 1, 0); PG8_LDB(B1, 1, 1); PG8_SCHED; PG8_LDA(At, 1, 0); PG8_STAGE(PG8_SA(0, 1), a2 + hstep, voffA);
;             PG8_WAIT_V(8); PG8_WAIT_L(0); PG8_BAR; PG8_MMA(0, 0, At, B0); PG8_MMA(0, 1, At, B1); PG8_BAR; PG8_SCHED;
	s_add_i32 s52, 0, 0x18000
	s_add_i32 s53, 0, 0x1c000
	v_add_u32_e32 v142, s52, v231
	v_add_u32_e32 v158, s53, v231
	ds_read_b128 v[130:133], v142
	ds_read_b128 v[134:137], v142 offset:1024
	ds_read_b128 v[138:141], v142 offset:2048
	ds_read_b128 v[142:145], v142 offset:3072
	ds_read_b128 v[146:149], v158
	ds_read_b128 v[150:153], v158 offset:1024
	ds_read_b128 v[154:157], v158 offset:2048
	ds_read_b128 v[158:161], v158 offset:3072
	s_add_u32 s22, s22, 0x40000
	s_addc_u32 s23, s23, 0
	s_mov_b32 m0, s31
	v_lshl_add_u64 v[214:215], s[22:23], 0, v[200:201]
	ds_read_b128 v[162:165], v232 offset:32768
	ds_read_b128 v[166:169], v232 offset:33792
	ds_read_b128 v[170:173], v232 offset:34816
	ds_read_b128 v[174:177], v232 offset:35840
	ds_read_b128 v[178:181], v232 offset:36864
	ds_read_b128 v[182:185], v232 offset:37888
	ds_read_b128 v[186:189], v232 offset:38912
	ds_read_b128 v[190:193], v232 offset:39936
	global_load_lds_dwordx4 v[214:215], off
	v_lshl_add_u64 v[214:215], s[22:23], 0, v[196:197]
	s_mov_b32 m0, s34
	s_nop 0
	global_load_lds_dwordx4 v[214:215], off
	s_waitcnt vmcnt(8)
	s_waitcnt lgkmcnt(0)
	s_barrier
	s_setprio 1
	s_waitcnt lgkmcnt(0)
	v_mfma_f32_16x16x32_bf16 v[126:129], v[130:133], v[162:165], v[126:129]
	v_mfma_f32_16x16x32_bf16 v[122:125], v[138:141], v[162:165], v[122:125]
	v_mfma_f32_16x16x32_bf16 v[114:117], v[130:133], v[170:173], v[114:117]
	v_mfma_f32_16x16x32_bf16 v[106:109], v[138:141], v[170:173], v[106:109]
	v_mfma_f32_16x16x32_bf16 v[98:101], v[130:133], v[178:181], v[98:101]
	v_mfma_f32_16x16x32_bf16 v[90:93], v[138:141], v[178:181], v[90:93]
	v_mfma_f32_16x16x32_bf16 v[82:85], v[130:133], v[186:189], v[82:85]
	v_mfma_f32_16x16x32_bf16 v[74:77], v[138:141], v[186:189], v[74:77]
	v_mfma_f32_16x16x32_bf16 v[126:129], v[134:137], v[166:169], v[126:129]
	v_mfma_f32_16x16x32_bf16 v[122:125], v[142:145], v[166:169], v[122:125]
	v_mfma_f32_16x16x32_bf16 v[114:117], v[134:137], v[174:177], v[114:117]
	v_mfma_f32_16x16x32_bf16 v[106:109], v[142:145], v[174:177], v[106:109]
	v_mfma_f32_16x16x32_bf16 v[98:101], v[134:137], v[182:185], v[98:101]
	v_mfma_f32_16x16x32_bf16 v[90:93], v[142:145], v[182:185], v[90:93]
	v_mfma_f32_16x16x32_bf16 v[82:85], v[134:137], v[190:193], v[82:85]
	v_mfma_f32_16x16x32_bf16 v[74:77], v[142:145], v[190:193], v[74:77]
	s_setprio 0
	s_setprio 1
	v_mfma_f32_16x16x32_bf16 v[118:121], v[146:149], v[162:165], v[118:121]
	v_mfma_f32_16x16x32_bf16 v[110:113], v[154:157], v[162:165], v[110:113]
	v_mfma_f32_16x16x32_bf16 v[102:105], v[146:149], v[170:173], v[102:105]
	v_mfma_f32_16x16x32_bf16 v[94:97], v[154:157], v[170:173], v[94:97]
	v_mfma_f32_16x16x32_bf16 v[86:89], v[146:149], v[178:181], v[86:89]
	v_mfma_f32_16x16x32_bf16 v[78:81], v[154:157], v[178:181], v[78:81]
	v_mfma_f32_16x16x32_bf16 v[70:73], v[146:149], v[186:189], v[70:73]
	v_mfma_f32_16x16x32_bf16 v[66:69], v[154:157], v[186:189], v[66:69]
	v_mfma_f32_16x16x32_bf16 v[118:121], v[150:153], v[166:169], v[118:121]
	v_mfma_f32_16x16x32_bf16 v[110:113], v[158:161], v[166:169], v[110:113]
	v_mfma_f32_16x16x32_bf16 v[102:105], v[150:153], v[174:177], v[102:105]
	v_mfma_f32_16x16x32_bf16 v[94:97], v[158:161], v[174:177], v[94:97]
	v_mfma_f32_16x16x32_bf16 v[86:89], v[150:153], v[182:185], v[86:89]
	v_mfma_f32_16x16x32_bf16 v[78:81], v[158:161], v[182:185], v[78:81]
	v_mfma_f32_16x16x32_bf16 v[70:73], v[150:153], v[190:193], v[70:73]
	v_mfma_f32_16x16x32_bf16 v[66:69], v[158:161], v[190:193], v[66:69]
	s_setprio 0
	s_barrier
; #define PG8_STAGE(bufoff, gbase, voff) do { _Pragma("unroll") for (int _i = 0; _i < 2; ++_i) \
;         __builtin_amdgcn_global_load_lds((const unsigned*)((const char*)(gbase) + (voff)[_i]), (PG8_LAS unsigned*)(lds + (bufoff) + ldsw + _i * 8192), 16, 0, 0); } while (0)
; #define PG8_LDA(dst, b, h) do { _Pragma("unroll") for (int m = 0; m < 4; ++m) _Pragma("unroll") for (int k = 0; k < 2; ++k) dst[m][k] = *(const PG8_LAS bf16x8*)(lds + PG8_SA(b, h) + aoff + m * 2048 + k * 1024); } while (0)
; #define PG8_MMA(ai, bj, At, Bt) do { __builtin_amdgcn_s_setprio(1); _Pragma("unroll") for (int m = 0; m < 4; ++m) _Pragma("unroll") for (int n = 0; n < 2; ++n) _Pragma("unroll") for (int k = 0; k < 2; ++k) \
;         acc[ai][bj][m][n] = __builtin_amdgcn_mfma_f32_16x16x32_bf16(Bt[n][k], At[m][k], acc[ai][bj][m][n], 0, 0, 0); __builtin_amdgcn_s_setprio(0); } while (0)
; #define PG8_WAIT_V(n) asm volatile("s_waitcnt vmcnt(" #n ")" ::: "memory")
; #define PG8_WAIT_L(n) asm volatile("s_waitcnt lgkmcnt(" #n ")" ::: "memory")
; #define PG8_BAR __builtin_amdgcn_s_barrier()
; #define PG8_SCHED __builtin_amdgcn_sched_barrier(0)
; template <class Epi, class Sched, bool ALIGN_EPI = false, bool SP2 = false>
; __device__ __forceinline__ void gemm_phase(PG8_LAS unsigned char* lds, const Gemm g, const Sched& S, const Epi& E) {
;     ...
;         for (int t = 0; t < nt; t += 2) {
;             const bool last = (t == nt - 2);
;             const char* a1 = cA + (size_t)(t + 1) * kstep;
;             const char* a2 = last ? nA : cA + (size_t)(t + 2) * kstep; const char* b2 = last ? nB : cB + (size_t)(t + 2) * kstep;
;     ...
;             PG8_LDA(At, 1, 1); PG8_STAGE(PG8_SB(1, 0), b3, voffB); PG8_STAGE(PG8_SB(1, 1), b3 + hstep, voffB); PG8_STAGE(PG8_SA(1, 0), a3, voffA);
;             PG8_WAIT_V(8); PG8_WAIT_L(0); PG8_BAR; PG8_MMA(1, 0, At, B0); PG8_MMA(1, 1, At, B1); PG8_BAR; PG8_SCHED;
	s_add_i32 s22, s52, s28
	v_lshl_add_u64 v[206:207], v[206:207], 0, s[94:95]
	s_mov_b32 m0, s22
	ds_read_b128 v[162:165], v232 offset:49152
	ds_read_b128 v[166:169], v232 offset:50176
	ds_read_b128 v[170:173], v232 offset:51200
	ds_read_b128 v[174:177], v232 offset:52224
	ds_read_b128 v[178:181], v232 offset:53248
	ds_read_b128 v[182:185], v232 offset:54272
	ds_read_b128 v[186:189], v232 offset:55296
	ds_read_b128 v[190:193], v232 offset:56320
	global_load_lds_dwordx4 v[206:207], off
	s_add_i32 m0, s22, 0x2000
	s_add_u32 s16, s16, 0x40080
	v_lshl_add_u64 v[206:207], v[208:209], 0, s[94:95]
	s_addc_u32 s17, s17, 0
	s_add_i32 s22, s53, s28
	global_load_lds_dwordx4 v[206:207], off
	v_lshl_add_u64 v[206:207], s[16:17], 0, v[198:199]
	s_mov_b32 m0, s22
	s_nop 0
	global_load_lds_dwordx4 v[206:207], off
	v_lshl_add_u64 v[206:207], s[16:17], 0, v[194:195]
	s_add_i32 m0, s22, 0x2000
	s_nop 0
	global_load_lds_dwordx4 v[206:207], off
	v_lshl_add_u64 v[206:207], v[210:211], 0, s[94:95]
	s_mov_b32 m0, s33
	s_nop 0
	global_load_lds_dwordx4 v[206:207], off
	v_lshl_add_u64 v[206:207], v[212:213], 0, s[94:95]
	s_mov_b32 m0, s35
	s_nop 0
	global_load_lds_dwordx4 v[206:207], off
	s_waitcnt vmcnt(8)
	s_waitcnt lgkmcnt(0)
	s_barrier
	s_setprio 1
	s_waitcnt lgkmcnt(0)
	v_mfma_f32_16x16x32_bf16 v[62:65], v[130:133], v[162:165], v[62:65]
	v_mfma_f32_16x16x32_bf16 v[58:61], v[138:141], v[162:165], v[58:61]
	v_mfma_f32_16x16x32_bf16 v[50:53], v[130:133], v[170:173], v[50:53]
	v_mfma_f32_16x16x32_bf16 v[42:45], v[138:141], v[170:173], v[42:45]
	v_mfma_f32_16x16x32_bf16 v[34:37], v[130:133], v[178:181], v[34:37]
	v_mfma_f32_16x16x32_bf16 v[26:29], v[138:141], v[178:181], v[26:29]
	v_mfma_f32_16x16x32_bf16 v[18:21], v[130:133], v[186:189], v[18:21]
	v_mfma_f32_16x16x32_bf16 v[10:13], v[138:141], v[186:189], v[10:13]
	v_mfma_f32_16x16x32_bf16 v[62:65], v[134:137], v[166:169], v[62:65]
	v_mfma_f32_16x16x32_bf16 v[58:61], v[142:145], v[166:169], v[58:61]
	v_mfma_f32_16x16x32_bf16 v[50:53], v[134:137], v[174:177], v[50:53]
	v_mfma_f32_16x16x32_bf16 v[42:45], v[142:145], v[174:177], v[42:45]
	v_mfma_f32_16x16x32_bf16 v[34:37], v[134:137], v[182:185], v[34:37]
	v_mfma_f32_16x16x32_bf16 v[26:29], v[142:145], v[182:185], v[26:29]
	v_mfma_f32_16x16x32_bf16 v[18:21], v[134:137], v[190:193], v[18:21]
	v_mfma_f32_16x16x32_bf16 v[10:13], v[142:145], v[190:193], v[10:13]
	s_setprio 0
	s_setprio 1
	v_mfma_f32_16x16x32_bf16 v[54:57], v[146:149], v[162:165], v[54:57]
	v_mfma_f32_16x16x32_bf16 v[46:49], v[154:157], v[162:165], v[46:49]
	v_mfma_f32_16x16x32_bf16 v[38:41], v[146:149], v[170:173], v[38:41]
	v_mfma_f32_16x16x32_bf16 v[30:33], v[154:157], v[170:173], v[30:33]
	v_mfma_f32_16x16x32_bf16 v[22:25], v[146:149], v[178:181], v[22:25]
	v_mfma_f32_16x16x32_bf16 v[14:17], v[154:157], v[178:181], v[14:17]
	v_mfma_f32_16x16x32_bf16 v[6:9], v[146:149], v[186:189], v[6:9]
	v_mfma_f32_16x16x32_bf16 v[2:5], v[154:157], v[186:189], v[2:5]
	v_mfma_f32_16x16x32_bf16 v[54:57], v[150:153], v[166:169], v[54:57]
	v_mfma_f32_16x16x32_bf16 v[46:49], v[158:161], v[166:169], v[46:49]
	v_mfma_f32_16x16x32_bf16 v[38:41], v[150:153], v[174:177], v[38:41]
	v_mfma_f32_16x16x32_bf16 v[30:33], v[158:161], v[174:177], v[30:33]
	v_mfma_f32_16x16x32_bf16 v[22:25], v[150:153], v[182:185], v[22:25]
	v_mfma_f32_16x16x32_bf16 v[14:17], v[158:161], v[182:185], v[14:17]
	v_mfma_f32_16x16x32_bf16 v[6:9], v[150:153], v[190:193], v[6:9]
	v_mfma_f32_16x16x32_bf16 v[2:5], v[158:161], v[190:193], v[2:5]
	s_add_i32 s50, s50, 2
	s_add_u32 s20, s20, 0x100
	s_addc_u32 s21, s21, 0
	s_add_u32 s55, s55, 0x100
	s_addc_u32 s56, s56, 0
	s_add_u32 s16, s20, 0xfffc0080
	s_addc_u32 s17, s21, -1
	s_add_i32 s52, 0, 0x10000
	s_cmp_eq_u32 s50, 12
	s_cselect_b32 s23, s13, s17
	s_cselect_b32 s22, s39, s16
	s_cselect_b32 s17, s11, s56
	s_cselect_b32 s16, s46, s55
	s_add_i32 s57, 0, 0x14000
	s_cmp_gt_u32 s50, 13
	s_setprio 0
	s_barrier
	s_cbranch_scc0 .LBB0_697
	s_and_b64 vcc, exec, s[8:9]
	s_cbranch_vccz .LBB0_700
	s_barrier

; #define PG8_STAGE(bufoff, gbase, voff) do { _Pragma("unroll") for (int _i = 0; _i < 2; ++_i) \
;         __builtin_amdgcn_global_load_lds((const unsigned*)((const char*)(gbase) + (voff)[_i]), (PG8_LAS unsigned*)(lds + (bufoff) + ldsw + _i * 8192), 16, 0, 0); } while (0)
; #define PG8_LDA(dst, b, h) do { _Pragma("unroll") for (int m = 0; m < 4; ++m) _Pragma("unroll") for (int k = 0; k < 2; ++k) dst[m][k] = *(const PG8_LAS bf16x8*)(lds + PG8_SA(b, h) + aoff + m * 2048 + k * 1024); } while (0)
; #define PG8_LDB(dst, b, h) do { _Pragma("unroll") for (int n = 0; n < 2; ++n) _Pragma("unroll") for (int k = 0; k < 2; ++k) dst[n][k] = *(const PG8_LAS bf16x8*)(lds + PG8_SB(b, h) + boff + n * 2048 + k * 1024); } while (0)
; #define PG8_BAR __builtin_amdgcn_s_barrier()
; #define PG8_SCHED __builtin_amdgcn_sched_barrier(0)
; template <class Epi, class Sched, bool ALIGN_EPI = false, bool SP2 = false>
; __device__ __forceinline__ void gemm_phase(PG8_LAS unsigned char* lds, const Gemm g, const Sched& S, const Epi& E) {
;     ...
;         const char* nA = has_next ? (const char*)g.A + (size_t)nxt.pm * tstep : cA; const char* nB = has_next ? (const char*)g.Bt + (size_t)nxt.pn * tstep : cB;
;         for (int t = 0; t < nt; t += 2) {
;             const bool last = (t == nt - 2);
;             const char* a1 = cA + (size_t)(t + 1) * kstep;
;             const char* a2 = last ? nA : cA + (size_t)(t + 2) * kstep; const char* b2 = last ? nB : cB + (size_t)(t + 2) * kstep;
;             const char* a3 = a2 + kstep; const char* b3 = b2 + kstep;
;             if (last && has_next) S.a_ready(nxt);
;             if constexpr (SP2) {
;             PG8_LDB(B0, 0, 0); PG8_LDB(B1, 0, 1); PG8_SCHED; PG8_LDA(At, 0, 0); PG8_STAGE(PG8_SA(1, 1), a1 + hstep, voffA);
;     ...
; #pragma unroll
;         for (int a = 0; a < 2; ++a)
; #pragma unroll
;             for (int b = 0; b < 2; ++b)
; #pragma unroll
;                 for (int m = 0; m < 4; ++m)
; #pragma unroll
;                     for (int n = 0; n < 2; ++n) acc[a][b][m][n] = (f32x4){0.f, 0.f, 0.f, 0.f};
;         cur = nxt; cA = nA; cB = nB; ++ui;
;         if constexpr (ALIGN_EPI) { if (wr == 1) PG8_BAR; }
.LBB0_815:
	s_ashr_i32 s13, s12, 31
	s_lshl_b64 s[14:15], s[12:13], 19
	s_add_u32 s14, s24, s14
	s_addc_u32 s15, s25, s15
	s_and_b64 s[18:19], s[4:5], exec
	s_cselect_b32 s13, s15, s21
	s_cselect_b32 s39, s14, s20
	s_ashr_i32 s11, s10, 31
	s_lshl_b64 s[18:19], s[10:11], 19
	s_add_u32 s18, s26, s18
	s_addc_u32 s19, s27, s19
	s_and_b64 s[22:23], s[4:5], exec
	s_cselect_b32 s11, s19, s17
	s_cselect_b32 s46, s18, s16
	s_add_u32 s20, s20, 0x40080
	s_addc_u32 s21, s21, 0
	s_add_u32 s55, s16, 0x100
	v_mov_b32_e32 v2, 0
	s_addc_u32 s56, s17, 0
	s_mov_b32 s50, -2
	v_mov_b32_e32 v3, v2
	v_mov_b32_e32 v4, v2
	v_mov_b32_e32 v5, v2
	v_mov_b32_e32 v6, v2
	v_mov_b32_e32 v7, v2
	v_mov_b32_e32 v8, v2
	v_mov_b32_e32 v9, v2
	v_mov_b32_e32 v18, v2
	v_mov_b32_e32 v19, v2
	v_mov_b32_e32 v20, v2
	v_mov_b32_e32 v21, v2
	v_mov_b32_e32 v22, v2
	v_mov_b32_e32 v23, v2
	v_mov_b32_e32 v24, v2
	v_mov_b32_e32 v25, v2
	v_mov_b32_e32 v34, v2
	v_mov_b32_e32 v35, v2
	v_mov_b32_e32 v36, v2
	v_mov_b32_e32 v37, v2
	v_mov_b32_e32 v38, v2
	v_mov_b32_e32 v39, v2
	v_mov_b32_e32 v40, v2
	v_mov_b32_e32 v41, v2
	v_mov_b32_e32 v50, v2
	v_mov_b32_e32 v51, v2
	v_mov_b32_e32 v52, v2
	v_mov_b32_e32 v53, v2
	v_mov_b32_e32 v54, v2
	v_mov_b32_e32 v55, v2
	v_mov_b32_e32 v56, v2
	v_mov_b32_e32 v57, v2
	v_mov_b32_e32 v10, v2
	v_mov_b32_e32 v11, v2
	v_mov_b32_e32 v12, v2
	v_mov_b32_e32 v13, v2
	v_mov_b32_e32 v14, v2
	v_mov_b32_e32 v15, v2
	v_mov_b32_e32 v16, v2
	v_mov_b32_e32 v17, v2
	v_mov_b32_e32 v26, v2
	v_mov_b32_e32 v27, v2
	v_mov_b32_e32 v28, v2
	v_mov_b32_e32 v29, v2
	v_mov_b32_e32 v30, v2
	v_mov_b32_e32 v31, v2
	v_mov_b32_e32 v32, v2
	v_mov_b32_e32 v33, v2
	v_mov_b32_e32 v42, v2
	v_mov_b32_e32 v43, v2
	v_mov_b32_e32 v44, v2
	v_mov_b32_e32 v45, v2
	v_mov_b32_e32 v46, v2
	v_mov_b32_e32 v47, v2
	v_mov_b32_e32 v48, v2
	v_mov_b32_e32 v49, v2
	v_mov_b32_e32 v58, v2
	v_mov_b32_e32 v59, v2
	v_mov_b32_e32 v60, v2
	v_mov_b32_e32 v61, v2
	v_mov_b32_e32 v62, v2
	v_mov_b32_e32 v63, v2
	v_mov_b32_e32 v64, v2
	v_mov_b32_e32 v65, v2
	v_mov_b32_e32 v66, v2
	v_mov_b32_e32 v67, v2
	v_mov_b32_e32 v68, v2
	v_mov_b32_e32 v69, v2
	v_mov_b32_e32 v70, v2
	v_mov_b32_e32 v71, v2
	v_mov_b32_e32 v72, v2
	v_mov_b32_e32 v73, v2
	v_mov_b32_e32 v82, v2
	v_mov_b32_e32 v83, v2
	v_mov_b32_e32 v84, v2
	v_mov_b32_e32 v85, v2
	v_mov_b32_e32 v86, v2
	v_mov_b32_e32 v87, v2
	v_mov_b32_e32 v88, v2
	v_mov_b32_e32 v89, v2
	v_mov_b32_e32 v98, v2
	v_mov_b32_e32 v99, v2
	v_mov_b32_e32 v100, v2
	v_mov_b32_e32 v101, v2
	v_mov_b32_e32 v102, v2
	v_mov_b32_e32 v103, v2
	v_mov_b32_e32 v104, v2
	v_mov_b32_e32 v105, v2
	v_mov_b32_e32 v114, v2
	v_mov_b32_e32 v115, v2
	v_mov_b32_e32 v116, v2
	v_mov_b32_e32 v117, v2
	v_mov_b32_e32 v118, v2
	v_mov_b32_e32 v119, v2
	v_mov_b32_e32 v120, v2
	v_mov_b32_e32 v121, v2
	v_mov_b32_e32 v74, v2
	v_mov_b32_e32 v75, v2
	v_mov_b32_e32 v76, v2
	v_mov_b32_e32 v77, v2
	v_mov_b32_e32 v78, v2
	v_mov_b32_e32 v79, v2
	v_mov_b32_e32 v80, v2
	v_mov_b32_e32 v81, v2
	v_mov_b32_e32 v90, v2
	v_mov_b32_e32 v91, v2
	v_mov_b32_e32 v92, v2
	v_mov_b32_e32 v93, v2
	v_mov_b32_e32 v94, v2
	v_mov_b32_e32 v95, v2
	v_mov_b32_e32 v96, v2
	v_mov_b32_e32 v97, v2
	v_mov_b32_e32 v106, v2
	v_mov_b32_e32 v107, v2
	v_mov_b32_e32 v108, v2
	v_mov_b32_e32 v109, v2
	v_mov_b32_e32 v110, v2
	v_mov_b32_e32 v111, v2
	v_mov_b32_e32 v112, v2
	v_mov_b32_e32 v113, v2
	v_mov_b32_e32 v122, v2
	v_mov_b32_e32 v123, v2
	v_mov_b32_e32 v124, v2
	v_mov_b32_e32 v125, v2
	v_mov_b32_e32 v126, v2
	v_mov_b32_e32 v127, v2
	v_mov_b32_e32 v128, v2
	v_mov_b32_e32 v129, v2
	s_cmp_eq_u64 s[0:1], 0
	s_cbranch_scc1 .Lboff_skip_K
	s_barrier
.Lboff_skip_K:
	s_add_u32 s16, s20, 0xfffc0080
	s_addc_u32 s17, s21, -1
	s_add_i32 s52, 0, 0x10000
	s_cmp_eq_u32 s50, 12
	s_cselect_b32 s23, s13, s17
	s_cselect_b32 s22, s39, s16
	s_cselect_b32 s17, s11, s56
	s_cselect_b32 s16, s46, s55
	s_add_i32 s57, 0, 0x14000
.LBB0_816:
	v_add_u32_e32 v142, s52, v145
	ds_read_b128 v[148:151], v142
	ds_read_b128 v[152:155], v142 offset:1024
	ds_read_b128 v[156:159], v142 offset:2048
	ds_read_b128 v[160:163], v142 offset:3072
	v_add_u32_e32 v142, s57, v145
	ds_read_b128 v[164:167], v142
	ds_read_b128 v[168:171], v142 offset:1024
	ds_read_b128 v[172:175], v142 offset:2048
	ds_read_b128 v[176:179], v142 offset:3072
	v_lshl_add_u64 v[142:143], s[20:21], 0, v[138:139]
	s_add_i32 m0, s29, 0xc000
	ds_read_b128 v[180:183], v146
	ds_read_b128 v[184:187], v146 offset:1024
	ds_read_b128 v[188:191], v146 offset:2048
	ds_read_b128 v[192:195], v146 offset:3072
	ds_read_b128 v[196:199], v146 offset:4096
	ds_read_b128 v[200:203], v146 offset:5120
	ds_read_b128 v[204:207], v146 offset:6144
	ds_read_b128 v[208:211], v146 offset:7168
	global_load_lds_dwordx4 v[142:143], off
	v_lshl_add_u64 v[142:143], s[20:21], 0, v[140:141]
	s_add_i32 m0, s29, 0xe000
	s_nop 0
	global_load_lds_dwordx4 v[142:143], off
	s_waitcnt vmcnt(8)
	s_waitcnt lgkmcnt(0)
	s_barrier
; #define PG8_STAGE(bufoff, gbase, voff) do { _Pragma("unroll") for (int _i = 0; _i < 2; ++_i) \
;         __builtin_amdgcn_global_load_lds((const unsigned*)((const char*)(gbase) + (voff)[_i]), (PG8_LAS unsigned*)(lds + (bufoff) + ldsw + _i * 8192), 16, 0, 0); } while (0)
; #define PG8_LDA(dst, b, h) do { _Pragma("unroll") for (int m = 0; m < 4; ++m) _Pragma("unroll") for (int k = 0; k < 2; ++k) dst[m][k] = *(const PG8_LAS bf16x8*)(lds + PG8_SA(b, h) + aoff + m * 2048 + k * 1024); } while (0)
; #define PG8_MMA(ai, bj, At, Bt) do { __builtin_amdgcn_s_setprio(1); _Pragma("unroll") for (int m = 0; m < 4; ++m) _Pragma("unroll") for (int n = 0; n < 2; ++n) _Pragma("unroll") for (int k = 0; k < 2; ++k) \
;         acc[ai][bj][m][n] = __builtin_amdgcn_mfma_f32_16x16x32_bf16(Bt[n][k], At[m][k], acc[ai][bj][m][n], 0, 0, 0); __builtin_amdgcn_s_setprio(0); } while (0)
; #define PG8_WAIT_V(n) asm volatile("s_waitcnt vmcnt(" #n ")" ::: "memory")
; #define PG8_WAIT_L(n) asm volatile("s_waitcnt lgkmcnt(" #n ")" ::: "memory")
; #define PG8_BAR __builtin_amdgcn_s_barrier()
; #define PG8_SCHED __builtin_amdgcn_sched_barrier(0)
; template <class Epi, class Sched, bool ALIGN_EPI = false, bool SP2 = false>
; __device__ __forceinline__ void gemm_phase(PG8_LAS unsigned char* lds, const Gemm g, const Sched& S, const Epi& E) {
;     ...
;             PG8_WAIT_V(8); PG8_WAIT_L(0); PG8_BAR; PG8_MMA(0, 0, At, B0); PG8_MMA(0, 1, At, B1); PG8_BAR; PG8_SCHED;
;             PG8_LDA(At, 0, 1); PG8_STAGE(PG8_SB(0, 0), b2, voffB); PG8_STAGE(PG8_SB(0, 1), b2 + hstep, voffB); PG8_STAGE(PG8_SA(0, 0), a2, voffA);
;             PG8_WAIT_V(8); PG8_WAIT_L(0); PG8_BAR; PG8_MMA(1, 0, At, B0); PG8_MMA(1, 1, At, B1); PG8_BAR; PG8_SCHED;
	s_setprio 1
	s_waitcnt lgkmcnt(0)
	v_mfma_f32_16x16x32_bf16 v[126:129], v[148:151], v[180:183], v[126:129]
	v_mfma_f32_16x16x32_bf16 v[122:125], v[156:159], v[180:183], v[122:125]
	v_mfma_f32_16x16x32_bf16 v[110:113], v[148:151], v[188:191], v[110:113]
	v_mfma_f32_16x16x32_bf16 v[106:109], v[156:159], v[188:191], v[106:109]
	v_mfma_f32_16x16x32_bf16 v[94:97], v[148:151], v[196:199], v[94:97]
	v_mfma_f32_16x16x32_bf16 v[90:93], v[156:159], v[196:199], v[90:93]
	v_mfma_f32_16x16x32_bf16 v[78:81], v[148:151], v[204:207], v[78:81]
	v_mfma_f32_16x16x32_bf16 v[74:77], v[156:159], v[204:207], v[74:77]
	v_mfma_f32_16x16x32_bf16 v[126:129], v[152:155], v[184:187], v[126:129]
	v_mfma_f32_16x16x32_bf16 v[122:125], v[160:163], v[184:187], v[122:125]
	v_mfma_f32_16x16x32_bf16 v[110:113], v[152:155], v[192:195], v[110:113]
	v_mfma_f32_16x16x32_bf16 v[106:109], v[160:163], v[192:195], v[106:109]
	v_mfma_f32_16x16x32_bf16 v[94:97], v[152:155], v[200:203], v[94:97]
	v_mfma_f32_16x16x32_bf16 v[90:93], v[160:163], v[200:203], v[90:93]
	v_mfma_f32_16x16x32_bf16 v[78:81], v[152:155], v[208:211], v[78:81]
	v_mfma_f32_16x16x32_bf16 v[74:77], v[160:163], v[208:211], v[74:77]
	s_setprio 0
	s_setprio 1
	v_mfma_f32_16x16x32_bf16 v[118:121], v[164:167], v[180:183], v[118:121]
	v_mfma_f32_16x16x32_bf16 v[114:117], v[172:175], v[180:183], v[114:117]
	v_mfma_f32_16x16x32_bf16 v[102:105], v[164:167], v[188:191], v[102:105]
	v_mfma_f32_16x16x32_bf16 v[98:101], v[172:175], v[188:191], v[98:101]
	v_mfma_f32_16x16x32_bf16 v[86:89], v[164:167], v[196:199], v[86:89]
	v_mfma_f32_16x16x32_bf16 v[82:85], v[172:175], v[196:199], v[82:85]
	v_mfma_f32_16x16x32_bf16 v[70:73], v[164:167], v[204:207], v[70:73]
	v_mfma_f32_16x16x32_bf16 v[66:69], v[172:175], v[204:207], v[66:69]
	v_mfma_f32_16x16x32_bf16 v[118:121], v[168:171], v[184:187], v[118:121]
	v_mfma_f32_16x16x32_bf16 v[114:117], v[176:179], v[184:187], v[114:117]
	v_mfma_f32_16x16x32_bf16 v[102:105], v[168:171], v[192:195], v[102:105]
	v_mfma_f32_16x16x32_bf16 v[98:101], v[176:179], v[192:195], v[98:101]
	v_mfma_f32_16x16x32_bf16 v[86:89], v[168:171], v[200:203], v[86:89]
	v_mfma_f32_16x16x32_bf16 v[82:85], v[176:179], v[200:203], v[82:85]
	v_mfma_f32_16x16x32_bf16 v[70:73], v[168:171], v[208:211], v[70:73]
	v_mfma_f32_16x16x32_bf16 v[66:69], v[176:179], v[208:211], v[66:69]
	s_setprio 0
	s_barrier
	s_add_i32 s52, s52, s28
	v_lshl_add_u64 v[142:143], s[16:17], 0, v[134:135]
	s_mov_b32 m0, s52
	ds_read_b128 v[180:183], v146 offset:16384
	ds_read_b128 v[184:187], v146 offset:17408
	ds_read_b128 v[188:191], v146 offset:18432
	ds_read_b128 v[192:195], v146 offset:19456
	ds_read_b128 v[196:199], v146 offset:20480
	ds_read_b128 v[200:203], v146 offset:21504
	ds_read_b128 v[204:207], v146 offset:22528
	ds_read_b128 v[208:211], v146 offset:23552
	global_load_lds_dwordx4 v[142:143], off
	s_add_i32 m0, s52, 0x2000
	s_add_u32 s52, s16, 0x40000
	v_lshl_add_u64 v[212:213], s[16:17], 0, v[130:131]
	s_addc_u32 s53, s17, 0
	s_add_i32 s57, s57, s28
	global_load_lds_dwordx4 v[212:213], off
	v_lshl_add_u64 v[214:215], s[52:53], 0, v[134:135]
	s_mov_b32 m0, s57
	v_lshl_add_u64 v[216:217], s[22:23], 0, v[132:133]
	global_load_lds_dwordx4 v[214:215], off
	v_lshl_add_u64 v[214:215], s[52:53], 0, v[130:131]
	s_add_i32 m0, s57, 0x2000
	s_nop 0
	global_load_lds_dwordx4 v[214:215], off
	v_lshl_add_u64 v[214:215], s[22:23], 0, v[136:137]
	s_mov_b32 m0, s29
	s_nop 0
	global_load_lds_dwordx4 v[214:215], off
	s_mov_b32 m0, s30
	s_nop 0
	global_load_lds_dwordx4 v[216:217], off
	s_waitcnt vmcnt(8)
	s_waitcnt lgkmcnt(0)
	s_barrier
	s_setprio 1
	s_waitcnt lgkmcnt(0)
	v_mfma_f32_16x16x32_bf16 v[62:65], v[148:151], v[180:183], v[62:65]
	v_mfma_f32_16x16x32_bf16 v[58:61], v[156:159], v[180:183], v[58:61]
	v_mfma_f32_16x16x32_bf16 v[46:49], v[148:151], v[188:191], v[46:49]
	v_mfma_f32_16x16x32_bf16 v[42:45], v[156:159], v[188:191], v[42:45]
	v_mfma_f32_16x16x32_bf16 v[30:33], v[148:151], v[196:199], v[30:33]
	v_mfma_f32_16x16x32_bf16 v[26:29], v[156:159], v[196:199], v[26:29]
	v_mfma_f32_16x16x32_bf16 v[14:17], v[148:151], v[204:207], v[14:17]
	v_mfma_f32_16x16x32_bf16 v[10:13], v[156:159], v[204:207], v[10:13]
	v_mfma_f32_16x16x32_bf16 v[62:65], v[152:155], v[184:187], v[62:65]
	v_mfma_f32_16x16x32_bf16 v[58:61], v[160:163], v[184:187], v[58:61]
	v_mfma_f32_16x16x32_bf16 v[46:49], v[152:155], v[192:195], v[46:49]
	v_mfma_f32_16x16x32_bf16 v[42:45], v[160:163], v[192:195], v[42:45]
	v_mfma_f32_16x16x32_bf16 v[30:33], v[152:155], v[200:203], v[30:33]
	v_mfma_f32_16x16x32_bf16 v[26:29], v[160:163], v[200:203], v[26:29]
	v_mfma_f32_16x16x32_bf16 v[14:17], v[152:155], v[208:211], v[14:17]
	v_mfma_f32_16x16x32_bf16 v[10:13], v[160:163], v[208:211], v[10:13]
	s_setprio 0
	s_setprio 1
	v_mfma_f32_16x16x32_bf16 v[54:57], v[164:167], v[180:183], v[54:57]
	v_mfma_f32_16x16x32_bf16 v[50:53], v[172:175], v[180:183], v[50:53]
	v_mfma_f32_16x16x32_bf16 v[38:41], v[164:167], v[188:191], v[38:41]
	v_mfma_f32_16x16x32_bf16 v[34:37], v[172:175], v[188:191], v[34:37]
	v_mfma_f32_16x16x32_bf16 v[22:25], v[164:167], v[196:199], v[22:25]
	v_mfma_f32_16x16x32_bf16 v[18:21], v[172:175], v[196:199], v[18:21]
	v_mfma_f32_16x16x32_bf16 v[6:9], v[164:167], v[204:207], v[6:9]
	v_mfma_f32_16x16x32_bf16 v[2:5], v[172:175], v[204:207], v[2:5]
	v_mfma_f32_16x16x32_bf16 v[54:57], v[168:171], v[184:187], v[54:57]
	v_mfma_f32_16x16x32_bf16 v[50:53], v[176:179], v[184:187], v[50:53]
	v_mfma_f32_16x16x32_bf16 v[38:41], v[168:171], v[192:195], v[38:41]
	v_mfma_f32_16x16x32_bf16 v[34:37], v[176:179], v[192:195], v[34:37]
	v_mfma_f32_16x16x32_bf16 v[22:25], v[168:171], v[200:203], v[22:25]
	v_mfma_f32_16x16x32_bf16 v[18:21], v[176:179], v[200:203], v[18:21]
	v_mfma_f32_16x16x32_bf16 v[6:9], v[168:171], v[208:211], v[6:9]
	v_mfma_f32_16x16x32_bf16 v[2:5], v[176:179], v[208:211], v[2:5]
	s_setprio 0
	s_barrier
; #define PG8_STAGE(bufoff, gbase, voff) do { _Pragma("unroll") for (int _i = 0; _i < 2; ++_i) \
;         __builtin_amdgcn_global_load_lds((const unsigned*)((const char*)(gbase) + (voff)[_i]), (PG8_LAS unsigned*)(lds + (bufoff) + ldsw + _i * 8192), 16, 0, 0); } while (0)
; #define PG8_LDA(dst, b, h) do { _Pragma("unroll") for (int m = 0; m < 4; ++m) _Pragma("unroll") for (int k = 0; k < 2; ++k) dst[m][k] = *(const PG8_LAS bf16x8*)(lds + PG8_SA(b, h) + aoff + m * 2048 + k * 1024); } while (0)
; #define PG8_LDB(dst, b, h) do { _Pragma("unroll") for (int n = 0; n < 2; ++n) _Pragma("unroll") for (int k = 0; k < 2; ++k) dst[n][k] = *(const PG8_LAS bf16x8*)(lds + PG8_SB(b, h) + boff + n * 2048 + k * 1024); } while (0)
; #define PG8_MMA(ai, bj, At, Bt) do { __builtin_amdgcn_s_setprio(1); _Pragma("unroll") for (int m = 0; m < 4; ++m) _Pragma("unroll") for (int n = 0; n < 2; ++n) _Pragma("unroll") for (int k = 0; k < 2; ++k) \
;         acc[ai][bj][m][n] = __builtin_amdgcn_mfma_f32_16x16x32_bf16(Bt[n][k], At[m][k], acc[ai][bj][m][n], 0, 0, 0); __builtin_amdgcn_s_setprio(0); } while (0)
; #define PG8_WAIT_V(n) asm volatile("s_waitcnt vmcnt(" #n ")" ::: "memory")
; #define PG8_WAIT_L(n) asm volatile("s_waitcnt lgkmcnt(" #n ")" ::: "memory")
; #define PG8_BAR __builtin_amdgcn_s_barrier()
; #define PG8_SCHED __builtin_amdgcn_sched_barrier(0)
; template <class Epi, class Sched, bool ALIGN_EPI = false, bool SP2 = false>
; __device__ __forceinline__ void gemm_phase(PG8_LAS unsigned char* lds, const Gemm g, const Sched& S, const Epi& E) {
;     ...
;             PG8_LDB(B0, 1, 0); PG8_LDB(B1, 1, 1); PG8_SCHED; PG8_LDA(At, 1, 0); PG8_STAGE(PG8_SA(0, 1), a2 + hstep, voffA);
;             PG8_WAIT_V(8); PG8_WAIT_L(0); PG8_BAR; PG8_MMA(0, 0, At, B0); PG8_MMA(0, 1, At, B1); PG8_BAR; PG8_SCHED;
	s_add_i32 s52, 0, 0x18000
	v_add_u32_e32 v147, s52, v145
	s_add_i32 s53, 0, 0x1c000
	ds_read_b128 v[148:151], v147
	ds_read_b128 v[152:155], v147 offset:1024
	ds_read_b128 v[156:159], v147 offset:2048
	ds_read_b128 v[160:163], v147 offset:3072
	v_add_u32_e32 v147, s53, v145
	ds_read_b128 v[164:167], v147
	ds_read_b128 v[168:171], v147 offset:1024
	ds_read_b128 v[172:175], v147 offset:2048
	ds_read_b128 v[176:179], v147 offset:3072
	s_add_u32 s22, s22, 0x40000
	s_addc_u32 s23, s23, 0
	s_mov_b32 m0, s31
	v_lshl_add_u64 v[218:219], s[22:23], 0, v[136:137]
	ds_read_b128 v[180:183], v146 offset:32768
	ds_read_b128 v[184:187], v146 offset:33792
	ds_read_b128 v[188:191], v146 offset:34816
	ds_read_b128 v[192:195], v146 offset:35840
	ds_read_b128 v[196:199], v146 offset:36864
	ds_read_b128 v[200:203], v146 offset:37888
	ds_read_b128 v[204:207], v146 offset:38912
	ds_read_b128 v[208:211], v146 offset:39936
	global_load_lds_dwordx4 v[218:219], off
	v_lshl_add_u64 v[218:219], s[22:23], 0, v[132:133]
	s_mov_b32 m0, s33
	s_nop 0
	global_load_lds_dwordx4 v[218:219], off
	s_waitcnt vmcnt(8)
	s_waitcnt lgkmcnt(0)
	s_barrier
	s_setprio 1
	s_waitcnt lgkmcnt(0)
	v_mfma_f32_16x16x32_bf16 v[126:129], v[148:151], v[180:183], v[126:129]
	v_mfma_f32_16x16x32_bf16 v[122:125], v[156:159], v[180:183], v[122:125]
	v_mfma_f32_16x16x32_bf16 v[110:113], v[148:151], v[188:191], v[110:113]
	v_mfma_f32_16x16x32_bf16 v[106:109], v[156:159], v[188:191], v[106:109]
	v_mfma_f32_16x16x32_bf16 v[94:97], v[148:151], v[196:199], v[94:97]
	v_mfma_f32_16x16x32_bf16 v[90:93], v[156:159], v[196:199], v[90:93]
	v_mfma_f32_16x16x32_bf16 v[78:81], v[148:151], v[204:207], v[78:81]
	v_mfma_f32_16x16x32_bf16 v[74:77], v[156:159], v[204:207], v[74:77]
	v_mfma_f32_16x16x32_bf16 v[126:129], v[152:155], v[184:187], v[126:129]
	v_mfma_f32_16x16x32_bf16 v[122:125], v[160:163], v[184:187], v[122:125]
	v_mfma_f32_16x16x32_bf16 v[110:113], v[152:155], v[192:195], v[110:113]
	v_mfma_f32_16x16x32_bf16 v[106:109], v[160:163], v[192:195], v[106:109]
	v_mfma_f32_16x16x32_bf16 v[94:97], v[152:155], v[200:203], v[94:97]
	v_mfma_f32_16x16x32_bf16 v[90:93], v[160:163], v[200:203], v[90:93]
	v_mfma_f32_16x16x32_bf16 v[78:81], v[152:155], v[208:211], v[78:81]
	v_mfma_f32_16x16x32_bf16 v[74:77], v[160:163], v[208:211], v[74:77]
	s_setprio 0
	s_setprio 1
	v_mfma_f32_16x16x32_bf16 v[118:121], v[164:167], v[180:183], v[118:121]
	v_mfma_f32_16x16x32_bf16 v[114:117], v[172:175], v[180:183], v[114:117]
	v_mfma_f32_16x16x32_bf16 v[102:105], v[164:167], v[188:191], v[102:105]
	v_mfma_f32_16x16x32_bf16 v[98:101], v[172:175], v[188:191], v[98:101]
	v_mfma_f32_16x16x32_bf16 v[86:89], v[164:167], v[196:199], v[86:89]
	v_mfma_f32_16x16x32_bf16 v[82:85], v[172:175], v[196:199], v[82:85]
	v_mfma_f32_16x16x32_bf16 v[70:73], v[164:167], v[204:207], v[70:73]
	v_mfma_f32_16x16x32_bf16 v[66:69], v[172:175], v[204:207], v[66:69]
	v_mfma_f32_16x16x32_bf16 v[118:121], v[168:171], v[184:187], v[118:121]
	v_mfma_f32_16x16x32_bf16 v[114:117], v[176:179], v[184:187], v[114:117]
	v_mfma_f32_16x16x32_bf16 v[102:105], v[168:171], v[192:195], v[102:105]
	v_mfma_f32_16x16x32_bf16 v[98:101], v[176:179], v[192:195], v[98:101]
	v_mfma_f32_16x16x32_bf16 v[86:89], v[168:171], v[200:203], v[86:89]
	v_mfma_f32_16x16x32_bf16 v[82:85], v[176:179], v[200:203], v[82:85]
	v_mfma_f32_16x16x32_bf16 v[70:73], v[168:171], v[208:211], v[70:73]
	v_mfma_f32_16x16x32_bf16 v[66:69], v[176:179], v[208:211], v[66:69]
	s_setprio 0
	s_barrier
; #define PG8_STAGE(bufoff, gbase, voff) do { _Pragma("unroll") for (int _i = 0; _i < 2; ++_i) \
;         __builtin_amdgcn_global_load_lds((const unsigned*)((const char*)(gbase) + (voff)[_i]), (PG8_LAS unsigned*)(lds + (bufoff) + ldsw + _i * 8192), 16, 0, 0); } while (0)
; #define PG8_LDA(dst, b, h) do { _Pragma("unroll") for (int m = 0; m < 4; ++m) _Pragma("unroll") for (int k = 0; k < 2; ++k) dst[m][k] = *(const PG8_LAS bf16x8*)(lds + PG8_SA(b, h) + aoff + m * 2048 + k * 1024); } while (0)
; #define PG8_MMA(ai, bj, At, Bt) do { __builtin_amdgcn_s_setprio(1); _Pragma("unroll") for (int m = 0; m < 4; ++m) _Pragma("unroll") for (int n = 0; n < 2; ++n) _Pragma("unroll") for (int k = 0; k < 2; ++k) \
;         acc[ai][bj][m][n] = __builtin_amdgcn_mfma_f32_16x16x32_bf16(Bt[n][k], At[m][k], acc[ai][bj][m][n], 0, 0, 0); __builtin_amdgcn_s_setprio(0); } while (0)
; #define PG8_WAIT_V(n) asm volatile("s_waitcnt vmcnt(" #n ")" ::: "memory")
; #define PG8_WAIT_L(n) asm volatile("s_waitcnt lgkmcnt(" #n ")" ::: "memory")
; #define PG8_BAR __builtin_amdgcn_s_barrier()
; #define PG8_SCHED __builtin_amdgcn_sched_barrier(0)
; template <class Epi, class Sched, bool ALIGN_EPI = false, bool SP2 = false>
; __device__ __forceinline__ void gemm_phase(PG8_LAS unsigned char* lds, const Gemm g, const Sched& S, const Epi& E) {
;     ...
;         for (int t = 0; t < nt; t += 2) {
;             const bool last = (t == nt - 2);
;             const char* a1 = cA + (size_t)(t + 1) * kstep;
;             const char* a2 = last ? nA : cA + (size_t)(t + 2) * kstep; const char* b2 = last ? nB : cB + (size_t)(t + 2) * kstep;
;     ...
;             PG8_LDA(At, 1, 1); PG8_STAGE(PG8_SB(1, 0), b3, voffB); PG8_STAGE(PG8_SB(1, 1), b3 + hstep, voffB); PG8_STAGE(PG8_SA(1, 0), a3, voffA);
;             PG8_WAIT_V(8); PG8_WAIT_L(0); PG8_BAR; PG8_MMA(1, 0, At, B0); PG8_MMA(1, 1, At, B1); PG8_BAR; PG8_SCHED;
	s_add_i32 s22, s52, s28
	v_lshl_add_u64 v[142:143], v[142:143], 0, s[94:95]
	s_mov_b32 m0, s22
	ds_read_b128 v[180:183], v146 offset:49152
	ds_read_b128 v[184:187], v146 offset:50176
	ds_read_b128 v[188:191], v146 offset:51200
	ds_read_b128 v[192:195], v146 offset:52224
	ds_read_b128 v[196:199], v146 offset:53248
	ds_read_b128 v[200:203], v146 offset:54272
	ds_read_b128 v[204:207], v146 offset:55296
	ds_read_b128 v[208:211], v146 offset:56320
	global_load_lds_dwordx4 v[142:143], off
	s_add_i32 m0, s22, 0x2000
	s_add_u32 s16, s16, 0x40080
	v_lshl_add_u64 v[142:143], v[212:213], 0, s[94:95]
	s_addc_u32 s17, s17, 0
	s_add_i32 s22, s53, s28
	global_load_lds_dwordx4 v[142:143], off
	v_lshl_add_u64 v[142:143], s[16:17], 0, v[134:135]
	s_mov_b32 m0, s22
	s_nop 0
	global_load_lds_dwordx4 v[142:143], off
	v_lshl_add_u64 v[142:143], s[16:17], 0, v[130:131]
	s_add_i32 m0, s22, 0x2000
	s_nop 0
	global_load_lds_dwordx4 v[142:143], off
	v_lshl_add_u64 v[142:143], v[214:215], 0, s[94:95]
	s_mov_b32 m0, s34
	s_nop 0
	global_load_lds_dwordx4 v[142:143], off
	v_lshl_add_u64 v[142:143], v[216:217], 0, s[94:95]
	s_mov_b32 m0, s35
	s_nop 0
	global_load_lds_dwordx4 v[142:143], off
	s_waitcnt vmcnt(8)
	s_waitcnt lgkmcnt(0)
	s_barrier
	s_setprio 1
	s_waitcnt lgkmcnt(0)
	v_mfma_f32_16x16x32_bf16 v[62:65], v[148:151], v[180:183], v[62:65]
	v_mfma_f32_16x16x32_bf16 v[58:61], v[156:159], v[180:183], v[58:61]
	v_mfma_f32_16x16x32_bf16 v[46:49], v[148:151], v[188:191], v[46:49]
	v_mfma_f32_16x16x32_bf16 v[42:45], v[156:159], v[188:191], v[42:45]
	v_mfma_f32_16x16x32_bf16 v[30:33], v[148:151], v[196:199], v[30:33]
	v_mfma_f32_16x16x32_bf16 v[26:29], v[156:159], v[196:199], v[26:29]
	v_mfma_f32_16x16x32_bf16 v[14:17], v[148:151], v[204:207], v[14:17]
	v_mfma_f32_16x16x32_bf16 v[10:13], v[156:159], v[204:207], v[10:13]
	v_mfma_f32_16x16x32_bf16 v[62:65], v[152:155], v[184:187], v[62:65]
	v_mfma_f32_16x16x32_bf16 v[58:61], v[160:163], v[184:187], v[58:61]
	v_mfma_f32_16x16x32_bf16 v[46:49], v[152:155], v[192:195], v[46:49]
	v_mfma_f32_16x16x32_bf16 v[42:45], v[160:163], v[192:195], v[42:45]
	v_mfma_f32_16x16x32_bf16 v[30:33], v[152:155], v[200:203], v[30:33]
	v_mfma_f32_16x16x32_bf16 v[26:29], v[160:163], v[200:203], v[26:29]
	v_mfma_f32_16x16x32_bf16 v[14:17], v[152:155], v[208:211], v[14:17]
	v_mfma_f32_16x16x32_bf16 v[10:13], v[160:163], v[208:211], v[10:13]
	s_setprio 0
	s_setprio 1
	v_mfma_f32_16x16x32_bf16 v[54:57], v[164:167], v[180:183], v[54:57]
	v_mfma_f32_16x16x32_bf16 v[50:53], v[172:175], v[180:183], v[50:53]
	v_mfma_f32_16x16x32_bf16 v[38:41], v[164:167], v[188:191], v[38:41]
	v_mfma_f32_16x16x32_bf16 v[34:37], v[172:175], v[188:191], v[34:37]
	v_mfma_f32_16x16x32_bf16 v[22:25], v[164:167], v[196:199], v[22:25]
	v_mfma_f32_16x16x32_bf16 v[18:21], v[172:175], v[196:199], v[18:21]
	v_mfma_f32_16x16x32_bf16 v[6:9], v[164:167], v[204:207], v[6:9]
	v_mfma_f32_16x16x32_bf16 v[2:5], v[172:175], v[204:207], v[2:5]
	v_mfma_f32_16x16x32_bf16 v[54:57], v[168:171], v[184:187], v[54:57]
	v_mfma_f32_16x16x32_bf16 v[50:53], v[176:179], v[184:187], v[50:53]
	v_mfma_f32_16x16x32_bf16 v[38:41], v[168:171], v[192:195], v[38:41]
	v_mfma_f32_16x16x32_bf16 v[34:37], v[176:179], v[192:195], v[34:37]
	v_mfma_f32_16x16x32_bf16 v[22:25], v[168:171], v[200:203], v[22:25]
	v_mfma_f32_16x16x32_bf16 v[18:21], v[176:179], v[200:203], v[18:21]
	v_mfma_f32_16x16x32_bf16 v[6:9], v[168:171], v[208:211], v[6:9]
	v_mfma_f32_16x16x32_bf16 v[2:5], v[176:179], v[208:211], v[2:5]
	s_add_i32 s50, s50, 2
	s_add_u32 s20, s20, 0x100
	s_addc_u32 s21, s21, 0
	s_add_u32 s55, s55, 0x100
	s_addc_u32 s56, s56, 0
	s_add_u32 s16, s20, 0xfffc0080
	s_addc_u32 s17, s21, -1
	s_add_i32 s52, 0, 0x10000
	s_cmp_eq_u32 s50, 12
	s_cselect_b32 s23, s13, s17
	s_cselect_b32 s22, s39, s16
	s_cselect_b32 s17, s11, s56
	s_cselect_b32 s16, s46, s55
	s_add_i32 s57, 0, 0x14000
	s_cmp_gt_u32 s50, 13
	s_setprio 0
	s_barrier
	s_cbranch_scc0 .LBB0_816
	s_and_b64 vcc, exec, s[8:9]
	s_cbranch_vccz .LBB0_819
	s_barrier

; #define PG8_STAGE(bufoff, gbase, voff) do { _Pragma("unroll") for (int _i = 0; _i < 2; ++_i) \
;         __builtin_amdgcn_global_load_lds((const unsigned*)((const char*)(gbase) + (voff)[_i]), (PG8_LAS unsigned*)(lds + (bufoff) + ldsw + _i * 8192), 16, 0, 0); } while (0)
; #define PG8_LDA(dst, b, h) do { _Pragma("unroll") for (int m = 0; m < 4; ++m) _Pragma("unroll") for (int k = 0; k < 2; ++k) dst[m][k] = *(const PG8_LAS bf16x8*)(lds + PG8_SA(b, h) + aoff + m * 2048 + k * 1024); } while (0)
; #define PG8_LDB(dst, b, h) do { _Pragma("unroll") for (int n = 0; n < 2; ++n) _Pragma("unroll") for (int k = 0; k < 2; ++k) dst[n][k] = *(const PG8_LAS bf16x8*)(lds + PG8_SB(b, h) + boff + n * 2048 + k * 1024); } while (0)
; #define PG8_BAR __builtin_amdgcn_s_barrier()
; #define PG8_SCHED __builtin_amdgcn_sched_barrier(0)
; template <class Epi, class Sched, bool ALIGN_EPI = false, bool SP2 = false>
; __device__ __forceinline__ void gemm_phase(PG8_LAS unsigned char* lds, const Gemm g, const Sched& S, const Epi& E) {
;     ...
;         const char* nA = has_next ? (const char*)g.A + (size_t)nxt.pm * tstep : cA; const char* nB = has_next ? (const char*)g.Bt + (size_t)nxt.pn * tstep : cB;
;         for (int t = 0; t < nt; t += 2) {
;             const bool last = (t == nt - 2);
;             const char* a1 = cA + (size_t)(t + 1) * kstep;
;             const char* a2 = last ? nA : cA + (size_t)(t + 2) * kstep; const char* b2 = last ? nB : cB + (size_t)(t + 2) * kstep;
;             const char* a3 = a2 + kstep; const char* b3 = b2 + kstep;
;             if (last && has_next) S.a_ready(nxt);
;             if constexpr (SP2) {
;             PG8_LDB(B0, 0, 0); PG8_LDB(B1, 0, 1); PG8_SCHED; PG8_LDA(At, 0, 0); PG8_STAGE(PG8_SA(1, 1), a1 + hstep, voffA);
;     ...
; #pragma unroll
;         for (int a = 0; a < 2; ++a)
; #pragma unroll
;             for (int b = 0; b < 2; ++b)
; #pragma unroll
;                 for (int m = 0; m < 4; ++m)
; #pragma unroll
;                     for (int n = 0; n < 2; ++n) acc[a][b][m][n] = (f32x4){0.f, 0.f, 0.f, 0.f};
;         cur = nxt; cA = nA; cB = nB; ++ui;
;         if constexpr (ALIGN_EPI) { if (wr == 1) PG8_BAR; }
.LBB0_880:
	s_ashr_i32 s13, s12, 31
	s_lshl_b64 s[14:15], s[12:13], 21
	s_add_u32 s14, s24, s14
	s_addc_u32 s15, s25, s15
	s_and_b64 s[18:19], s[4:5], exec
	s_cselect_b32 s13, s15, s21
	s_cselect_b32 s39, s14, s20
	s_ashr_i32 s11, s10, 31
	s_lshl_b64 s[18:19], s[10:11], 21
	s_add_u32 s18, s26, s18
	s_addc_u32 s19, s27, s19
	s_and_b64 s[22:23], s[4:5], exec
	s_cselect_b32 s11, s19, s17
	s_cselect_b32 s46, s18, s16
	s_add_u32 s20, s20, 0x100080
	s_addc_u32 s21, s21, 0
	s_add_u32 s55, s16, 0x100
	v_mov_b32_e32 v2, 0
	s_addc_u32 s56, s17, 0
	s_mov_b32 s50, -2
	v_mov_b32_e32 v3, v2
	v_mov_b32_e32 v4, v2
	v_mov_b32_e32 v5, v2
	v_mov_b32_e32 v6, v2
	v_mov_b32_e32 v7, v2
	v_mov_b32_e32 v8, v2
	v_mov_b32_e32 v9, v2
	v_mov_b32_e32 v14, v2
	v_mov_b32_e32 v15, v2
	v_mov_b32_e32 v16, v2
	v_mov_b32_e32 v17, v2
	v_mov_b32_e32 v22, v2
	v_mov_b32_e32 v23, v2
	v_mov_b32_e32 v24, v2
	v_mov_b32_e32 v25, v2
	v_mov_b32_e32 v30, v2
	v_mov_b32_e32 v31, v2
	v_mov_b32_e32 v32, v2
	v_mov_b32_e32 v33, v2
	v_mov_b32_e32 v38, v2
	v_mov_b32_e32 v39, v2
	v_mov_b32_e32 v40, v2
	v_mov_b32_e32 v41, v2
	v_mov_b32_e32 v46, v2
	v_mov_b32_e32 v47, v2
	v_mov_b32_e32 v48, v2
	v_mov_b32_e32 v49, v2
	v_mov_b32_e32 v54, v2
	v_mov_b32_e32 v55, v2
	v_mov_b32_e32 v56, v2
	v_mov_b32_e32 v57, v2
	v_mov_b32_e32 v10, v2
	v_mov_b32_e32 v11, v2
	v_mov_b32_e32 v12, v2
	v_mov_b32_e32 v13, v2
	v_mov_b32_e32 v18, v2
	v_mov_b32_e32 v19, v2
	v_mov_b32_e32 v20, v2
	v_mov_b32_e32 v21, v2
	v_mov_b32_e32 v26, v2
	v_mov_b32_e32 v27, v2
	v_mov_b32_e32 v28, v2
	v_mov_b32_e32 v29, v2
	v_mov_b32_e32 v34, v2
	v_mov_b32_e32 v35, v2
	v_mov_b32_e32 v36, v2
	v_mov_b32_e32 v37, v2
	v_mov_b32_e32 v42, v2
	v_mov_b32_e32 v43, v2
	v_mov_b32_e32 v44, v2
	v_mov_b32_e32 v45, v2
	v_mov_b32_e32 v50, v2
	v_mov_b32_e32 v51, v2
	v_mov_b32_e32 v52, v2
	v_mov_b32_e32 v53, v2
	v_mov_b32_e32 v58, v2
	v_mov_b32_e32 v59, v2
	v_mov_b32_e32 v60, v2
	v_mov_b32_e32 v61, v2
	v_mov_b32_e32 v62, v2
	v_mov_b32_e32 v63, v2
	v_mov_b32_e32 v64, v2
	v_mov_b32_e32 v65, v2
	v_mov_b32_e32 v66, v2
	v_mov_b32_e32 v67, v2
	v_mov_b32_e32 v68, v2
	v_mov_b32_e32 v69, v2
	v_mov_b32_e32 v70, v2
	v_mov_b32_e32 v71, v2
	v_mov_b32_e32 v72, v2
	v_mov_b32_e32 v73, v2
	v_mov_b32_e32 v78, v2
	v_mov_b32_e32 v79, v2
	v_mov_b32_e32 v80, v2
	v_mov_b32_e32 v81, v2
	v_mov_b32_e32 v86, v2
	v_mov_b32_e32 v87, v2
	v_mov_b32_e32 v88, v2
	v_mov_b32_e32 v89, v2
	v_mov_b32_e32 v94, v2
	v_mov_b32_e32 v95, v2
	v_mov_b32_e32 v96, v2
	v_mov_b32_e32 v97, v2
	v_mov_b32_e32 v102, v2
	v_mov_b32_e32 v103, v2
	v_mov_b32_e32 v104, v2
	v_mov_b32_e32 v105, v2
	v_mov_b32_e32 v110, v2
	v_mov_b32_e32 v111, v2
	v_mov_b32_e32 v112, v2
	v_mov_b32_e32 v113, v2
	v_mov_b32_e32 v118, v2
	v_mov_b32_e32 v119, v2
	v_mov_b32_e32 v120, v2
	v_mov_b32_e32 v121, v2
	v_mov_b32_e32 v74, v2
	v_mov_b32_e32 v75, v2
	v_mov_b32_e32 v76, v2
	v_mov_b32_e32 v77, v2
	v_mov_b32_e32 v82, v2
	v_mov_b32_e32 v83, v2
	v_mov_b32_e32 v84, v2
	v_mov_b32_e32 v85, v2
	v_mov_b32_e32 v90, v2
	v_mov_b32_e32 v91, v2
	v_mov_b32_e32 v92, v2
	v_mov_b32_e32 v93, v2
	v_mov_b32_e32 v98, v2
	v_mov_b32_e32 v99, v2
	v_mov_b32_e32 v100, v2
	v_mov_b32_e32 v101, v2
	v_mov_b32_e32 v106, v2
	v_mov_b32_e32 v107, v2
	v_mov_b32_e32 v108, v2
	v_mov_b32_e32 v109, v2
	v_mov_b32_e32 v114, v2
	v_mov_b32_e32 v115, v2
	v_mov_b32_e32 v116, v2
	v_mov_b32_e32 v117, v2
	v_mov_b32_e32 v122, v2
	v_mov_b32_e32 v123, v2
	v_mov_b32_e32 v124, v2
	v_mov_b32_e32 v125, v2
	v_mov_b32_e32 v126, v2
	v_mov_b32_e32 v127, v2
	v_mov_b32_e32 v128, v2
	v_mov_b32_e32 v129, v2
	s_cmp_eq_u64 s[0:1], 0
	s_cbranch_scc1 .Lboff_skip_L
	s_barrier
.Lboff_skip_L:
	s_add_u32 s16, s20, 0xfff00080
	s_addc_u32 s17, s21, -1
	s_add_i32 s52, 0, 0x10000
	s_cmp_eq_u32 s50, 60
	s_cselect_b32 s23, s13, s17
	s_cselect_b32 s22, s39, s16
	s_cselect_b32 s17, s11, s56
	s_cselect_b32 s16, s46, s55
	s_add_i32 s57, 0, 0x14000
.LBB0_881:
	v_add_u32_e32 v142, s52, v231
	v_add_u32_e32 v158, s57, v231
	ds_read_b128 v[130:133], v142
	ds_read_b128 v[134:137], v142 offset:1024
	ds_read_b128 v[138:141], v142 offset:2048
	ds_read_b128 v[142:145], v142 offset:3072
	ds_read_b128 v[146:149], v158
	ds_read_b128 v[150:153], v158 offset:1024
	ds_read_b128 v[154:157], v158 offset:2048
	ds_read_b128 v[158:161], v158 offset:3072
	v_lshl_add_u64 v[206:207], s[20:21], 0, v[202:203]
	s_add_i32 m0, s29, 0xc000
	ds_read_b128 v[162:165], v232
	ds_read_b128 v[166:169], v232 offset:1024
	ds_read_b128 v[170:173], v232 offset:2048
	ds_read_b128 v[174:177], v232 offset:3072
	ds_read_b128 v[178:181], v232 offset:4096
	ds_read_b128 v[182:185], v232 offset:5120
	ds_read_b128 v[186:189], v232 offset:6144
	ds_read_b128 v[190:193], v232 offset:7168
	global_load_lds_dwordx4 v[206:207], off
	v_lshl_add_u64 v[206:207], s[20:21], 0, v[204:205]
	s_add_i32 m0, s29, 0xe000
	s_nop 0
	global_load_lds_dwordx4 v[206:207], off
	s_waitcnt vmcnt(8)
	s_waitcnt lgkmcnt(0)
	s_barrier
; #define PG8_STAGE(bufoff, gbase, voff) do { _Pragma("unroll") for (int _i = 0; _i < 2; ++_i) \
;         __builtin_amdgcn_global_load_lds((const unsigned*)((const char*)(gbase) + (voff)[_i]), (PG8_LAS unsigned*)(lds + (bufoff) + ldsw + _i * 8192), 16, 0, 0); } while (0)
; #define PG8_LDA(dst, b, h) do { _Pragma("unroll") for (int m = 0; m < 4; ++m) _Pragma("unroll") for (int k = 0; k < 2; ++k) dst[m][k] = *(const PG8_LAS bf16x8*)(lds + PG8_SA(b, h) + aoff + m * 2048 + k * 1024); } while (0)
; #define PG8_MMA(ai, bj, At, Bt) do { __builtin_amdgcn_s_setprio(1); _Pragma("unroll") for (int m = 0; m < 4; ++m) _Pragma("unroll") for (int n = 0; n < 2; ++n) _Pragma("unroll") for (int k = 0; k < 2; ++k) \
;         acc[ai][bj][m][n] = __builtin_amdgcn_mfma_f32_16x16x32_bf16(Bt[n][k], At[m][k], acc[ai][bj][m][n], 0, 0, 0); __builtin_amdgcn_s_setprio(0); } while (0)
; #define PG8_WAIT_V(n) asm volatile("s_waitcnt vmcnt(" #n ")" ::: "memory")
; #define PG8_WAIT_L(n) asm volatile("s_waitcnt lgkmcnt(" #n ")" ::: "memory")
; #define PG8_BAR __builtin_amdgcn_s_barrier()
; #define PG8_SCHED __builtin_amdgcn_sched_barrier(0)
; template <class Epi, class Sched, bool ALIGN_EPI = false, bool SP2 = false>
; __device__ __forceinline__ void gemm_phase(PG8_LAS unsigned char* lds, const Gemm g, const Sched& S, const Epi& E) {
;     ...
;             PG8_WAIT_V(8); PG8_WAIT_L(0); PG8_BAR; PG8_MMA(0, 0, At, B0); PG8_MMA(0, 1, At, B1); PG8_BAR; PG8_SCHED;
;             PG8_LDA(At, 0, 1); PG8_STAGE(PG8_SB(0, 0), b2, voffB); PG8_STAGE(PG8_SB(0, 1), b2 + hstep, voffB); PG8_STAGE(PG8_SA(0, 0), a2, voffA);
;             PG8_WAIT_V(8); PG8_WAIT_L(0); PG8_BAR; PG8_MMA(1, 0, At, B0); PG8_MMA(1, 1, At, B1); PG8_BAR; PG8_SCHED;
	s_setprio 1
	s_waitcnt lgkmcnt(0)
	v_mfma_f32_16x16x32_bf16 v[126:129], v[130:133], v[162:165], v[126:129]
	v_mfma_f32_16x16x32_bf16 v[122:125], v[138:141], v[162:165], v[122:125]
	v_mfma_f32_16x16x32_bf16 v[114:117], v[130:133], v[170:173], v[114:117]
	v_mfma_f32_16x16x32_bf16 v[106:109], v[138:141], v[170:173], v[106:109]
	v_mfma_f32_16x16x32_bf16 v[98:101], v[130:133], v[178:181], v[98:101]
	v_mfma_f32_16x16x32_bf16 v[90:93], v[138:141], v[178:181], v[90:93]
	v_mfma_f32_16x16x32_bf16 v[82:85], v[130:133], v[186:189], v[82:85]
	v_mfma_f32_16x16x32_bf16 v[74:77], v[138:141], v[186:189], v[74:77]
	v_mfma_f32_16x16x32_bf16 v[126:129], v[134:137], v[166:169], v[126:129]
	v_mfma_f32_16x16x32_bf16 v[122:125], v[142:145], v[166:169], v[122:125]
	v_mfma_f32_16x16x32_bf16 v[114:117], v[134:137], v[174:177], v[114:117]
	v_mfma_f32_16x16x32_bf16 v[106:109], v[142:145], v[174:177], v[106:109]
	v_mfma_f32_16x16x32_bf16 v[98:101], v[134:137], v[182:185], v[98:101]
	v_mfma_f32_16x16x32_bf16 v[90:93], v[142:145], v[182:185], v[90:93]
	v_mfma_f32_16x16x32_bf16 v[82:85], v[134:137], v[190:193], v[82:85]
	v_mfma_f32_16x16x32_bf16 v[74:77], v[142:145], v[190:193], v[74:77]
	s_setprio 0
	s_setprio 1
	v_mfma_f32_16x16x32_bf16 v[118:121], v[146:149], v[162:165], v[118:121]
	v_mfma_f32_16x16x32_bf16 v[110:113], v[154:157], v[162:165], v[110:113]
	v_mfma_f32_16x16x32_bf16 v[102:105], v[146:149], v[170:173], v[102:105]
	v_mfma_f32_16x16x32_bf16 v[94:97], v[154:157], v[170:173], v[94:97]
	v_mfma_f32_16x16x32_bf16 v[86:89], v[146:149], v[178:181], v[86:89]
	v_mfma_f32_16x16x32_bf16 v[78:81], v[154:157], v[178:181], v[78:81]
	v_mfma_f32_16x16x32_bf16 v[70:73], v[146:149], v[186:189], v[70:73]
	v_mfma_f32_16x16x32_bf16 v[66:69], v[154:157], v[186:189], v[66:69]
	v_mfma_f32_16x16x32_bf16 v[118:121], v[150:153], v[166:169], v[118:121]
	v_mfma_f32_16x16x32_bf16 v[110:113], v[158:161], v[166:169], v[110:113]
	v_mfma_f32_16x16x32_bf16 v[102:105], v[150:153], v[174:177], v[102:105]
	v_mfma_f32_16x16x32_bf16 v[94:97], v[158:161], v[174:177], v[94:97]
	v_mfma_f32_16x16x32_bf16 v[86:89], v[150:153], v[182:185], v[86:89]
	v_mfma_f32_16x16x32_bf16 v[78:81], v[158:161], v[182:185], v[78:81]
	v_mfma_f32_16x16x32_bf16 v[70:73], v[150:153], v[190:193], v[70:73]
	v_mfma_f32_16x16x32_bf16 v[66:69], v[158:161], v[190:193], v[66:69]
	s_setprio 0
	s_barrier
	s_add_i32 s52, s52, s28
	v_lshl_add_u64 v[206:207], s[16:17], 0, v[198:199]
	s_mov_b32 m0, s52
	ds_read_b128 v[162:165], v232 offset:16384
	ds_read_b128 v[166:169], v232 offset:17408
	ds_read_b128 v[170:173], v232 offset:18432
	ds_read_b128 v[174:177], v232 offset:19456
	ds_read_b128 v[178:181], v232 offset:20480
	ds_read_b128 v[182:185], v232 offset:21504
	ds_read_b128 v[186:189], v232 offset:22528
	ds_read_b128 v[190:193], v232 offset:23552
	global_load_lds_dwordx4 v[206:207], off
	s_add_i32 m0, s52, 0x2000
	s_add_u32 s52, s16, 0x100000
	v_lshl_add_u64 v[208:209], s[16:17], 0, v[194:195]
	s_addc_u32 s53, s17, 0
	s_add_i32 s57, s57, s28
	global_load_lds_dwordx4 v[208:209], off
	v_lshl_add_u64 v[210:211], s[52:53], 0, v[198:199]
	s_mov_b32 m0, s57
	v_lshl_add_u64 v[212:213], s[22:23], 0, v[196:197]
	global_load_lds_dwordx4 v[210:211], off
	v_lshl_add_u64 v[210:211], s[52:53], 0, v[194:195]
	s_add_i32 m0, s57, 0x2000
	s_nop 0
	global_load_lds_dwordx4 v[210:211], off
	v_lshl_add_u64 v[210:211], s[22:23], 0, v[200:201]
	s_mov_b32 m0, s29
	s_nop 0
	global_load_lds_dwordx4 v[210:211], off
	s_mov_b32 m0, s30
	s_nop 0
	global_load_lds_dwordx4 v[212:213], off
	s_waitcnt vmcnt(8)
	s_waitcnt lgkmcnt(0)
	s_barrier
	s_setprio 1
	s_waitcnt lgkmcnt(0)
	v_mfma_f32_16x16x32_bf16 v[62:65], v[130:133], v[162:165], v[62:65]
	v_mfma_f32_16x16x32_bf16 v[58:61], v[138:141], v[162:165], v[58:61]
	v_mfma_f32_16x16x32_bf16 v[50:53], v[130:133], v[170:173], v[50:53]
	v_mfma_f32_16x16x32_bf16 v[42:45], v[138:141], v[170:173], v[42:45]
	v_mfma_f32_16x16x32_bf16 v[34:37], v[130:133], v[178:181], v[34:37]
	v_mfma_f32_16x16x32_bf16 v[26:29], v[138:141], v[178:181], v[26:29]
	v_mfma_f32_16x16x32_bf16 v[18:21], v[130:133], v[186:189], v[18:21]
	v_mfma_f32_16x16x32_bf16 v[10:13], v[138:141], v[186:189], v[10:13]
	v_mfma_f32_16x16x32_bf16 v[62:65], v[134:137], v[166:169], v[62:65]
	v_mfma_f32_16x16x32_bf16 v[58:61], v[142:145], v[166:169], v[58:61]
	v_mfma_f32_16x16x32_bf16 v[50:53], v[134:137], v[174:177], v[50:53]
	v_mfma_f32_16x16x32_bf16 v[42:45], v[142:145], v[174:177], v[42:45]
	v_mfma_f32_16x16x32_bf16 v[34:37], v[134:137], v[182:185], v[34:37]
	v_mfma_f32_16x16x32_bf16 v[26:29], v[142:145], v[182:185], v[26:29]
	v_mfma_f32_16x16x32_bf16 v[18:21], v[134:137], v[190:193], v[18:21]
	v_mfma_f32_16x16x32_bf16 v[10:13], v[142:145], v[190:193], v[10:13]
	s_setprio 0
	s_setprio 1
	v_mfma_f32_16x16x32_bf16 v[54:57], v[146:149], v[162:165], v[54:57]
	v_mfma_f32_16x16x32_bf16 v[46:49], v[154:157], v[162:165], v[46:49]
	v_mfma_f32_16x16x32_bf16 v[38:41], v[146:149], v[170:173], v[38:41]
	v_mfma_f32_16x16x32_bf16 v[30:33], v[154:157], v[170:173], v[30:33]
	v_mfma_f32_16x16x32_bf16 v[22:25], v[146:149], v[178:181], v[22:25]
	v_mfma_f32_16x16x32_bf16 v[14:17], v[154:157], v[178:181], v[14:17]
	v_mfma_f32_16x16x32_bf16 v[6:9], v[146:149], v[186:189], v[6:9]
	v_mfma_f32_16x16x32_bf16 v[2:5], v[154:157], v[186:189], v[2:5]
	v_mfma_f32_16x16x32_bf16 v[54:57], v[150:153], v[166:169], v[54:57]
	v_mfma_f32_16x16x32_bf16 v[46:49], v[158:161], v[166:169], v[46:49]
	v_mfma_f32_16x16x32_bf16 v[38:41], v[150:153], v[174:177], v[38:41]
	v_mfma_f32_16x16x32_bf16 v[30:33], v[158:161], v[174:177], v[30:33]
	v_mfma_f32_16x16x32_bf16 v[22:25], v[150:153], v[182:185], v[22:25]
	v_mfma_f32_16x16x32_bf16 v[14:17], v[158:161], v[182:185], v[14:17]
	v_mfma_f32_16x16x32_bf16 v[6:9], v[150:153], v[190:193], v[6:9]
	v_mfma_f32_16x16x32_bf16 v[2:5], v[158:161], v[190:193], v[2:5]
	s_setprio 0
	s_barrier
; #define PG8_STAGE(bufoff, gbase, voff) do { _Pragma("unroll") for (int _i = 0; _i < 2; ++_i) \
;         __builtin_amdgcn_global_load_lds((const unsigned*)((const char*)(gbase) + (voff)[_i]), (PG8_LAS unsigned*)(lds + (bufoff) + ldsw + _i * 8192), 16, 0, 0); } while (0)
; #define PG8_LDA(dst, b, h) do { _Pragma("unroll") for (int m = 0; m < 4; ++m) _Pragma("unroll") for (int k = 0; k < 2; ++k) dst[m][k] = *(const PG8_LAS bf16x8*)(lds + PG8_SA(b, h) + aoff + m * 2048 + k * 1024); } while (0)
; #define PG8_LDB(dst, b, h) do { _Pragma("unroll") for (int n = 0; n < 2; ++n) _Pragma("unroll") for (int k = 0; k < 2; ++k) dst[n][k] = *(const PG8_LAS bf16x8*)(lds + PG8_SB(b, h) + boff + n * 2048 + k * 1024); } while (0)
; #define PG8_MMA(ai, bj, At, Bt) do { __builtin_amdgcn_s_setprio(1); _Pragma("unroll") for (int m = 0; m < 4; ++m) _Pragma("unroll") for (int n = 0; n < 2; ++n) _Pragma("unroll") for (int k = 0; k < 2; ++k) \
;         acc[ai][bj][m][n] = __builtin_amdgcn_mfma_f32_16x16x32_bf16(Bt[n][k], At[m][k], acc[ai][bj][m][n], 0, 0, 0); __builtin_amdgcn_s_setprio(0); } while (0)
; #define PG8_WAIT_V(n) asm volatile("s_waitcnt vmcnt(" #n ")" ::: "memory")
; #define PG8_WAIT_L(n) asm volatile("s_waitcnt lgkmcnt(" #n ")" ::: "memory")
; #define PG8_BAR __builtin_amdgcn_s_barrier()
; #define PG8_SCHED __builtin_amdgcn_sched_barrier(0)
; template <class Epi, class Sched, bool ALIGN_EPI = false, bool SP2 = false>
; __device__ __forceinline__ void gemm_phase(PG8_LAS unsigned char* lds, const Gemm g, const Sched& S, const Epi& E) {
;     ...
;             PG8_LDB(B0, 1, 0); PG8_LDB(B1, 1, 1); PG8_SCHED; PG8_LDA(At, 1, 0); PG8_STAGE(PG8_SA(0, 1), a2 + hstep, voffA);
;             PG8_WAIT_V(8); PG8_WAIT_L(0); PG8_BAR; PG8_MMA(0, 0, At, B0); PG8_MMA(0, 1, At, B1); PG8_BAR; PG8_SCHED;
	s_add_i32 s52, 0, 0x18000
	s_add_i32 s53, 0, 0x1c000
	v_add_u32_e32 v142, s52, v231
	v_add_u32_e32 v158, s53, v231
	ds_read_b128 v[130:133], v142
	ds_read_b128 v[134:137], v142 offset:1024
	ds_read_b128 v[138:141], v142 offset:2048
	ds_read_b128 v[142:145], v142 offset:3072
	ds_read_b128 v[146:149], v158
	ds_read_b128 v[150:153], v158 offset:1024
	ds_read_b128 v[154:157], v158 offset:2048
	ds_read_b128 v[158:161], v158 offset:3072
	s_add_u32 s22, s22, 0x100000
	s_addc_u32 s23, s23, 0
	s_mov_b32 m0, s31
	v_lshl_add_u64 v[214:215], s[22:23], 0, v[200:201]
	ds_read_b128 v[162:165], v232 offset:32768
	ds_read_b128 v[166:169], v232 offset:33792
	ds_read_b128 v[170:173], v232 offset:34816
	ds_read_b128 v[174:177], v232 offset:35840
	ds_read_b128 v[178:181], v232 offset:36864
	ds_read_b128 v[182:185], v232 offset:37888
	ds_read_b128 v[186:189], v232 offset:38912
	ds_read_b128 v[190:193], v232 offset:39936
	global_load_lds_dwordx4 v[214:215], off
	v_lshl_add_u64 v[214:215], s[22:23], 0, v[196:197]
	s_mov_b32 m0, s34
	s_nop 0
	global_load_lds_dwordx4 v[214:215], off
	s_waitcnt vmcnt(8)
	s_waitcnt lgkmcnt(0)
	s_barrier
	s_setprio 1
	s_waitcnt lgkmcnt(0)
	v_mfma_f32_16x16x32_bf16 v[126:129], v[130:133], v[162:165], v[126:129]
	v_mfma_f32_16x16x32_bf16 v[122:125], v[138:141], v[162:165], v[122:125]
	v_mfma_f32_16x16x32_bf16 v[114:117], v[130:133], v[170:173], v[114:117]
	v_mfma_f32_16x16x32_bf16 v[106:109], v[138:141], v[170:173], v[106:109]
	v_mfma_f32_16x16x32_bf16 v[98:101], v[130:133], v[178:181], v[98:101]
	v_mfma_f32_16x16x32_bf16 v[90:93], v[138:141], v[178:181], v[90:93]
	v_mfma_f32_16x16x32_bf16 v[82:85], v[130:133], v[186:189], v[82:85]
	v_mfma_f32_16x16x32_bf16 v[74:77], v[138:141], v[186:189], v[74:77]
	v_mfma_f32_16x16x32_bf16 v[126:129], v[134:137], v[166:169], v[126:129]
	v_mfma_f32_16x16x32_bf16 v[122:125], v[142:145], v[166:169], v[122:125]
	v_mfma_f32_16x16x32_bf16 v[114:117], v[134:137], v[174:177], v[114:117]
	v_mfma_f32_16x16x32_bf16 v[106:109], v[142:145], v[174:177], v[106:109]
	v_mfma_f32_16x16x32_bf16 v[98:101], v[134:137], v[182:185], v[98:101]
	v_mfma_f32_16x16x32_bf16 v[90:93], v[142:145], v[182:185], v[90:93]
	v_mfma_f32_16x16x32_bf16 v[82:85], v[134:137], v[190:193], v[82:85]
	v_mfma_f32_16x16x32_bf16 v[74:77], v[142:145], v[190:193], v[74:77]
	s_setprio 0
	s_setprio 1
	v_mfma_f32_16x16x32_bf16 v[118:121], v[146:149], v[162:165], v[118:121]
	v_mfma_f32_16x16x32_bf16 v[110:113], v[154:157], v[162:165], v[110:113]
	v_mfma_f32_16x16x32_bf16 v[102:105], v[146:149], v[170:173], v[102:105]
	v_mfma_f32_16x16x32_bf16 v[94:97], v[154:157], v[170:173], v[94:97]
	v_mfma_f32_16x16x32_bf16 v[86:89], v[146:149], v[178:181], v[86:89]
	v_mfma_f32_16x16x32_bf16 v[78:81], v[154:157], v[178:181], v[78:81]
	v_mfma_f32_16x16x32_bf16 v[70:73], v[146:149], v[186:189], v[70:73]
	v_mfma_f32_16x16x32_bf16 v[66:69], v[154:157], v[186:189], v[66:69]
	v_mfma_f32_16x16x32_bf16 v[118:121], v[150:153], v[166:169], v[118:121]
	v_mfma_f32_16x16x32_bf16 v[110:113], v[158:161], v[166:169], v[110:113]
	v_mfma_f32_16x16x32_bf16 v[102:105], v[150:153], v[174:177], v[102:105]
	v_mfma_f32_16x16x32_bf16 v[94:97], v[158:161], v[174:177], v[94:97]
	v_mfma_f32_16x16x32_bf16 v[86:89], v[150:153], v[182:185], v[86:89]
	v_mfma_f32_16x16x32_bf16 v[78:81], v[158:161], v[182:185], v[78:81]
	v_mfma_f32_16x16x32_bf16 v[70:73], v[150:153], v[190:193], v[70:73]
	v_mfma_f32_16x16x32_bf16 v[66:69], v[158:161], v[190:193], v[66:69]
	s_setprio 0
	s_barrier
; #define PG8_STAGE(bufoff, gbase, voff) do { _Pragma("unroll") for (int _i = 0; _i < 2; ++_i) \
;         __builtin_amdgcn_global_load_lds((const unsigned*)((const char*)(gbase) + (voff)[_i]), (PG8_LAS unsigned*)(lds + (bufoff) + ldsw + _i * 8192), 16, 0, 0); } while (0)
; #define PG8_LDA(dst, b, h) do { _Pragma("unroll") for (int m = 0; m < 4; ++m) _Pragma("unroll") for (int k = 0; k < 2; ++k) dst[m][k] = *(const PG8_LAS bf16x8*)(lds + PG8_SA(b, h) + aoff + m * 2048 + k * 1024); } while (0)
; #define PG8_MMA(ai, bj, At, Bt) do { __builtin_amdgcn_s_setprio(1); _Pragma("unroll") for (int m = 0; m < 4; ++m) _Pragma("unroll") for (int n = 0; n < 2; ++n) _Pragma("unroll") for (int k = 0; k < 2; ++k) \
;         acc[ai][bj][m][n] = __builtin_amdgcn_mfma_f32_16x16x32_bf16(Bt[n][k], At[m][k], acc[ai][bj][m][n], 0, 0, 0); __builtin_amdgcn_s_setprio(0); } while (0)
; #define PG8_WAIT_V(n) asm volatile("s_waitcnt vmcnt(" #n ")" ::: "memory")
; #define PG8_WAIT_L(n) asm volatile("s_waitcnt lgkmcnt(" #n ")" ::: "memory")
; #define PG8_BAR __builtin_amdgcn_s_barrier()
; #define PG8_SCHED __builtin_amdgcn_sched_barrier(0)
; template <class Epi, class Sched, bool ALIGN_EPI = false, bool SP2 = false>
; __device__ __forceinline__ void gemm_phase(PG8_LAS unsigned char* lds, const Gemm g, const Sched& S, const Epi& E) {
;     ...
;         for (int t = 0; t < nt; t += 2) {
;             const bool last = (t == nt - 2);
;             const char* a1 = cA + (size_t)(t + 1) * kstep;
;             const char* a2 = last ? nA : cA + (size_t)(t + 2) * kstep; const char* b2 = last ? nB : cB + (size_t)(t + 2) * kstep;
;     ...
;             PG8_LDA(At, 1, 1); PG8_STAGE(PG8_SB(1, 0), b3, voffB); PG8_STAGE(PG8_SB(1, 1), b3 + hstep, voffB); PG8_STAGE(PG8_SA(1, 0), a3, voffA);
;             PG8_WAIT_V(8); PG8_WAIT_L(0); PG8_BAR; PG8_MMA(1, 0, At, B0); PG8_MMA(1, 1, At, B1); PG8_BAR; PG8_SCHED;
	s_add_i32 s22, s52, s28
	v_lshl_add_u64 v[206:207], v[206:207], 0, s[94:95]
	s_mov_b32 m0, s22
	ds_read_b128 v[162:165], v232 offset:49152
	ds_read_b128 v[166:169], v232 offset:50176
	ds_read_b128 v[170:173], v232 offset:51200
	ds_read_b128 v[174:177], v232 offset:52224
	ds_read_b128 v[178:181], v232 offset:53248
	ds_read_b128 v[182:185], v232 offset:54272
	ds_read_b128 v[186:189], v232 offset:55296
	ds_read_b128 v[190:193], v232 offset:56320
	global_load_lds_dwordx4 v[206:207], off
	s_add_i32 m0, s22, 0x2000
	s_add_u32 s16, s16, 0x100080
	v_lshl_add_u64 v[206:207], v[208:209], 0, s[94:95]
	s_addc_u32 s17, s17, 0
	s_add_i32 s22, s53, s28
	global_load_lds_dwordx4 v[206:207], off
	v_lshl_add_u64 v[206:207], s[16:17], 0, v[198:199]
	s_mov_b32 m0, s22
	s_nop 0
	global_load_lds_dwordx4 v[206:207], off
	v_lshl_add_u64 v[206:207], s[16:17], 0, v[194:195]
	s_add_i32 m0, s22, 0x2000
	s_nop 0
	global_load_lds_dwordx4 v[206:207], off
	v_lshl_add_u64 v[206:207], v[210:211], 0, s[94:95]
	s_mov_b32 m0, s33
	s_nop 0
	global_load_lds_dwordx4 v[206:207], off
	v_lshl_add_u64 v[206:207], v[212:213], 0, s[94:95]
	s_mov_b32 m0, s35
	s_nop 0
	global_load_lds_dwordx4 v[206:207], off
	s_waitcnt vmcnt(8)
	s_waitcnt lgkmcnt(0)
	s_barrier
	s_setprio 1
	s_waitcnt lgkmcnt(0)
	v_mfma_f32_16x16x32_bf16 v[62:65], v[130:133], v[162:165], v[62:65]
	v_mfma_f32_16x16x32_bf16 v[58:61], v[138:141], v[162:165], v[58:61]
	v_mfma_f32_16x16x32_bf16 v[50:53], v[130:133], v[170:173], v[50:53]
	v_mfma_f32_16x16x32_bf16 v[42:45], v[138:141], v[170:173], v[42:45]
	v_mfma_f32_16x16x32_bf16 v[34:37], v[130:133], v[178:181], v[34:37]
	v_mfma_f32_16x16x32_bf16 v[26:29], v[138:141], v[178:181], v[26:29]
	v_mfma_f32_16x16x32_bf16 v[18:21], v[130:133], v[186:189], v[18:21]
	v_mfma_f32_16x16x32_bf16 v[10:13], v[138:141], v[186:189], v[10:13]
	v_mfma_f32_16x16x32_bf16 v[62:65], v[134:137], v[166:169], v[62:65]
	v_mfma_f32_16x16x32_bf16 v[58:61], v[142:145], v[166:169], v[58:61]
	v_mfma_f32_16x16x32_bf16 v[50:53], v[134:137], v[174:177], v[50:53]
	v_mfma_f32_16x16x32_bf16 v[42:45], v[142:145], v[174:177], v[42:45]
	v_mfma_f32_16x16x32_bf16 v[34:37], v[134:137], v[182:185], v[34:37]
	v_mfma_f32_16x16x32_bf16 v[26:29], v[142:145], v[182:185], v[26:29]
	v_mfma_f32_16x16x32_bf16 v[18:21], v[134:137], v[190:193], v[18:21]
	v_mfma_f32_16x16x32_bf16 v[10:13], v[142:145], v[190:193], v[10:13]
	s_setprio 0
	s_setprio 1
	v_mfma_f32_16x16x32_bf16 v[54:57], v[146:149], v[162:165], v[54:57]
	v_mfma_f32_16x16x32_bf16 v[46:49], v[154:157], v[162:165], v[46:49]
	v_mfma_f32_16x16x32_bf16 v[38:41], v[146:149], v[170:173], v[38:41]
	v_mfma_f32_16x16x32_bf16 v[30:33], v[154:157], v[170:173], v[30:33]
	v_mfma_f32_16x16x32_bf16 v[22:25], v[146:149], v[178:181], v[22:25]
	v_mfma_f32_16x16x32_bf16 v[14:17], v[154:157], v[178:181], v[14:17]
	v_mfma_f32_16x16x32_bf16 v[6:9], v[146:149], v[186:189], v[6:9]
	v_mfma_f32_16x16x32_bf16 v[2:5], v[154:157], v[186:189], v[2:5]
	v_mfma_f32_16x16x32_bf16 v[54:57], v[150:153], v[166:169], v[54:57]
	v_mfma_f32_16x16x32_bf16 v[46:49], v[158:161], v[166:169], v[46:49]
	v_mfma_f32_16x16x32_bf16 v[38:41], v[150:153], v[174:177], v[38:41]
	v_mfma_f32_16x16x32_bf16 v[30:33], v[158:161], v[174:177], v[30:33]
	v_mfma_f32_16x16x32_bf16 v[22:25], v[150:153], v[182:185], v[22:25]
	v_mfma_f32_16x16x32_bf16 v[14:17], v[158:161], v[182:185], v[14:17]
	v_mfma_f32_16x16x32_bf16 v[6:9], v[150:153], v[190:193], v[6:9]
	v_mfma_f32_16x16x32_bf16 v[2:5], v[158:161], v[190:193], v[2:5]
	s_add_i32 s50, s50, 2
	s_add_u32 s20, s20, 0x100
	s_addc_u32 s21, s21, 0
	s_add_u32 s55, s55, 0x100
	s_addc_u32 s56, s56, 0
	s_add_u32 s16, s20, 0xfff00080
	s_addc_u32 s17, s21, -1
	s_add_i32 s52, 0, 0x10000
	s_cmp_eq_u32 s50, 60
	s_cselect_b32 s23, s13, s17
	s_cselect_b32 s22, s39, s16
	s_cselect_b32 s17, s11, s56
	s_cselect_b32 s16, s46, s55
	s_add_i32 s57, 0, 0x14000
	s_cmp_gt_u32 s50, 61
	s_setprio 0
	s_barrier
	s_cbranch_scc0 .LBB0_881
	s_and_b64 vcc, exec, s[8:9]
	s_cbranch_vccz .LBB0_884
	s_barrier
